# opt41: opt26 + first-iteration DMA move + split sa+2 K/V placement + G3 epilogue de-ladder + mid-segment setprio pair removed + MFMA-first compute segments
# speedup vs baseline: 1.0132x; 1.0019x over previous
; #define PG8_STAGE(bufoff, gbase, voff) do { _Pragma("unroll") for (int _i = 0; _i < 2; ++_i) \
;         __builtin_amdgcn_global_load_lds((const unsigned*)((const char*)(gbase) + (voff)[_i]), (LAS unsigned*)(lds + (bufoff) + ldsw + _i * 8192), 16, 0, 0); } while (0)
; #define PG8_LDA(dst, b, h) do { _Pragma("unroll") for (int m = 0; m < 4; ++m) _Pragma("unroll") for (int k = 0; k < 2; ++k) dst[m][k] = *(const LAS bf16x8*)(lds + PG8_SA(b, h) + aoff + m * 2048 + k * 1024); } while (0)
; #define PG8_LDB(dst, b, h) do { _Pragma("unroll") for (int n = 0; n < 2; ++n) _Pragma("unroll") for (int k = 0; k < 2; ++k) dst[n][k] = *(const LAS bf16x8*)(lds + PG8_SB(b, h) + boff + n * 2048 + k * 1024); } while (0)
; #define PG8_MMA(ai, bj, At, Bt) do { __builtin_amdgcn_s_setprio(1); _Pragma("unroll") for (int m = 0; m < 4; ++m) _Pragma("unroll") for (int n = 0; n < 2; ++n) _Pragma("unroll") for (int k = 0; k < 2; ++k) \
;         acc[ai][bj][m][n] = __builtin_amdgcn_mfma_f32_16x16x32_bf16(Bt[n][k], At[m][k], acc[ai][bj][m][n], 0, 0, 0); __builtin_amdgcn_s_setprio(0); } while (0)
; #define PG8_WAIT_V(n) asm volatile("s_waitcnt vmcnt(" #n ")" ::: "memory")
; #define PG8_WAIT_L(n) asm volatile("s_waitcnt lgkmcnt(" #n ")" ::: "memory")
; #define PG8_BAR __builtin_amdgcn_s_barrier()
; #define PG8_SCHED __builtin_amdgcn_sched_barrier(0)
; template <class Epi>
; __device__ __forceinline__ void gemm_phase(LAS unsigned char* lds, const Gemm g, const StaticOrder& S, const Epi& E) {
;     ...
;             const char* a2 = last ? nA : cA + ((Epi::HAS_MID && t + 2 >= nt1) ? dA2 : 0) + (size_t)(t + 2) * kstep; const char* b2 = last ? nB : cB + ((Epi::HAS_MID && t + 2 >= nt1) ? dB2 : 0) + (size_t)(t + 2) * kstep;
;             const char* a3 = a2 + kstep; const char* b3 = b2 + kstep;
;             PG8_LDB(B0, 0, 0); PG8_LDB(B1, 0, 1); PG8_SCHED; PG8_LDA(At, 0, 0); PG8_STAGE(PG8_SA(1, 1), a1 + hsA, voffA);
;             PG8_WAIT_V(8); PG8_WAIT_L(0); PG8_BAR; PG8_MMA(0, 0, At, B0); PG8_MMA(0, 1, At, B1); PG8_BAR; PG8_SCHED;
.LBB0_214:
	ds_read_b128 v[144:147], v155
	ds_read_b128 v[148:151], v155 offset:1024
	ds_read_b128 v[162:165], v155 offset:2048
	ds_read_b128 v[166:169], v155 offset:3072
	ds_read_b128 v[180:183], v156
	ds_read_b128 v[184:187], v156 offset:1024
	ds_read_b128 v[188:191], v156 offset:2048
	ds_read_b128 v[192:195], v156 offset:3072
	s_add_u32 s38, s58, 0xfffc0080
	s_addc_u32 s39, s59, -1
	s_cmp_eq_u32 s37, 12
	s_cselect_b32 s63, s6, s39
	s_cselect_b32 s62, s7, s38
	s_cselect_b32 s61, s11, s36
	s_cselect_b32 s60, s13, s35
	s_add_i32 m0, s19, 0xc000
	ds_read_b128 v[196:199], v157
	ds_read_b128 v[200:203], v157 offset:1024
	ds_read_b128 v[204:207], v157 offset:2048
	ds_read_b128 v[208:211], v157 offset:3072
	ds_read_b128 v[212:215], v157 offset:4096
	ds_read_b128 v[216:219], v157 offset:5120
	ds_read_b128 v[220:223], v157 offset:6144
	ds_read_b128 v[224:227], v157 offset:7168
	global_load_lds_dwordx4 v136, s[58:59]
	s_add_i32 m0, s19, 0xe000
	s_nop 0
	global_load_lds_dwordx4 v138, s[58:59]
	s_waitcnt vmcnt(8)
	s_waitcnt lgkmcnt(0)
	s_setprio 1
	s_barrier

; #define PG8_MMA(ai, bj, At, Bt) do { __builtin_amdgcn_s_setprio(1); _Pragma("unroll") for (int m = 0; m < 4; ++m) _Pragma("unroll") for (int n = 0; n < 2; ++n) _Pragma("unroll") for (int k = 0; k < 2; ++k) \
;         acc[ai][bj][m][n] = __builtin_amdgcn_mfma_f32_16x16x32_bf16(Bt[n][k], At[m][k], acc[ai][bj][m][n], 0, 0, 0); __builtin_amdgcn_s_setprio(0); } while (0)
; #define PG8_WAIT_V(n) asm volatile("s_waitcnt vmcnt(" #n ")" ::: "memory")
; #define PG8_WAIT_L(n) asm volatile("s_waitcnt lgkmcnt(" #n ")" ::: "memory")
; #define PG8_BAR __builtin_amdgcn_s_barrier()
; #define PG8_SCHED __builtin_amdgcn_sched_barrier(0)
; template <class Epi>
; __device__ __forceinline__ void gemm_phase(LAS unsigned char* lds, const Gemm g, const StaticOrder& S, const Epi& E) {
;     ...
;             PG8_WAIT_V(8); PG8_WAIT_L(0); PG8_BAR; PG8_MMA(0, 0, At, B0); PG8_MMA(0, 1, At, B1); PG8_BAR; PG8_SCHED;
	v_mfma_f32_16x16x32_bf16 v[124:127], v[144:147], v[196:199], v[124:127]
	v_mfma_f32_16x16x32_bf16 v[120:123], v[162:165], v[196:199], v[120:123]
	v_mfma_f32_16x16x32_bf16 v[108:111], v[144:147], v[204:207], v[108:111]
	v_mfma_f32_16x16x32_bf16 v[104:107], v[162:165], v[204:207], v[104:107]
	v_mfma_f32_16x16x32_bf16 v[92:95], v[144:147], v[212:215], v[92:95]
	v_mfma_f32_16x16x32_bf16 v[88:91], v[162:165], v[212:215], v[88:91]
	v_mfma_f32_16x16x32_bf16 v[76:79], v[144:147], v[220:223], v[76:79]
	v_mfma_f32_16x16x32_bf16 v[72:75], v[162:165], v[220:223], v[72:75]
	v_mfma_f32_16x16x32_bf16 v[124:127], v[148:151], v[200:203], v[124:127]
	v_mfma_f32_16x16x32_bf16 v[120:123], v[166:169], v[200:203], v[120:123]
	v_mfma_f32_16x16x32_bf16 v[108:111], v[148:151], v[208:211], v[108:111]
	v_mfma_f32_16x16x32_bf16 v[104:107], v[166:169], v[208:211], v[104:107]
	v_mfma_f32_16x16x32_bf16 v[92:95], v[148:151], v[216:219], v[92:95]
	v_mfma_f32_16x16x32_bf16 v[88:91], v[166:169], v[216:219], v[88:91]
	v_mfma_f32_16x16x32_bf16 v[76:79], v[148:151], v[224:227], v[76:79]
	v_mfma_f32_16x16x32_bf16 v[72:75], v[166:169], v[224:227], v[72:75]


; #define PG8_STAGE(bufoff, gbase, voff) do { _Pragma("unroll") for (int _i = 0; _i < 2; ++_i) \
;         __builtin_amdgcn_global_load_lds((const unsigned*)((const char*)(gbase) + (voff)[_i]), (LAS unsigned*)(lds + (bufoff) + ldsw + _i * 8192), 16, 0, 0); } while (0)
; #define PG8_LDA(dst, b, h) do { _Pragma("unroll") for (int m = 0; m < 4; ++m) _Pragma("unroll") for (int k = 0; k < 2; ++k) dst[m][k] = *(const LAS bf16x8*)(lds + PG8_SA(b, h) + aoff + m * 2048 + k * 1024); } while (0)
; #define PG8_MMA(ai, bj, At, Bt) do { __builtin_amdgcn_s_setprio(1); _Pragma("unroll") for (int m = 0; m < 4; ++m) _Pragma("unroll") for (int n = 0; n < 2; ++n) _Pragma("unroll") for (int k = 0; k < 2; ++k) \
;         acc[ai][bj][m][n] = __builtin_amdgcn_mfma_f32_16x16x32_bf16(Bt[n][k], At[m][k], acc[ai][bj][m][n], 0, 0, 0); __builtin_amdgcn_s_setprio(0); } while (0)
; #define PG8_WAIT_V(n) asm volatile("s_waitcnt vmcnt(" #n ")" ::: "memory")
; #define PG8_WAIT_L(n) asm volatile("s_waitcnt lgkmcnt(" #n ")" ::: "memory")
; #define PG8_BAR __builtin_amdgcn_s_barrier()
; #define PG8_SCHED __builtin_amdgcn_sched_barrier(0)
; template <class Epi>
; __device__ __forceinline__ void gemm_phase(LAS unsigned char* lds, const Gemm g, const StaticOrder& S, const Epi& E) {
;     ...
;             PG8_WAIT_V(8); PG8_WAIT_L(0); PG8_BAR; PG8_MMA(0, 0, At, B0); PG8_MMA(0, 1, At, B1); PG8_BAR; PG8_SCHED;
;             PG8_LDA(At, 0, 1); PG8_STAGE(PG8_SB(0, 0), b2, voffB); PG8_STAGE(PG8_SB(0, 1), b2 + hsB, voffB); PG8_STAGE(PG8_SA(0, 0), a2, voffA);
;             PG8_WAIT_V(8); PG8_WAIT_L(0); PG8_BAR; PG8_MMA(1, 0, At, B0); PG8_MMA(1, 1, At, B1); PG8_BAR; PG8_SCHED;
	v_mfma_f32_16x16x32_bf16 v[116:119], v[180:183], v[196:199], v[116:119]
	v_mfma_f32_16x16x32_bf16 v[112:115], v[188:191], v[196:199], v[112:115]
	v_mfma_f32_16x16x32_bf16 v[100:103], v[180:183], v[204:207], v[100:103]
	v_mfma_f32_16x16x32_bf16 v[96:99], v[188:191], v[204:207], v[96:99]
	v_mfma_f32_16x16x32_bf16 v[84:87], v[180:183], v[212:215], v[84:87]
	v_mfma_f32_16x16x32_bf16 v[80:83], v[188:191], v[212:215], v[80:83]
	v_mfma_f32_16x16x32_bf16 v[68:71], v[180:183], v[220:223], v[68:71]
	v_mfma_f32_16x16x32_bf16 v[64:67], v[188:191], v[220:223], v[64:67]
	v_mfma_f32_16x16x32_bf16 v[116:119], v[184:187], v[200:203], v[116:119]
	v_mfma_f32_16x16x32_bf16 v[112:115], v[192:195], v[200:203], v[112:115]
	v_mfma_f32_16x16x32_bf16 v[100:103], v[184:187], v[208:211], v[100:103]
	v_mfma_f32_16x16x32_bf16 v[96:99], v[192:195], v[208:211], v[96:99]
	v_mfma_f32_16x16x32_bf16 v[84:87], v[184:187], v[216:219], v[84:87]
	v_mfma_f32_16x16x32_bf16 v[80:83], v[192:195], v[216:219], v[80:83]
	v_mfma_f32_16x16x32_bf16 v[68:71], v[184:187], v[224:227], v[68:71]
	v_mfma_f32_16x16x32_bf16 v[64:67], v[192:195], v[224:227], v[64:67]
	s_setprio 0
	s_barrier
	s_add_i32 s38, s30, s16
	s_mov_b32 m0, s38
	ds_read_b128 v[196:199], v157 offset:16384
	ds_read_b128 v[200:203], v157 offset:17408
	ds_read_b128 v[204:207], v157 offset:18432
	ds_read_b128 v[208:211], v157 offset:19456
	ds_read_b128 v[212:215], v157 offset:20480
	ds_read_b128 v[216:219], v157 offset:21504
	ds_read_b128 v[220:223], v157 offset:22528
	ds_read_b128 v[224:227], v157 offset:23552
	global_load_lds_dwordx4 v132, s[60:61]
	s_add_i32 m0, s38, 0x2000
	s_add_u32 s38, s60, 0x40000
	s_addc_u32 s39, s61, 0
	s_add_i32 s40, s31, s16
	global_load_lds_dwordx4 v128, s[60:61]
	s_mov_b32 m0, s40
	s_nop 0
	global_load_lds_dwordx4 v132, s[38:39]
	s_add_i32 m0, s40, 0x2000
	s_nop 0
	global_load_lds_dwordx4 v128, s[38:39]
	s_mov_b32 m0, s19
	s_nop 0
	global_load_lds_dwordx4 v134, s[62:63]
	s_mov_b32 m0, s22
	s_nop 0
	global_load_lds_dwordx4 v130, s[62:63]
	s_waitcnt vmcnt(8)
	s_waitcnt lgkmcnt(0)
	s_setprio 1
	s_barrier

; #define PG8_MMA(ai, bj, At, Bt) do { __builtin_amdgcn_s_setprio(1); _Pragma("unroll") for (int m = 0; m < 4; ++m) _Pragma("unroll") for (int n = 0; n < 2; ++n) _Pragma("unroll") for (int k = 0; k < 2; ++k) \
;         acc[ai][bj][m][n] = __builtin_amdgcn_mfma_f32_16x16x32_bf16(Bt[n][k], At[m][k], acc[ai][bj][m][n], 0, 0, 0); __builtin_amdgcn_s_setprio(0); } while (0)
; #define PG8_WAIT_V(n) asm volatile("s_waitcnt vmcnt(" #n ")" ::: "memory")
; #define PG8_WAIT_L(n) asm volatile("s_waitcnt lgkmcnt(" #n ")" ::: "memory")
; #define PG8_BAR __builtin_amdgcn_s_barrier()
; #define PG8_SCHED __builtin_amdgcn_sched_barrier(0)
; template <class Epi>
; __device__ __forceinline__ void gemm_phase(LAS unsigned char* lds, const Gemm g, const StaticOrder& S, const Epi& E) {
;     ...
;             PG8_WAIT_V(8); PG8_WAIT_L(0); PG8_BAR; PG8_MMA(1, 0, At, B0); PG8_MMA(1, 1, At, B1); PG8_BAR; PG8_SCHED;
	v_mfma_f32_16x16x32_bf16 v[60:63], v[144:147], v[196:199], v[60:63]
	v_mfma_f32_16x16x32_bf16 v[56:59], v[162:165], v[196:199], v[56:59]
	v_mfma_f32_16x16x32_bf16 v[44:47], v[144:147], v[204:207], v[44:47]
	v_mfma_f32_16x16x32_bf16 v[40:43], v[162:165], v[204:207], v[40:43]
	v_mfma_f32_16x16x32_bf16 v[28:31], v[144:147], v[212:215], v[28:31]
	v_mfma_f32_16x16x32_bf16 v[24:27], v[162:165], v[212:215], v[24:27]
	v_mfma_f32_16x16x32_bf16 v[12:15], v[144:147], v[220:223], v[12:15]
	v_mfma_f32_16x16x32_bf16 v[8:11], v[162:165], v[220:223], v[8:11]
	v_mfma_f32_16x16x32_bf16 v[60:63], v[148:151], v[200:203], v[60:63]
	v_mfma_f32_16x16x32_bf16 v[56:59], v[166:169], v[200:203], v[56:59]
	v_mfma_f32_16x16x32_bf16 v[44:47], v[148:151], v[208:211], v[44:47]
	v_mfma_f32_16x16x32_bf16 v[40:43], v[166:169], v[208:211], v[40:43]
	v_mfma_f32_16x16x32_bf16 v[28:31], v[148:151], v[216:219], v[28:31]
	v_mfma_f32_16x16x32_bf16 v[24:27], v[166:169], v[216:219], v[24:27]
	v_mfma_f32_16x16x32_bf16 v[12:15], v[148:151], v[224:227], v[12:15]
	v_mfma_f32_16x16x32_bf16 v[8:11], v[166:169], v[224:227], v[8:11]


; #define PG8_STAGE(bufoff, gbase, voff) do { _Pragma("unroll") for (int _i = 0; _i < 2; ++_i) \
;         __builtin_amdgcn_global_load_lds((const unsigned*)((const char*)(gbase) + (voff)[_i]), (LAS unsigned*)(lds + (bufoff) + ldsw + _i * 8192), 16, 0, 0); } while (0)
; #define PG8_LDA(dst, b, h) do { _Pragma("unroll") for (int m = 0; m < 4; ++m) _Pragma("unroll") for (int k = 0; k < 2; ++k) dst[m][k] = *(const LAS bf16x8*)(lds + PG8_SA(b, h) + aoff + m * 2048 + k * 1024); } while (0)
; #define PG8_LDB(dst, b, h) do { _Pragma("unroll") for (int n = 0; n < 2; ++n) _Pragma("unroll") for (int k = 0; k < 2; ++k) dst[n][k] = *(const LAS bf16x8*)(lds + PG8_SB(b, h) + boff + n * 2048 + k * 1024); } while (0)
; #define PG8_MMA(ai, bj, At, Bt) do { __builtin_amdgcn_s_setprio(1); _Pragma("unroll") for (int m = 0; m < 4; ++m) _Pragma("unroll") for (int n = 0; n < 2; ++n) _Pragma("unroll") for (int k = 0; k < 2; ++k) \
;         acc[ai][bj][m][n] = __builtin_amdgcn_mfma_f32_16x16x32_bf16(Bt[n][k], At[m][k], acc[ai][bj][m][n], 0, 0, 0); __builtin_amdgcn_s_setprio(0); } while (0)
; #define PG8_WAIT_V(n) asm volatile("s_waitcnt vmcnt(" #n ")" ::: "memory")
; #define PG8_WAIT_L(n) asm volatile("s_waitcnt lgkmcnt(" #n ")" ::: "memory")
; #define PG8_BAR __builtin_amdgcn_s_barrier()
; #define PG8_SCHED __builtin_amdgcn_sched_barrier(0)
; template <class Epi>
; __device__ __forceinline__ void gemm_phase(LAS unsigned char* lds, const Gemm g, const StaticOrder& S, const Epi& E) {
;     ...
;             PG8_WAIT_V(8); PG8_WAIT_L(0); PG8_BAR; PG8_MMA(1, 0, At, B0); PG8_MMA(1, 1, At, B1); PG8_BAR; PG8_SCHED;
;             PG8_LDB(B0, 1, 0); PG8_LDB(B1, 1, 1); PG8_SCHED; PG8_LDA(At, 1, 0); PG8_STAGE(PG8_SA(0, 1), a2 + hsA, voffA);
;             PG8_WAIT_V(8); PG8_WAIT_L(0); PG8_BAR; PG8_MMA(0, 0, At, B0); PG8_MMA(0, 1, At, B1); PG8_BAR; PG8_SCHED;
	v_mfma_f32_16x16x32_bf16 v[52:55], v[180:183], v[196:199], v[52:55]
	v_mfma_f32_16x16x32_bf16 v[48:51], v[188:191], v[196:199], v[48:51]
	v_mfma_f32_16x16x32_bf16 v[36:39], v[180:183], v[204:207], v[36:39]
	v_mfma_f32_16x16x32_bf16 v[32:35], v[188:191], v[204:207], v[32:35]
	v_mfma_f32_16x16x32_bf16 v[20:23], v[180:183], v[212:215], v[20:23]
	v_mfma_f32_16x16x32_bf16 v[16:19], v[188:191], v[212:215], v[16:19]
	v_mfma_f32_16x16x32_bf16 v[4:7], v[180:183], v[220:223], v[4:7]
	v_mfma_f32_16x16x32_bf16 v[0:3], v[188:191], v[220:223], v[0:3]
	v_mfma_f32_16x16x32_bf16 v[52:55], v[184:187], v[200:203], v[52:55]
	v_mfma_f32_16x16x32_bf16 v[48:51], v[192:195], v[200:203], v[48:51]
	v_mfma_f32_16x16x32_bf16 v[36:39], v[184:187], v[208:211], v[36:39]
	v_mfma_f32_16x16x32_bf16 v[32:35], v[192:195], v[208:211], v[32:35]
	v_mfma_f32_16x16x32_bf16 v[20:23], v[184:187], v[216:219], v[20:23]
	v_mfma_f32_16x16x32_bf16 v[16:19], v[192:195], v[216:219], v[16:19]
	v_mfma_f32_16x16x32_bf16 v[4:7], v[184:187], v[224:227], v[4:7]
	v_mfma_f32_16x16x32_bf16 v[0:3], v[192:195], v[224:227], v[0:3]
	s_setprio 0
	s_barrier
	s_add_i32 s40, 0, 0x18000
	v_add_u32_e32 v159, s40, v153
	s_add_i32 s41, 0, 0x1c000
	ds_read_b128 v[144:147], v159
	ds_read_b128 v[148:151], v159 offset:1024
	ds_read_b128 v[162:165], v159 offset:2048
	ds_read_b128 v[166:169], v159 offset:3072
	v_add_u32_e32 v159, s41, v153
	ds_read_b128 v[180:183], v159
	ds_read_b128 v[184:187], v159 offset:1024
	ds_read_b128 v[188:191], v159 offset:2048
	ds_read_b128 v[192:195], v159 offset:3072
	s_add_u32 s38, s62, 0x40000
	s_addc_u32 s39, s63, 0
	s_mov_b32 m0, s23
	ds_read_b128 v[196:199], v157 offset:32768
	ds_read_b128 v[200:203], v157 offset:33792
	ds_read_b128 v[204:207], v157 offset:34816
	ds_read_b128 v[208:211], v157 offset:35840
	ds_read_b128 v[212:215], v157 offset:36864
	ds_read_b128 v[216:219], v157 offset:37888
	ds_read_b128 v[220:223], v157 offset:38912
	ds_read_b128 v[224:227], v157 offset:39936
	global_load_lds_dwordx4 v134, s[38:39]
	s_mov_b32 m0, s24
	s_nop 0
	global_load_lds_dwordx4 v130, s[38:39]
	s_waitcnt vmcnt(8)
	s_waitcnt lgkmcnt(0)
	s_setprio 1
	s_barrier

; #define PG8_MMA(ai, bj, At, Bt) do { __builtin_amdgcn_s_setprio(1); _Pragma("unroll") for (int m = 0; m < 4; ++m) _Pragma("unroll") for (int n = 0; n < 2; ++n) _Pragma("unroll") for (int k = 0; k < 2; ++k) \
;         acc[ai][bj][m][n] = __builtin_amdgcn_mfma_f32_16x16x32_bf16(Bt[n][k], At[m][k], acc[ai][bj][m][n], 0, 0, 0); __builtin_amdgcn_s_setprio(0); } while (0)
; #define PG8_WAIT_V(n) asm volatile("s_waitcnt vmcnt(" #n ")" ::: "memory")
; #define PG8_WAIT_L(n) asm volatile("s_waitcnt lgkmcnt(" #n ")" ::: "memory")
; #define PG8_BAR __builtin_amdgcn_s_barrier()
; #define PG8_SCHED __builtin_amdgcn_sched_barrier(0)
; template <class Epi>
; __device__ __forceinline__ void gemm_phase(LAS unsigned char* lds, const Gemm g, const StaticOrder& S, const Epi& E) {
;     ...
;             PG8_WAIT_V(8); PG8_WAIT_L(0); PG8_BAR; PG8_MMA(0, 0, At, B0); PG8_MMA(0, 1, At, B1); PG8_BAR; PG8_SCHED;
	v_mfma_f32_16x16x32_bf16 v[124:127], v[144:147], v[196:199], v[124:127]
	v_mfma_f32_16x16x32_bf16 v[120:123], v[162:165], v[196:199], v[120:123]
	v_mfma_f32_16x16x32_bf16 v[108:111], v[144:147], v[204:207], v[108:111]
	v_mfma_f32_16x16x32_bf16 v[104:107], v[162:165], v[204:207], v[104:107]
	v_mfma_f32_16x16x32_bf16 v[92:95], v[144:147], v[212:215], v[92:95]
	v_mfma_f32_16x16x32_bf16 v[88:91], v[162:165], v[212:215], v[88:91]
	v_mfma_f32_16x16x32_bf16 v[76:79], v[144:147], v[220:223], v[76:79]
	v_mfma_f32_16x16x32_bf16 v[72:75], v[162:165], v[220:223], v[72:75]
	v_mfma_f32_16x16x32_bf16 v[124:127], v[148:151], v[200:203], v[124:127]
	v_mfma_f32_16x16x32_bf16 v[120:123], v[166:169], v[200:203], v[120:123]
	v_mfma_f32_16x16x32_bf16 v[108:111], v[148:151], v[208:211], v[108:111]
	v_mfma_f32_16x16x32_bf16 v[104:107], v[166:169], v[208:211], v[104:107]
	v_mfma_f32_16x16x32_bf16 v[92:95], v[148:151], v[216:219], v[92:95]
	v_mfma_f32_16x16x32_bf16 v[88:91], v[166:169], v[216:219], v[88:91]
	v_mfma_f32_16x16x32_bf16 v[76:79], v[148:151], v[224:227], v[76:79]
	v_mfma_f32_16x16x32_bf16 v[72:75], v[166:169], v[224:227], v[72:75]


; #define PG8_STAGE(bufoff, gbase, voff) do { _Pragma("unroll") for (int _i = 0; _i < 2; ++_i) \
;         __builtin_amdgcn_global_load_lds((const unsigned*)((const char*)(gbase) + (voff)[_i]), (LAS unsigned*)(lds + (bufoff) + ldsw + _i * 8192), 16, 0, 0); } while (0)
; #define PG8_LDA(dst, b, h) do { _Pragma("unroll") for (int m = 0; m < 4; ++m) _Pragma("unroll") for (int k = 0; k < 2; ++k) dst[m][k] = *(const LAS bf16x8*)(lds + PG8_SA(b, h) + aoff + m * 2048 + k * 1024); } while (0)
; #define PG8_MMA(ai, bj, At, Bt) do { __builtin_amdgcn_s_setprio(1); _Pragma("unroll") for (int m = 0; m < 4; ++m) _Pragma("unroll") for (int n = 0; n < 2; ++n) _Pragma("unroll") for (int k = 0; k < 2; ++k) \
;         acc[ai][bj][m][n] = __builtin_amdgcn_mfma_f32_16x16x32_bf16(Bt[n][k], At[m][k], acc[ai][bj][m][n], 0, 0, 0); __builtin_amdgcn_s_setprio(0); } while (0)
; #define PG8_WAIT_V(n) asm volatile("s_waitcnt vmcnt(" #n ")" ::: "memory")
; #define PG8_WAIT_L(n) asm volatile("s_waitcnt lgkmcnt(" #n ")" ::: "memory")
; #define PG8_BAR __builtin_amdgcn_s_barrier()
; #define PG8_SCHED __builtin_amdgcn_sched_barrier(0)
; template <class Epi>
; __device__ __forceinline__ void gemm_phase(LAS unsigned char* lds, const Gemm g, const StaticOrder& S, const Epi& E) {
;     ...
;             PG8_WAIT_V(8); PG8_WAIT_L(0); PG8_BAR; PG8_MMA(0, 0, At, B0); PG8_MMA(0, 1, At, B1); PG8_BAR; PG8_SCHED;
;             PG8_LDA(At, 1, 1); PG8_STAGE(PG8_SB(1, 0), b3, voffB); PG8_STAGE(PG8_SB(1, 1), b3 + hsB, voffB); PG8_STAGE(PG8_SA(1, 0), a3, voffA);
;             PG8_WAIT_V(8); PG8_WAIT_L(0); PG8_BAR; PG8_MMA(1, 0, At, B0); PG8_MMA(1, 1, At, B1); PG8_BAR; PG8_SCHED;
	v_mfma_f32_16x16x32_bf16 v[116:119], v[180:183], v[196:199], v[116:119]
	v_mfma_f32_16x16x32_bf16 v[112:115], v[188:191], v[196:199], v[112:115]
	v_mfma_f32_16x16x32_bf16 v[100:103], v[180:183], v[204:207], v[100:103]
	v_mfma_f32_16x16x32_bf16 v[96:99], v[188:191], v[204:207], v[96:99]
	v_mfma_f32_16x16x32_bf16 v[84:87], v[180:183], v[212:215], v[84:87]
	v_mfma_f32_16x16x32_bf16 v[80:83], v[188:191], v[212:215], v[80:83]
	v_mfma_f32_16x16x32_bf16 v[68:71], v[180:183], v[220:223], v[68:71]
	v_mfma_f32_16x16x32_bf16 v[64:67], v[188:191], v[220:223], v[64:67]
	v_mfma_f32_16x16x32_bf16 v[116:119], v[184:187], v[200:203], v[116:119]
	v_mfma_f32_16x16x32_bf16 v[112:115], v[192:195], v[200:203], v[112:115]
	v_mfma_f32_16x16x32_bf16 v[100:103], v[184:187], v[208:211], v[100:103]
	v_mfma_f32_16x16x32_bf16 v[96:99], v[192:195], v[208:211], v[96:99]
	v_mfma_f32_16x16x32_bf16 v[84:87], v[184:187], v[216:219], v[84:87]
	v_mfma_f32_16x16x32_bf16 v[80:83], v[192:195], v[216:219], v[80:83]
	v_mfma_f32_16x16x32_bf16 v[68:71], v[184:187], v[224:227], v[68:71]
	v_mfma_f32_16x16x32_bf16 v[64:67], v[192:195], v[224:227], v[64:67]
	s_setprio 0
	s_barrier
	s_add_u32 s98, s60, 0x80
	s_addc_u32 s99, s61, 0
	s_add_u32 s100, s62, 0x80
	s_addc_u32 s101, s63, 0
	s_add_i32 s38, s40, s16
	s_mov_b32 m0, s38
	ds_read_b128 v[196:199], v157 offset:49152
	ds_read_b128 v[200:203], v157 offset:50176
	ds_read_b128 v[204:207], v157 offset:51200
	ds_read_b128 v[208:211], v157 offset:52224
	ds_read_b128 v[212:215], v157 offset:53248
	ds_read_b128 v[216:219], v157 offset:54272
	ds_read_b128 v[220:223], v157 offset:55296
	ds_read_b128 v[224:227], v157 offset:56320
	global_load_lds_dwordx4 v132, s[98:99]
	s_add_i32 m0, s38, 0x2000
	s_add_u32 s38, s60, 0x40080
	s_addc_u32 s39, s61, 0
	s_add_i32 s40, s41, s16
	global_load_lds_dwordx4 v128, s[98:99]
	s_mov_b32 m0, s40
	s_nop 0
	global_load_lds_dwordx4 v132, s[38:39]
	s_add_i32 m0, s40, 0x2000
	s_nop 0
	global_load_lds_dwordx4 v128, s[38:39]
	s_mov_b32 m0, s25
	s_nop 0
	global_load_lds_dwordx4 v134, s[100:101]
	s_mov_b32 m0, s26
	s_nop 0
	global_load_lds_dwordx4 v130, s[100:101]
	s_waitcnt vmcnt(8)
	s_waitcnt lgkmcnt(0)
	s_setprio 1
	s_barrier

; #define PG8_MMA(ai, bj, At, Bt) do { __builtin_amdgcn_s_setprio(1); _Pragma("unroll") for (int m = 0; m < 4; ++m) _Pragma("unroll") for (int n = 0; n < 2; ++n) _Pragma("unroll") for (int k = 0; k < 2; ++k) \
;         acc[ai][bj][m][n] = __builtin_amdgcn_mfma_f32_16x16x32_bf16(Bt[n][k], At[m][k], acc[ai][bj][m][n], 0, 0, 0); __builtin_amdgcn_s_setprio(0); } while (0)
; #define PG8_WAIT_V(n) asm volatile("s_waitcnt vmcnt(" #n ")" ::: "memory")
; #define PG8_WAIT_L(n) asm volatile("s_waitcnt lgkmcnt(" #n ")" ::: "memory")
; #define PG8_BAR __builtin_amdgcn_s_barrier()
; #define PG8_SCHED __builtin_amdgcn_sched_barrier(0)
; template <class Epi>
; __device__ __forceinline__ void gemm_phase(LAS unsigned char* lds, const Gemm g, const StaticOrder& S, const Epi& E) {
;     ...
;             PG8_WAIT_V(8); PG8_WAIT_L(0); PG8_BAR; PG8_MMA(1, 0, At, B0); PG8_MMA(1, 1, At, B1); PG8_BAR; PG8_SCHED;
	v_mfma_f32_16x16x32_bf16 v[60:63], v[144:147], v[196:199], v[60:63]
	v_mfma_f32_16x16x32_bf16 v[56:59], v[162:165], v[196:199], v[56:59]
	v_mfma_f32_16x16x32_bf16 v[44:47], v[144:147], v[204:207], v[44:47]
	v_mfma_f32_16x16x32_bf16 v[40:43], v[162:165], v[204:207], v[40:43]
	v_mfma_f32_16x16x32_bf16 v[28:31], v[144:147], v[212:215], v[28:31]
	v_mfma_f32_16x16x32_bf16 v[24:27], v[162:165], v[212:215], v[24:27]
	v_mfma_f32_16x16x32_bf16 v[12:15], v[144:147], v[220:223], v[12:15]
	v_mfma_f32_16x16x32_bf16 v[8:11], v[162:165], v[220:223], v[8:11]
	v_mfma_f32_16x16x32_bf16 v[60:63], v[148:151], v[200:203], v[60:63]
	v_mfma_f32_16x16x32_bf16 v[56:59], v[166:169], v[200:203], v[56:59]
	v_mfma_f32_16x16x32_bf16 v[44:47], v[148:151], v[208:211], v[44:47]
	v_mfma_f32_16x16x32_bf16 v[40:43], v[166:169], v[208:211], v[40:43]
	v_mfma_f32_16x16x32_bf16 v[28:31], v[148:151], v[216:219], v[28:31]
	v_mfma_f32_16x16x32_bf16 v[24:27], v[166:169], v[216:219], v[24:27]
	v_mfma_f32_16x16x32_bf16 v[12:15], v[148:151], v[224:227], v[12:15]
	v_mfma_f32_16x16x32_bf16 v[8:11], v[166:169], v[224:227], v[8:11]


; #define PG8_MMA(ai, bj, At, Bt) do { __builtin_amdgcn_s_setprio(1); _Pragma("unroll") for (int m = 0; m < 4; ++m) _Pragma("unroll") for (int n = 0; n < 2; ++n) _Pragma("unroll") for (int k = 0; k < 2; ++k) \
;         acc[ai][bj][m][n] = __builtin_amdgcn_mfma_f32_16x16x32_bf16(Bt[n][k], At[m][k], acc[ai][bj][m][n], 0, 0, 0); __builtin_amdgcn_s_setprio(0); } while (0)
; #define PG8_WAIT_V(n) asm volatile("s_waitcnt vmcnt(" #n ")" ::: "memory")
; #define PG8_WAIT_L(n) asm volatile("s_waitcnt lgkmcnt(" #n ")" ::: "memory")
; #define PG8_BAR __builtin_amdgcn_s_barrier()
; #define PG8_SCHED __builtin_amdgcn_sched_barrier(0)
; template <class Epi>
; __device__ __forceinline__ void gemm_phase(LAS unsigned char* lds, const Gemm g, const StaticOrder& S, const Epi& E) {
;     ...
;         for (int t = 0; t < nt; t += 2) {
;     ...
;             PG8_WAIT_V(8); PG8_WAIT_L(0); PG8_BAR; PG8_MMA(1, 0, At, B0); PG8_MMA(1, 1, At, B1); PG8_BAR; PG8_SCHED;
;         }
;         if (wr == 0) PG8_BAR;
	v_mfma_f32_16x16x32_bf16 v[52:55], v[180:183], v[196:199], v[52:55]
	v_mfma_f32_16x16x32_bf16 v[48:51], v[188:191], v[196:199], v[48:51]
	v_mfma_f32_16x16x32_bf16 v[36:39], v[180:183], v[204:207], v[36:39]
	v_mfma_f32_16x16x32_bf16 v[32:35], v[188:191], v[204:207], v[32:35]
	v_mfma_f32_16x16x32_bf16 v[20:23], v[180:183], v[212:215], v[20:23]
	v_mfma_f32_16x16x32_bf16 v[16:19], v[188:191], v[212:215], v[16:19]
	v_mfma_f32_16x16x32_bf16 v[4:7], v[180:183], v[220:223], v[4:7]
	v_mfma_f32_16x16x32_bf16 v[0:3], v[188:191], v[220:223], v[0:3]
	v_mfma_f32_16x16x32_bf16 v[52:55], v[184:187], v[200:203], v[52:55]
	v_mfma_f32_16x16x32_bf16 v[48:51], v[192:195], v[200:203], v[48:51]
	v_mfma_f32_16x16x32_bf16 v[36:39], v[184:187], v[208:211], v[36:39]
	v_mfma_f32_16x16x32_bf16 v[32:35], v[192:195], v[208:211], v[32:35]
	v_mfma_f32_16x16x32_bf16 v[20:23], v[184:187], v[216:219], v[20:23]
	v_mfma_f32_16x16x32_bf16 v[16:19], v[192:195], v[216:219], v[16:19]
	v_mfma_f32_16x16x32_bf16 v[4:7], v[184:187], v[224:227], v[4:7]
	v_mfma_f32_16x16x32_bf16 v[0:3], v[192:195], v[224:227], v[0:3]
	s_setprio 0
	s_barrier
	s_add_i32 s37, s37, 2
	s_add_u32 s58, s58, 0x100
	s_addc_u32 s59, s59, 0
	s_add_u32 s35, s35, 0x100
	s_addc_u32 s36, s36, 0
	s_cmp_gt_u32 s37, 13
	s_cbranch_scc0 .LBB0_214
	s_and_b64 vcc, exec, s[8:9]
	s_cbranch_vccz .LBB0_217
	s_barrier

; #define PG8_STAGE(bufoff, gbase, voff) do { _Pragma("unroll") for (int _i = 0; _i < 2; ++_i) \
;         __builtin_amdgcn_global_load_lds((const unsigned*)((const char*)(gbase) + (voff)[_i]), (LAS unsigned*)(lds + (bufoff) + ldsw + _i * 8192), 16, 0, 0); } while (0)
; #define PG8_LDA(dst, b, h) do { _Pragma("unroll") for (int m = 0; m < 4; ++m) _Pragma("unroll") for (int k = 0; k < 2; ++k) dst[m][k] = *(const LAS bf16x8*)(lds + PG8_SA(b, h) + aoff + m * 2048 + k * 1024); } while (0)
; #define PG8_LDB(dst, b, h) do { _Pragma("unroll") for (int n = 0; n < 2; ++n) _Pragma("unroll") for (int k = 0; k < 2; ++k) dst[n][k] = *(const LAS bf16x8*)(lds + PG8_SB(b, h) + boff + n * 2048 + k * 1024); } while (0)
; #define PG8_MMA(ai, bj, At, Bt) do { __builtin_amdgcn_s_setprio(1); _Pragma("unroll") for (int m = 0; m < 4; ++m) _Pragma("unroll") for (int n = 0; n < 2; ++n) _Pragma("unroll") for (int k = 0; k < 2; ++k) \
;         acc[ai][bj][m][n] = __builtin_amdgcn_mfma_f32_16x16x32_bf16(Bt[n][k], At[m][k], acc[ai][bj][m][n], 0, 0, 0); __builtin_amdgcn_s_setprio(0); } while (0)
; #define PG8_WAIT_V(n) asm volatile("s_waitcnt vmcnt(" #n ")" ::: "memory")
; #define PG8_WAIT_L(n) asm volatile("s_waitcnt lgkmcnt(" #n ")" ::: "memory")
; #define PG8_BAR __builtin_amdgcn_s_barrier()
; #define PG8_SCHED __builtin_amdgcn_sched_barrier(0)
; template <class Epi>
; __device__ __forceinline__ void gemm_phase(LAS unsigned char* lds, const Gemm g, const StaticOrder& S, const Epi& E) {
;     ...
;             const char* a2 = last ? nA : cA + ((Epi::HAS_MID && t + 2 >= nt1) ? dA2 : 0) + (size_t)(t + 2) * kstep; const char* b2 = last ? nB : cB + ((Epi::HAS_MID && t + 2 >= nt1) ? dB2 : 0) + (size_t)(t + 2) * kstep;
;             const char* a3 = a2 + kstep; const char* b3 = b2 + kstep;
;             PG8_LDB(B0, 0, 0); PG8_LDB(B1, 0, 1); PG8_SCHED; PG8_LDA(At, 0, 0); PG8_STAGE(PG8_SA(1, 1), a1 + hsA, voffA);
;             PG8_WAIT_V(8); PG8_WAIT_L(0); PG8_BAR; PG8_MMA(0, 0, At, B0); PG8_MMA(0, 1, At, B1); PG8_BAR; PG8_SCHED;
.LBB0_296:
	ds_read_b128 v[144:147], v157
	ds_read_b128 v[148:151], v157 offset:1024
	ds_read_b128 v[164:167], v157 offset:2048
	ds_read_b128 v[168:171], v157 offset:3072
	ds_read_b128 v[180:183], v158
	ds_read_b128 v[184:187], v158 offset:1024
	ds_read_b128 v[188:191], v158 offset:2048
	ds_read_b128 v[192:195], v158 offset:3072
	s_add_u32 s60, s12, 0x100
	s_addc_u32 s61, s13, 0
	s_cmp_eq_u32 s34, 40
	s_cselect_b32 s65, s1, s61
	s_cselect_b32 s64, s0, s60
	s_cselect_b32 s63, s59, s7
	s_cselect_b32 s62, s58, s6
	s_add_i32 m0, s5, 0xc000
	ds_read_b128 v[196:199], v159
	ds_read_b128 v[200:203], v159 offset:1024
	ds_read_b128 v[204:207], v159 offset:2048
	ds_read_b128 v[208:211], v159 offset:3072
	ds_read_b128 v[212:215], v159 offset:4096
	ds_read_b128 v[216:219], v159 offset:5120
	ds_read_b128 v[220:223], v159 offset:6144
	ds_read_b128 v[224:227], v159 offset:7168
	global_load_lds_dwordx4 v136, s[12:13]
	s_add_i32 m0, s5, 0xe000
	s_nop 0
	global_load_lds_dwordx4 v138, s[12:13]
	s_waitcnt vmcnt(8)
	s_waitcnt lgkmcnt(0)
	s_setprio 1
	s_barrier

; #define PG8_MMA(ai, bj, At, Bt) do { __builtin_amdgcn_s_setprio(1); _Pragma("unroll") for (int m = 0; m < 4; ++m) _Pragma("unroll") for (int n = 0; n < 2; ++n) _Pragma("unroll") for (int k = 0; k < 2; ++k) \
;         acc[ai][bj][m][n] = __builtin_amdgcn_mfma_f32_16x16x32_bf16(Bt[n][k], At[m][k], acc[ai][bj][m][n], 0, 0, 0); __builtin_amdgcn_s_setprio(0); } while (0)
; #define PG8_WAIT_V(n) asm volatile("s_waitcnt vmcnt(" #n ")" ::: "memory")
; #define PG8_WAIT_L(n) asm volatile("s_waitcnt lgkmcnt(" #n ")" ::: "memory")
; #define PG8_BAR __builtin_amdgcn_s_barrier()
; #define PG8_SCHED __builtin_amdgcn_sched_barrier(0)
; template <class Epi>
; __device__ __forceinline__ void gemm_phase(LAS unsigned char* lds, const Gemm g, const StaticOrder& S, const Epi& E) {
;     ...
;             PG8_WAIT_V(8); PG8_WAIT_L(0); PG8_BAR; PG8_MMA(0, 0, At, B0); PG8_MMA(0, 1, At, B1); PG8_BAR; PG8_SCHED;
	v_mfma_f32_16x16x32_bf16 v[124:127], v[144:147], v[196:199], v[124:127]
	v_mfma_f32_16x16x32_bf16 v[120:123], v[164:167], v[196:199], v[120:123]
	v_mfma_f32_16x16x32_bf16 v[108:111], v[144:147], v[204:207], v[108:111]
	v_mfma_f32_16x16x32_bf16 v[104:107], v[164:167], v[204:207], v[104:107]
	v_mfma_f32_16x16x32_bf16 v[92:95], v[144:147], v[212:215], v[92:95]
	v_mfma_f32_16x16x32_bf16 v[88:91], v[164:167], v[212:215], v[88:91]
	v_mfma_f32_16x16x32_bf16 v[76:79], v[144:147], v[220:223], v[76:79]
	v_mfma_f32_16x16x32_bf16 v[72:75], v[164:167], v[220:223], v[72:75]
	v_mfma_f32_16x16x32_bf16 v[124:127], v[148:151], v[200:203], v[124:127]
	v_mfma_f32_16x16x32_bf16 v[120:123], v[168:171], v[200:203], v[120:123]
	v_mfma_f32_16x16x32_bf16 v[108:111], v[148:151], v[208:211], v[108:111]
	v_mfma_f32_16x16x32_bf16 v[104:107], v[168:171], v[208:211], v[104:107]
	v_mfma_f32_16x16x32_bf16 v[92:95], v[148:151], v[216:219], v[92:95]
	v_mfma_f32_16x16x32_bf16 v[88:91], v[168:171], v[216:219], v[88:91]
	v_mfma_f32_16x16x32_bf16 v[76:79], v[148:151], v[224:227], v[76:79]
	v_mfma_f32_16x16x32_bf16 v[72:75], v[168:171], v[224:227], v[72:75]


; #define PG8_STAGE(bufoff, gbase, voff) do { _Pragma("unroll") for (int _i = 0; _i < 2; ++_i) \
;         __builtin_amdgcn_global_load_lds((const unsigned*)((const char*)(gbase) + (voff)[_i]), (LAS unsigned*)(lds + (bufoff) + ldsw + _i * 8192), 16, 0, 0); } while (0)
; #define PG8_LDA(dst, b, h) do { _Pragma("unroll") for (int m = 0; m < 4; ++m) _Pragma("unroll") for (int k = 0; k < 2; ++k) dst[m][k] = *(const LAS bf16x8*)(lds + PG8_SA(b, h) + aoff + m * 2048 + k * 1024); } while (0)
; #define PG8_MMA(ai, bj, At, Bt) do { __builtin_amdgcn_s_setprio(1); _Pragma("unroll") for (int m = 0; m < 4; ++m) _Pragma("unroll") for (int n = 0; n < 2; ++n) _Pragma("unroll") for (int k = 0; k < 2; ++k) \
;         acc[ai][bj][m][n] = __builtin_amdgcn_mfma_f32_16x16x32_bf16(Bt[n][k], At[m][k], acc[ai][bj][m][n], 0, 0, 0); __builtin_amdgcn_s_setprio(0); } while (0)
; #define PG8_WAIT_V(n) asm volatile("s_waitcnt vmcnt(" #n ")" ::: "memory")
; #define PG8_WAIT_L(n) asm volatile("s_waitcnt lgkmcnt(" #n ")" ::: "memory")
; #define PG8_BAR __builtin_amdgcn_s_barrier()
; #define PG8_SCHED __builtin_amdgcn_sched_barrier(0)
; template <class Epi>
; __device__ __forceinline__ void gemm_phase(LAS unsigned char* lds, const Gemm g, const StaticOrder& S, const Epi& E) {
;     ...
;             PG8_WAIT_V(8); PG8_WAIT_L(0); PG8_BAR; PG8_MMA(0, 0, At, B0); PG8_MMA(0, 1, At, B1); PG8_BAR; PG8_SCHED;
;             PG8_LDA(At, 0, 1); PG8_STAGE(PG8_SB(0, 0), b2, voffB); PG8_STAGE(PG8_SB(0, 1), b2 + hsB, voffB); PG8_STAGE(PG8_SA(0, 0), a2, voffA);
;             PG8_WAIT_V(8); PG8_WAIT_L(0); PG8_BAR; PG8_MMA(1, 0, At, B0); PG8_MMA(1, 1, At, B1); PG8_BAR; PG8_SCHED;
	v_mfma_f32_16x16x32_bf16 v[116:119], v[180:183], v[196:199], v[116:119]
	v_mfma_f32_16x16x32_bf16 v[112:115], v[188:191], v[196:199], v[112:115]
	v_mfma_f32_16x16x32_bf16 v[100:103], v[180:183], v[204:207], v[100:103]
	v_mfma_f32_16x16x32_bf16 v[96:99], v[188:191], v[204:207], v[96:99]
	v_mfma_f32_16x16x32_bf16 v[84:87], v[180:183], v[212:215], v[84:87]
	v_mfma_f32_16x16x32_bf16 v[80:83], v[188:191], v[212:215], v[80:83]
	v_mfma_f32_16x16x32_bf16 v[68:71], v[180:183], v[220:223], v[68:71]
	v_mfma_f32_16x16x32_bf16 v[64:67], v[188:191], v[220:223], v[64:67]
	v_mfma_f32_16x16x32_bf16 v[116:119], v[184:187], v[200:203], v[116:119]
	v_mfma_f32_16x16x32_bf16 v[112:115], v[192:195], v[200:203], v[112:115]
	v_mfma_f32_16x16x32_bf16 v[100:103], v[184:187], v[208:211], v[100:103]
	v_mfma_f32_16x16x32_bf16 v[96:99], v[192:195], v[208:211], v[96:99]
	v_mfma_f32_16x16x32_bf16 v[84:87], v[184:187], v[216:219], v[84:87]
	v_mfma_f32_16x16x32_bf16 v[80:83], v[192:195], v[216:219], v[80:83]
	v_mfma_f32_16x16x32_bf16 v[68:71], v[184:187], v[224:227], v[68:71]
	v_mfma_f32_16x16x32_bf16 v[64:67], v[192:195], v[224:227], v[64:67]
	s_setprio 0
	s_barrier
	s_add_i32 s12, s27, s4
	s_mov_b32 m0, s12
	ds_read_b128 v[196:199], v159 offset:16384
	ds_read_b128 v[200:203], v159 offset:17408
	ds_read_b128 v[204:207], v159 offset:18432
	ds_read_b128 v[208:211], v159 offset:19456
	ds_read_b128 v[212:215], v159 offset:20480
	ds_read_b128 v[216:219], v159 offset:21504
	ds_read_b128 v[220:223], v159 offset:22528
	ds_read_b128 v[224:227], v159 offset:23552
	global_load_lds_dwordx4 v130, s[62:63]
	s_add_i32 m0, s12, 0x2000
	s_add_u32 s12, s62, 0xb0000
	s_addc_u32 s13, s63, 0
	s_add_i32 s35, s28, s4
	global_load_lds_dwordx4 v134, s[62:63]
	s_mov_b32 m0, s35
	s_nop 0
	global_load_lds_dwordx4 v130, s[12:13]
	s_add_i32 m0, s35, 0x2000
	s_nop 0
	global_load_lds_dwordx4 v134, s[12:13]
	s_mov_b32 m0, s5
	s_nop 0
	global_load_lds_dwordx4 v128, s[64:65]
	s_mov_b32 m0, s16
	s_nop 0
	global_load_lds_dwordx4 v132, s[64:65]
	s_waitcnt vmcnt(8)
	s_waitcnt lgkmcnt(0)
	s_setprio 1
	s_barrier

; #define PG8_MMA(ai, bj, At, Bt) do { __builtin_amdgcn_s_setprio(1); _Pragma("unroll") for (int m = 0; m < 4; ++m) _Pragma("unroll") for (int n = 0; n < 2; ++n) _Pragma("unroll") for (int k = 0; k < 2; ++k) \
;         acc[ai][bj][m][n] = __builtin_amdgcn_mfma_f32_16x16x32_bf16(Bt[n][k], At[m][k], acc[ai][bj][m][n], 0, 0, 0); __builtin_amdgcn_s_setprio(0); } while (0)
; #define PG8_WAIT_V(n) asm volatile("s_waitcnt vmcnt(" #n ")" ::: "memory")
; #define PG8_WAIT_L(n) asm volatile("s_waitcnt lgkmcnt(" #n ")" ::: "memory")
; #define PG8_BAR __builtin_amdgcn_s_barrier()
; #define PG8_SCHED __builtin_amdgcn_sched_barrier(0)
; template <class Epi>
; __device__ __forceinline__ void gemm_phase(LAS unsigned char* lds, const Gemm g, const StaticOrder& S, const Epi& E) {
;     ...
;             PG8_WAIT_V(8); PG8_WAIT_L(0); PG8_BAR; PG8_MMA(1, 0, At, B0); PG8_MMA(1, 1, At, B1); PG8_BAR; PG8_SCHED;
	v_mfma_f32_16x16x32_bf16 v[60:63], v[144:147], v[196:199], v[60:63]
	v_mfma_f32_16x16x32_bf16 v[56:59], v[164:167], v[196:199], v[56:59]
	v_mfma_f32_16x16x32_bf16 v[44:47], v[144:147], v[204:207], v[44:47]
	v_mfma_f32_16x16x32_bf16 v[40:43], v[164:167], v[204:207], v[40:43]
	v_mfma_f32_16x16x32_bf16 v[28:31], v[144:147], v[212:215], v[28:31]
	v_mfma_f32_16x16x32_bf16 v[24:27], v[164:167], v[212:215], v[24:27]
	v_mfma_f32_16x16x32_bf16 v[12:15], v[144:147], v[220:223], v[12:15]
	v_mfma_f32_16x16x32_bf16 v[8:11], v[164:167], v[220:223], v[8:11]
	v_mfma_f32_16x16x32_bf16 v[60:63], v[148:151], v[200:203], v[60:63]
	v_mfma_f32_16x16x32_bf16 v[56:59], v[168:171], v[200:203], v[56:59]
	v_mfma_f32_16x16x32_bf16 v[44:47], v[148:151], v[208:211], v[44:47]
	v_mfma_f32_16x16x32_bf16 v[40:43], v[168:171], v[208:211], v[40:43]
	v_mfma_f32_16x16x32_bf16 v[28:31], v[148:151], v[216:219], v[28:31]
	v_mfma_f32_16x16x32_bf16 v[24:27], v[168:171], v[216:219], v[24:27]
	v_mfma_f32_16x16x32_bf16 v[12:15], v[148:151], v[224:227], v[12:15]
	v_mfma_f32_16x16x32_bf16 v[8:11], v[168:171], v[224:227], v[8:11]


; #define PG8_STAGE(bufoff, gbase, voff) do { _Pragma("unroll") for (int _i = 0; _i < 2; ++_i) \
;         __builtin_amdgcn_global_load_lds((const unsigned*)((const char*)(gbase) + (voff)[_i]), (LAS unsigned*)(lds + (bufoff) + ldsw + _i * 8192), 16, 0, 0); } while (0)
; #define PG8_LDA(dst, b, h) do { _Pragma("unroll") for (int m = 0; m < 4; ++m) _Pragma("unroll") for (int k = 0; k < 2; ++k) dst[m][k] = *(const LAS bf16x8*)(lds + PG8_SA(b, h) + aoff + m * 2048 + k * 1024); } while (0)
; #define PG8_LDB(dst, b, h) do { _Pragma("unroll") for (int n = 0; n < 2; ++n) _Pragma("unroll") for (int k = 0; k < 2; ++k) dst[n][k] = *(const LAS bf16x8*)(lds + PG8_SB(b, h) + boff + n * 2048 + k * 1024); } while (0)
; #define PG8_MMA(ai, bj, At, Bt) do { __builtin_amdgcn_s_setprio(1); _Pragma("unroll") for (int m = 0; m < 4; ++m) _Pragma("unroll") for (int n = 0; n < 2; ++n) _Pragma("unroll") for (int k = 0; k < 2; ++k) \
;         acc[ai][bj][m][n] = __builtin_amdgcn_mfma_f32_16x16x32_bf16(Bt[n][k], At[m][k], acc[ai][bj][m][n], 0, 0, 0); __builtin_amdgcn_s_setprio(0); } while (0)
; #define PG8_WAIT_V(n) asm volatile("s_waitcnt vmcnt(" #n ")" ::: "memory")
; #define PG8_WAIT_L(n) asm volatile("s_waitcnt lgkmcnt(" #n ")" ::: "memory")
; #define PG8_BAR __builtin_amdgcn_s_barrier()
; #define PG8_SCHED __builtin_amdgcn_sched_barrier(0)
; template <class Epi>
; __device__ __forceinline__ void gemm_phase(LAS unsigned char* lds, const Gemm g, const StaticOrder& S, const Epi& E) {
;     ...
;             PG8_WAIT_V(8); PG8_WAIT_L(0); PG8_BAR; PG8_MMA(1, 0, At, B0); PG8_MMA(1, 1, At, B1); PG8_BAR; PG8_SCHED;
;             PG8_LDB(B0, 1, 0); PG8_LDB(B1, 1, 1); PG8_SCHED; PG8_LDA(At, 1, 0); PG8_STAGE(PG8_SA(0, 1), a2 + hsA, voffA);
;             PG8_WAIT_V(8); PG8_WAIT_L(0); PG8_BAR; PG8_MMA(0, 0, At, B0); PG8_MMA(0, 1, At, B1); PG8_BAR; PG8_SCHED;
	v_mfma_f32_16x16x32_bf16 v[52:55], v[180:183], v[196:199], v[52:55]
	v_mfma_f32_16x16x32_bf16 v[48:51], v[188:191], v[196:199], v[48:51]
	v_mfma_f32_16x16x32_bf16 v[36:39], v[180:183], v[204:207], v[36:39]
	v_mfma_f32_16x16x32_bf16 v[32:35], v[188:191], v[204:207], v[32:35]
	v_mfma_f32_16x16x32_bf16 v[20:23], v[180:183], v[212:215], v[20:23]
	v_mfma_f32_16x16x32_bf16 v[16:19], v[188:191], v[212:215], v[16:19]
	v_mfma_f32_16x16x32_bf16 v[4:7], v[180:183], v[220:223], v[4:7]
	v_mfma_f32_16x16x32_bf16 v[0:3], v[188:191], v[220:223], v[0:3]
	v_mfma_f32_16x16x32_bf16 v[52:55], v[184:187], v[200:203], v[52:55]
	v_mfma_f32_16x16x32_bf16 v[48:51], v[192:195], v[200:203], v[48:51]
	v_mfma_f32_16x16x32_bf16 v[36:39], v[184:187], v[208:211], v[36:39]
	v_mfma_f32_16x16x32_bf16 v[32:35], v[192:195], v[208:211], v[32:35]
	v_mfma_f32_16x16x32_bf16 v[20:23], v[184:187], v[216:219], v[20:23]
	v_mfma_f32_16x16x32_bf16 v[16:19], v[192:195], v[216:219], v[16:19]
	v_mfma_f32_16x16x32_bf16 v[4:7], v[184:187], v[224:227], v[4:7]
	v_mfma_f32_16x16x32_bf16 v[0:3], v[192:195], v[224:227], v[0:3]
	s_setprio 0
	s_barrier
	s_add_i32 s35, 0, 0x18000
	v_add_u32_e32 v163, s35, v155
	s_add_i32 s36, 0, 0x1c000
	ds_read_b128 v[144:147], v163
	ds_read_b128 v[148:151], v163 offset:1024
	ds_read_b128 v[164:167], v163 offset:2048
	ds_read_b128 v[168:171], v163 offset:3072
	v_add_u32_e32 v163, s36, v155
	ds_read_b128 v[180:183], v163
	ds_read_b128 v[184:187], v163 offset:1024
	ds_read_b128 v[188:191], v163 offset:2048
	ds_read_b128 v[192:195], v163 offset:3072
	s_add_u32 s12, s64, 0xb0000
	s_addc_u32 s13, s65, 0
	s_mov_b32 m0, s17
	ds_read_b128 v[196:199], v159 offset:32768
	ds_read_b128 v[200:203], v159 offset:33792
	ds_read_b128 v[204:207], v159 offset:34816
	ds_read_b128 v[208:211], v159 offset:35840
	ds_read_b128 v[212:215], v159 offset:36864
	ds_read_b128 v[216:219], v159 offset:37888
	ds_read_b128 v[220:223], v159 offset:38912
	ds_read_b128 v[224:227], v159 offset:39936
	global_load_lds_dwordx4 v128, s[12:13]
	s_mov_b32 m0, s18
	s_nop 0
	global_load_lds_dwordx4 v132, s[12:13]
	s_waitcnt vmcnt(8)
	s_waitcnt lgkmcnt(0)
	s_setprio 1
	s_barrier

; #define PG8_MMA(ai, bj, At, Bt) do { __builtin_amdgcn_s_setprio(1); _Pragma("unroll") for (int m = 0; m < 4; ++m) _Pragma("unroll") for (int n = 0; n < 2; ++n) _Pragma("unroll") for (int k = 0; k < 2; ++k) \
;         acc[ai][bj][m][n] = __builtin_amdgcn_mfma_f32_16x16x32_bf16(Bt[n][k], At[m][k], acc[ai][bj][m][n], 0, 0, 0); __builtin_amdgcn_s_setprio(0); } while (0)
; #define PG8_WAIT_V(n) asm volatile("s_waitcnt vmcnt(" #n ")" ::: "memory")
; #define PG8_WAIT_L(n) asm volatile("s_waitcnt lgkmcnt(" #n ")" ::: "memory")
; #define PG8_BAR __builtin_amdgcn_s_barrier()
; #define PG8_SCHED __builtin_amdgcn_sched_barrier(0)
; template <class Epi>
; __device__ __forceinline__ void gemm_phase(LAS unsigned char* lds, const Gemm g, const StaticOrder& S, const Epi& E) {
;     ...
;             PG8_WAIT_V(8); PG8_WAIT_L(0); PG8_BAR; PG8_MMA(0, 0, At, B0); PG8_MMA(0, 1, At, B1); PG8_BAR; PG8_SCHED;
	v_mfma_f32_16x16x32_bf16 v[124:127], v[144:147], v[196:199], v[124:127]
	v_mfma_f32_16x16x32_bf16 v[120:123], v[164:167], v[196:199], v[120:123]
	v_mfma_f32_16x16x32_bf16 v[108:111], v[144:147], v[204:207], v[108:111]
	v_mfma_f32_16x16x32_bf16 v[104:107], v[164:167], v[204:207], v[104:107]
	v_mfma_f32_16x16x32_bf16 v[92:95], v[144:147], v[212:215], v[92:95]
	v_mfma_f32_16x16x32_bf16 v[88:91], v[164:167], v[212:215], v[88:91]
	v_mfma_f32_16x16x32_bf16 v[76:79], v[144:147], v[220:223], v[76:79]
	v_mfma_f32_16x16x32_bf16 v[72:75], v[164:167], v[220:223], v[72:75]
	v_mfma_f32_16x16x32_bf16 v[124:127], v[148:151], v[200:203], v[124:127]
	v_mfma_f32_16x16x32_bf16 v[120:123], v[168:171], v[200:203], v[120:123]
	v_mfma_f32_16x16x32_bf16 v[108:111], v[148:151], v[208:211], v[108:111]
	v_mfma_f32_16x16x32_bf16 v[104:107], v[168:171], v[208:211], v[104:107]
	v_mfma_f32_16x16x32_bf16 v[92:95], v[148:151], v[216:219], v[92:95]
	v_mfma_f32_16x16x32_bf16 v[88:91], v[168:171], v[216:219], v[88:91]
	v_mfma_f32_16x16x32_bf16 v[76:79], v[148:151], v[224:227], v[76:79]
	v_mfma_f32_16x16x32_bf16 v[72:75], v[168:171], v[224:227], v[72:75]


; #define PG8_STAGE(bufoff, gbase, voff) do { _Pragma("unroll") for (int _i = 0; _i < 2; ++_i) \
;         __builtin_amdgcn_global_load_lds((const unsigned*)((const char*)(gbase) + (voff)[_i]), (LAS unsigned*)(lds + (bufoff) + ldsw + _i * 8192), 16, 0, 0); } while (0)
; #define PG8_LDA(dst, b, h) do { _Pragma("unroll") for (int m = 0; m < 4; ++m) _Pragma("unroll") for (int k = 0; k < 2; ++k) dst[m][k] = *(const LAS bf16x8*)(lds + PG8_SA(b, h) + aoff + m * 2048 + k * 1024); } while (0)
; #define PG8_MMA(ai, bj, At, Bt) do { __builtin_amdgcn_s_setprio(1); _Pragma("unroll") for (int m = 0; m < 4; ++m) _Pragma("unroll") for (int n = 0; n < 2; ++n) _Pragma("unroll") for (int k = 0; k < 2; ++k) \
;         acc[ai][bj][m][n] = __builtin_amdgcn_mfma_f32_16x16x32_bf16(Bt[n][k], At[m][k], acc[ai][bj][m][n], 0, 0, 0); __builtin_amdgcn_s_setprio(0); } while (0)
; #define PG8_WAIT_V(n) asm volatile("s_waitcnt vmcnt(" #n ")" ::: "memory")
; #define PG8_WAIT_L(n) asm volatile("s_waitcnt lgkmcnt(" #n ")" ::: "memory")
; #define PG8_BAR __builtin_amdgcn_s_barrier()
; #define PG8_SCHED __builtin_amdgcn_sched_barrier(0)
; template <class Epi>
; __device__ __forceinline__ void gemm_phase(LAS unsigned char* lds, const Gemm g, const StaticOrder& S, const Epi& E) {
;     ...
;             PG8_WAIT_V(8); PG8_WAIT_L(0); PG8_BAR; PG8_MMA(0, 0, At, B0); PG8_MMA(0, 1, At, B1); PG8_BAR; PG8_SCHED;
;             PG8_LDA(At, 1, 1); PG8_STAGE(PG8_SB(1, 0), b3, voffB); PG8_STAGE(PG8_SB(1, 1), b3 + hsB, voffB); PG8_STAGE(PG8_SA(1, 0), a3, voffA);
;             PG8_WAIT_V(8); PG8_WAIT_L(0); PG8_BAR; PG8_MMA(1, 0, At, B0); PG8_MMA(1, 1, At, B1); PG8_BAR; PG8_SCHED;
	v_mfma_f32_16x16x32_bf16 v[116:119], v[180:183], v[196:199], v[116:119]
	v_mfma_f32_16x16x32_bf16 v[112:115], v[188:191], v[196:199], v[112:115]
	v_mfma_f32_16x16x32_bf16 v[100:103], v[180:183], v[204:207], v[100:103]
	v_mfma_f32_16x16x32_bf16 v[96:99], v[188:191], v[204:207], v[96:99]
	v_mfma_f32_16x16x32_bf16 v[84:87], v[180:183], v[212:215], v[84:87]
	v_mfma_f32_16x16x32_bf16 v[80:83], v[188:191], v[212:215], v[80:83]
	v_mfma_f32_16x16x32_bf16 v[68:71], v[180:183], v[220:223], v[68:71]
	v_mfma_f32_16x16x32_bf16 v[64:67], v[188:191], v[220:223], v[64:67]
	v_mfma_f32_16x16x32_bf16 v[116:119], v[184:187], v[200:203], v[116:119]
	v_mfma_f32_16x16x32_bf16 v[112:115], v[192:195], v[200:203], v[112:115]
	v_mfma_f32_16x16x32_bf16 v[100:103], v[184:187], v[208:211], v[100:103]
	v_mfma_f32_16x16x32_bf16 v[96:99], v[192:195], v[208:211], v[96:99]
	v_mfma_f32_16x16x32_bf16 v[84:87], v[184:187], v[216:219], v[84:87]
	v_mfma_f32_16x16x32_bf16 v[80:83], v[192:195], v[216:219], v[80:83]
	v_mfma_f32_16x16x32_bf16 v[68:71], v[184:187], v[224:227], v[68:71]
	v_mfma_f32_16x16x32_bf16 v[64:67], v[192:195], v[224:227], v[64:67]
	s_setprio 0
	s_barrier
	s_add_u32 s98, s62, 0x80
	s_addc_u32 s99, s63, 0
	s_add_u32 s100, s64, 0x80
	s_addc_u32 s101, s65, 0
	s_add_i32 s12, s35, s4
	s_mov_b32 m0, s12
	ds_read_b128 v[196:199], v159 offset:49152
	ds_read_b128 v[200:203], v159 offset:50176
	ds_read_b128 v[204:207], v159 offset:51200
	ds_read_b128 v[208:211], v159 offset:52224
	ds_read_b128 v[212:215], v159 offset:53248
	ds_read_b128 v[216:219], v159 offset:54272
	ds_read_b128 v[220:223], v159 offset:55296
	ds_read_b128 v[224:227], v159 offset:56320
	global_load_lds_dwordx4 v130, s[98:99]
	s_add_i32 m0, s12, 0x2000
	s_add_u32 s12, s62, 0xb0080
	s_addc_u32 s13, s63, 0
	s_add_i32 s35, s36, s4
	global_load_lds_dwordx4 v134, s[98:99]
	s_mov_b32 m0, s35
	s_nop 0
	global_load_lds_dwordx4 v130, s[12:13]
	s_add_i32 m0, s35, 0x2000
	s_nop 0
	global_load_lds_dwordx4 v134, s[12:13]
	s_mov_b32 m0, s22
	s_nop 0
	global_load_lds_dwordx4 v128, s[100:101]
	s_mov_b32 m0, s23
	s_nop 0
	global_load_lds_dwordx4 v132, s[100:101]
	s_waitcnt vmcnt(8)
	s_waitcnt lgkmcnt(0)
	s_setprio 1
	s_barrier

; #define PG8_MMA(ai, bj, At, Bt) do { __builtin_amdgcn_s_setprio(1); _Pragma("unroll") for (int m = 0; m < 4; ++m) _Pragma("unroll") for (int n = 0; n < 2; ++n) _Pragma("unroll") for (int k = 0; k < 2; ++k) \
;         acc[ai][bj][m][n] = __builtin_amdgcn_mfma_f32_16x16x32_bf16(Bt[n][k], At[m][k], acc[ai][bj][m][n], 0, 0, 0); __builtin_amdgcn_s_setprio(0); } while (0)
; #define PG8_WAIT_V(n) asm volatile("s_waitcnt vmcnt(" #n ")" ::: "memory")
; #define PG8_WAIT_L(n) asm volatile("s_waitcnt lgkmcnt(" #n ")" ::: "memory")
; #define PG8_BAR __builtin_amdgcn_s_barrier()
; #define PG8_SCHED __builtin_amdgcn_sched_barrier(0)
; template <class Epi>
; __device__ __forceinline__ void gemm_phase(LAS unsigned char* lds, const Gemm g, const StaticOrder& S, const Epi& E) {
;     ...
;             PG8_WAIT_V(8); PG8_WAIT_L(0); PG8_BAR; PG8_MMA(1, 0, At, B0); PG8_MMA(1, 1, At, B1); PG8_BAR; PG8_SCHED;
	v_mfma_f32_16x16x32_bf16 v[60:63], v[144:147], v[196:199], v[60:63]
	v_mfma_f32_16x16x32_bf16 v[56:59], v[164:167], v[196:199], v[56:59]
	v_mfma_f32_16x16x32_bf16 v[44:47], v[144:147], v[204:207], v[44:47]
	v_mfma_f32_16x16x32_bf16 v[40:43], v[164:167], v[204:207], v[40:43]
	v_mfma_f32_16x16x32_bf16 v[28:31], v[144:147], v[212:215], v[28:31]
	v_mfma_f32_16x16x32_bf16 v[24:27], v[164:167], v[212:215], v[24:27]
	v_mfma_f32_16x16x32_bf16 v[12:15], v[144:147], v[220:223], v[12:15]
	v_mfma_f32_16x16x32_bf16 v[8:11], v[164:167], v[220:223], v[8:11]
	v_mfma_f32_16x16x32_bf16 v[60:63], v[148:151], v[200:203], v[60:63]
	v_mfma_f32_16x16x32_bf16 v[56:59], v[168:171], v[200:203], v[56:59]
	v_mfma_f32_16x16x32_bf16 v[44:47], v[148:151], v[208:211], v[44:47]
	v_mfma_f32_16x16x32_bf16 v[40:43], v[168:171], v[208:211], v[40:43]
	v_mfma_f32_16x16x32_bf16 v[28:31], v[148:151], v[216:219], v[28:31]
	v_mfma_f32_16x16x32_bf16 v[24:27], v[168:171], v[216:219], v[24:27]
	v_mfma_f32_16x16x32_bf16 v[12:15], v[148:151], v[224:227], v[12:15]
	v_mfma_f32_16x16x32_bf16 v[8:11], v[168:171], v[224:227], v[8:11]


; #define PG8_MMA(ai, bj, At, Bt) do { __builtin_amdgcn_s_setprio(1); _Pragma("unroll") for (int m = 0; m < 4; ++m) _Pragma("unroll") for (int n = 0; n < 2; ++n) _Pragma("unroll") for (int k = 0; k < 2; ++k) \
;         acc[ai][bj][m][n] = __builtin_amdgcn_mfma_f32_16x16x32_bf16(Bt[n][k], At[m][k], acc[ai][bj][m][n], 0, 0, 0); __builtin_amdgcn_s_setprio(0); } while (0)
; #define PG8_WAIT_V(n) asm volatile("s_waitcnt vmcnt(" #n ")" ::: "memory")
; #define PG8_WAIT_L(n) asm volatile("s_waitcnt lgkmcnt(" #n ")" ::: "memory")
; #define PG8_BAR __builtin_amdgcn_s_barrier()
; #define PG8_SCHED __builtin_amdgcn_sched_barrier(0)
; template <class Epi>
; __device__ __forceinline__ void gemm_phase(LAS unsigned char* lds, const Gemm g, const StaticOrder& S, const Epi& E) {
;     ...
;         for (int t = 0; t < nt; t += 2) {
;     ...
;             PG8_WAIT_V(8); PG8_WAIT_L(0); PG8_BAR; PG8_MMA(1, 0, At, B0); PG8_MMA(1, 1, At, B1); PG8_BAR; PG8_SCHED;
;         }
;         if (wr == 0) PG8_BAR;
	v_mfma_f32_16x16x32_bf16 v[52:55], v[180:183], v[196:199], v[52:55]
	v_mfma_f32_16x16x32_bf16 v[48:51], v[188:191], v[196:199], v[48:51]
	v_mfma_f32_16x16x32_bf16 v[36:39], v[180:183], v[204:207], v[36:39]
	v_mfma_f32_16x16x32_bf16 v[32:35], v[188:191], v[204:207], v[32:35]
	v_mfma_f32_16x16x32_bf16 v[20:23], v[180:183], v[212:215], v[20:23]
	v_mfma_f32_16x16x32_bf16 v[16:19], v[188:191], v[212:215], v[16:19]
	v_mfma_f32_16x16x32_bf16 v[4:7], v[180:183], v[220:223], v[4:7]
	v_mfma_f32_16x16x32_bf16 v[0:3], v[188:191], v[220:223], v[0:3]
	v_mfma_f32_16x16x32_bf16 v[52:55], v[184:187], v[200:203], v[52:55]
	v_mfma_f32_16x16x32_bf16 v[48:51], v[192:195], v[200:203], v[48:51]
	v_mfma_f32_16x16x32_bf16 v[36:39], v[184:187], v[208:211], v[36:39]
	v_mfma_f32_16x16x32_bf16 v[32:35], v[192:195], v[208:211], v[32:35]
	v_mfma_f32_16x16x32_bf16 v[20:23], v[184:187], v[216:219], v[20:23]
	v_mfma_f32_16x16x32_bf16 v[16:19], v[192:195], v[216:219], v[16:19]
	v_mfma_f32_16x16x32_bf16 v[4:7], v[184:187], v[224:227], v[4:7]
	v_mfma_f32_16x16x32_bf16 v[0:3], v[192:195], v[224:227], v[0:3]
	s_setprio 0
	s_barrier
	s_add_i32 s34, s34, 2
	s_add_u32 s6, s6, 0x100
	s_addc_u32 s7, s7, 0
	s_cmp_gt_u32 s34, 41
	s_mov_b64 s[12:13], s[60:61]
	s_cbranch_scc0 .LBB0_296
	s_and_b64 vcc, exec, s[42:43]
	s_cbranch_vccz .LBB0_299
	s_barrier

; #define PG8_STAGE(bufoff, gbase, voff) do { _Pragma("unroll") for (int _i = 0; _i < 2; ++_i) \
;         __builtin_amdgcn_global_load_lds((const unsigned*)((const char*)(gbase) + (voff)[_i]), (LAS unsigned*)(lds + (bufoff) + ldsw + _i * 8192), 16, 0, 0); } while (0)
; #define PG8_LDA(dst, b, h) do { _Pragma("unroll") for (int m = 0; m < 4; ++m) _Pragma("unroll") for (int k = 0; k < 2; ++k) dst[m][k] = *(const LAS bf16x8*)(lds + PG8_SA(b, h) + aoff + m * 2048 + k * 1024); } while (0)
; #define PG8_LDB(dst, b, h) do { _Pragma("unroll") for (int n = 0; n < 2; ++n) _Pragma("unroll") for (int k = 0; k < 2; ++k) dst[n][k] = *(const LAS bf16x8*)(lds + PG8_SB(b, h) + boff + n * 2048 + k * 1024); } while (0)
; #define PG8_MMA(ai, bj, At, Bt) do { __builtin_amdgcn_s_setprio(1); _Pragma("unroll") for (int m = 0; m < 4; ++m) _Pragma("unroll") for (int n = 0; n < 2; ++n) _Pragma("unroll") for (int k = 0; k < 2; ++k) \
;         acc[ai][bj][m][n] = __builtin_amdgcn_mfma_f32_16x16x32_bf16(Bt[n][k], At[m][k], acc[ai][bj][m][n], 0, 0, 0); __builtin_amdgcn_s_setprio(0); } while (0)
; #define PG8_WAIT_V(n) asm volatile("s_waitcnt vmcnt(" #n ")" ::: "memory")
; #define PG8_WAIT_L(n) asm volatile("s_waitcnt lgkmcnt(" #n ")" ::: "memory")
; #define PG8_BAR __builtin_amdgcn_s_barrier()
; #define PG8_SCHED __builtin_amdgcn_sched_barrier(0)
; template <class Epi>
; __device__ __forceinline__ void gemm_phase(LAS unsigned char* lds, const Gemm g, const StaticOrder& S, const Epi& E) {
;     ...
;             const char* a2 = last ? nA : cA + ((Epi::HAS_MID && t + 2 >= nt1) ? dA2 : 0) + (size_t)(t + 2) * kstep; const char* b2 = last ? nB : cB + ((Epi::HAS_MID && t + 2 >= nt1) ? dB2 : 0) + (size_t)(t + 2) * kstep;
;             const char* a3 = a2 + kstep; const char* b3 = b2 + kstep;
;             PG8_LDB(B0, 0, 0); PG8_LDB(B1, 0, 1); PG8_SCHED; PG8_LDA(At, 0, 0); PG8_STAGE(PG8_SA(1, 1), a1 + hsA, voffA);
;             PG8_WAIT_V(8); PG8_WAIT_L(0); PG8_BAR; PG8_MMA(0, 0, At, B0); PG8_MMA(0, 1, At, B1); PG8_BAR; PG8_SCHED;
.LBB0_414:
	ds_read_b128 v[152:155], v167
	ds_read_b128 v[156:159], v167 offset:1024
	ds_read_b128 v[162:165], v167 offset:2048
	ds_read_b128 v[180:183], v167 offset:3072
	ds_read_b128 v[184:187], v168
	ds_read_b128 v[188:191], v168 offset:1024
	ds_read_b128 v[192:195], v168 offset:2048
	ds_read_b128 v[196:199], v168 offset:3072
	s_add_u32 s12, s10, 0xfffc0080
	s_addc_u32 s13, s11, -1
	s_cmp_eq_u32 s17, 12
	s_cselect_b32 s87, s0, s13
	s_cselect_b32 s86, s2, s12
	s_cselect_b32 s13, s3, s15
	s_cselect_b32 s12, s6, s7
	s_add_i32 m0, s5, 0xc000
	ds_read_b128 v[200:203], v169
	ds_read_b128 v[204:207], v169 offset:1024
	ds_read_b128 v[208:211], v169 offset:2048
	ds_read_b128 v[212:215], v169 offset:3072
	ds_read_b128 v[216:219], v169 offset:4096
	ds_read_b128 v[220:223], v169 offset:5120
	ds_read_b128 v[224:227], v169 offset:6144
	ds_read_b128 v[228:231], v169 offset:7168
	global_load_lds_dwordx4 v144, s[10:11]
	s_add_i32 m0, s5, 0xe000
	s_nop 0
	global_load_lds_dwordx4 v146, s[10:11]
	s_waitcnt vmcnt(8)
	s_waitcnt lgkmcnt(0)
	s_setprio 1
	s_barrier

; #define PG8_MMA(ai, bj, At, Bt) do { __builtin_amdgcn_s_setprio(1); _Pragma("unroll") for (int m = 0; m < 4; ++m) _Pragma("unroll") for (int n = 0; n < 2; ++n) _Pragma("unroll") for (int k = 0; k < 2; ++k) \
;         acc[ai][bj][m][n] = __builtin_amdgcn_mfma_f32_16x16x32_bf16(Bt[n][k], At[m][k], acc[ai][bj][m][n], 0, 0, 0); __builtin_amdgcn_s_setprio(0); } while (0)
; #define PG8_WAIT_V(n) asm volatile("s_waitcnt vmcnt(" #n ")" ::: "memory")
; #define PG8_WAIT_L(n) asm volatile("s_waitcnt lgkmcnt(" #n ")" ::: "memory")
; #define PG8_BAR __builtin_amdgcn_s_barrier()
; #define PG8_SCHED __builtin_amdgcn_sched_barrier(0)
; template <class Epi>
; __device__ __forceinline__ void gemm_phase(LAS unsigned char* lds, const Gemm g, const StaticOrder& S, const Epi& E) {
;     ...
;             PG8_WAIT_V(8); PG8_WAIT_L(0); PG8_BAR; PG8_MMA(0, 0, At, B0); PG8_MMA(0, 1, At, B1); PG8_BAR; PG8_SCHED;
	v_mfma_f32_16x16x32_bf16 v[124:127], v[152:155], v[200:203], v[124:127]
	v_mfma_f32_16x16x32_bf16 v[120:123], v[162:165], v[200:203], v[120:123]
	v_mfma_f32_16x16x32_bf16 v[108:111], v[152:155], v[208:211], v[108:111]
	v_mfma_f32_16x16x32_bf16 v[104:107], v[162:165], v[208:211], v[104:107]
	v_mfma_f32_16x16x32_bf16 v[92:95], v[152:155], v[216:219], v[92:95]
	v_mfma_f32_16x16x32_bf16 v[88:91], v[162:165], v[216:219], v[88:91]
	v_mfma_f32_16x16x32_bf16 v[76:79], v[152:155], v[224:227], v[76:79]
	v_mfma_f32_16x16x32_bf16 v[72:75], v[162:165], v[224:227], v[72:75]
	v_mfma_f32_16x16x32_bf16 v[124:127], v[156:159], v[204:207], v[124:127]
	v_mfma_f32_16x16x32_bf16 v[120:123], v[180:183], v[204:207], v[120:123]
	v_mfma_f32_16x16x32_bf16 v[108:111], v[156:159], v[212:215], v[108:111]
	v_mfma_f32_16x16x32_bf16 v[104:107], v[180:183], v[212:215], v[104:107]
	v_mfma_f32_16x16x32_bf16 v[92:95], v[156:159], v[220:223], v[92:95]
	v_mfma_f32_16x16x32_bf16 v[88:91], v[180:183], v[220:223], v[88:91]
	v_mfma_f32_16x16x32_bf16 v[76:79], v[156:159], v[228:231], v[76:79]
	v_mfma_f32_16x16x32_bf16 v[72:75], v[180:183], v[228:231], v[72:75]


; #define PG8_STAGE(bufoff, gbase, voff) do { _Pragma("unroll") for (int _i = 0; _i < 2; ++_i) \
;         __builtin_amdgcn_global_load_lds((const unsigned*)((const char*)(gbase) + (voff)[_i]), (LAS unsigned*)(lds + (bufoff) + ldsw + _i * 8192), 16, 0, 0); } while (0)
; #define PG8_LDA(dst, b, h) do { _Pragma("unroll") for (int m = 0; m < 4; ++m) _Pragma("unroll") for (int k = 0; k < 2; ++k) dst[m][k] = *(const LAS bf16x8*)(lds + PG8_SA(b, h) + aoff + m * 2048 + k * 1024); } while (0)
; #define PG8_MMA(ai, bj, At, Bt) do { __builtin_amdgcn_s_setprio(1); _Pragma("unroll") for (int m = 0; m < 4; ++m) _Pragma("unroll") for (int n = 0; n < 2; ++n) _Pragma("unroll") for (int k = 0; k < 2; ++k) \
;         acc[ai][bj][m][n] = __builtin_amdgcn_mfma_f32_16x16x32_bf16(Bt[n][k], At[m][k], acc[ai][bj][m][n], 0, 0, 0); __builtin_amdgcn_s_setprio(0); } while (0)
; #define PG8_WAIT_V(n) asm volatile("s_waitcnt vmcnt(" #n ")" ::: "memory")
; #define PG8_WAIT_L(n) asm volatile("s_waitcnt lgkmcnt(" #n ")" ::: "memory")
; #define PG8_BAR __builtin_amdgcn_s_barrier()
; #define PG8_SCHED __builtin_amdgcn_sched_barrier(0)
; template <class Epi>
; __device__ __forceinline__ void gemm_phase(LAS unsigned char* lds, const Gemm g, const StaticOrder& S, const Epi& E) {
;     ...
;             PG8_WAIT_V(8); PG8_WAIT_L(0); PG8_BAR; PG8_MMA(0, 0, At, B0); PG8_MMA(0, 1, At, B1); PG8_BAR; PG8_SCHED;
;             PG8_LDA(At, 0, 1); PG8_STAGE(PG8_SB(0, 0), b2, voffB); PG8_STAGE(PG8_SB(0, 1), b2 + hsB, voffB); PG8_STAGE(PG8_SA(0, 0), a2, voffA);
;             PG8_WAIT_V(8); PG8_WAIT_L(0); PG8_BAR; PG8_MMA(1, 0, At, B0); PG8_MMA(1, 1, At, B1); PG8_BAR; PG8_SCHED;
	v_mfma_f32_16x16x32_bf16 v[116:119], v[184:187], v[200:203], v[116:119]
	v_mfma_f32_16x16x32_bf16 v[112:115], v[192:195], v[200:203], v[112:115]
	v_mfma_f32_16x16x32_bf16 v[100:103], v[184:187], v[208:211], v[100:103]
	v_mfma_f32_16x16x32_bf16 v[96:99], v[192:195], v[208:211], v[96:99]
	v_mfma_f32_16x16x32_bf16 v[84:87], v[184:187], v[216:219], v[84:87]
	v_mfma_f32_16x16x32_bf16 v[80:83], v[192:195], v[216:219], v[80:83]
	v_mfma_f32_16x16x32_bf16 v[68:71], v[184:187], v[224:227], v[68:71]
	v_mfma_f32_16x16x32_bf16 v[64:67], v[192:195], v[224:227], v[64:67]
	v_mfma_f32_16x16x32_bf16 v[116:119], v[188:191], v[204:207], v[116:119]
	v_mfma_f32_16x16x32_bf16 v[112:115], v[196:199], v[204:207], v[112:115]
	v_mfma_f32_16x16x32_bf16 v[100:103], v[188:191], v[212:215], v[100:103]
	v_mfma_f32_16x16x32_bf16 v[96:99], v[196:199], v[212:215], v[96:99]
	v_mfma_f32_16x16x32_bf16 v[84:87], v[188:191], v[220:223], v[84:87]
	v_mfma_f32_16x16x32_bf16 v[80:83], v[196:199], v[220:223], v[80:83]
	v_mfma_f32_16x16x32_bf16 v[68:71], v[188:191], v[228:231], v[68:71]
	v_mfma_f32_16x16x32_bf16 v[64:67], v[196:199], v[228:231], v[64:67]
	s_setprio 0
	s_barrier
	s_add_i32 s19, s65, s4
	s_mov_b32 m0, s19
	ds_read_b128 v[200:203], v169 offset:16384
	ds_read_b128 v[204:207], v169 offset:17408
	ds_read_b128 v[208:211], v169 offset:18432
	ds_read_b128 v[212:215], v169 offset:19456
	ds_read_b128 v[216:219], v169 offset:20480
	ds_read_b128 v[220:223], v169 offset:21504
	ds_read_b128 v[224:227], v169 offset:22528
	ds_read_b128 v[228:231], v169 offset:23552
	global_load_lds_dwordx4 v130, s[12:13]
	s_add_i32 m0, s19, 0x2000
	s_add_u32 s24, s12, 0x40000
	s_addc_u32 s25, s13, 0
	s_add_i32 s19, s76, s4
	global_load_lds_dwordx4 v134, s[12:13]
	s_mov_b32 m0, s19
	s_nop 0
	global_load_lds_dwordx4 v130, s[24:25]
	s_add_i32 m0, s19, 0x2000
	s_nop 0
	global_load_lds_dwordx4 v134, s[24:25]
	s_mov_b32 m0, s5
	s_nop 0
	global_load_lds_dwordx4 v128, s[86:87]
	s_mov_b32 m0, s62
	s_nop 0
	global_load_lds_dwordx4 v132, s[86:87]
	s_waitcnt vmcnt(8)
	s_waitcnt lgkmcnt(0)
	s_setprio 1
	s_barrier

; #define PG8_MMA(ai, bj, At, Bt) do { __builtin_amdgcn_s_setprio(1); _Pragma("unroll") for (int m = 0; m < 4; ++m) _Pragma("unroll") for (int n = 0; n < 2; ++n) _Pragma("unroll") for (int k = 0; k < 2; ++k) \
;         acc[ai][bj][m][n] = __builtin_amdgcn_mfma_f32_16x16x32_bf16(Bt[n][k], At[m][k], acc[ai][bj][m][n], 0, 0, 0); __builtin_amdgcn_s_setprio(0); } while (0)
; #define PG8_WAIT_V(n) asm volatile("s_waitcnt vmcnt(" #n ")" ::: "memory")
; #define PG8_WAIT_L(n) asm volatile("s_waitcnt lgkmcnt(" #n ")" ::: "memory")
; #define PG8_BAR __builtin_amdgcn_s_barrier()
; #define PG8_SCHED __builtin_amdgcn_sched_barrier(0)
; template <class Epi>
; __device__ __forceinline__ void gemm_phase(LAS unsigned char* lds, const Gemm g, const StaticOrder& S, const Epi& E) {
;     ...
;             PG8_WAIT_V(8); PG8_WAIT_L(0); PG8_BAR; PG8_MMA(1, 0, At, B0); PG8_MMA(1, 1, At, B1); PG8_BAR; PG8_SCHED;
	v_mfma_f32_16x16x32_bf16 v[60:63], v[152:155], v[200:203], v[60:63]
	v_mfma_f32_16x16x32_bf16 v[56:59], v[162:165], v[200:203], v[56:59]
	v_mfma_f32_16x16x32_bf16 v[44:47], v[152:155], v[208:211], v[44:47]
	v_mfma_f32_16x16x32_bf16 v[40:43], v[162:165], v[208:211], v[40:43]
	v_mfma_f32_16x16x32_bf16 v[28:31], v[152:155], v[216:219], v[28:31]
	v_mfma_f32_16x16x32_bf16 v[24:27], v[162:165], v[216:219], v[24:27]
	v_mfma_f32_16x16x32_bf16 v[12:15], v[152:155], v[224:227], v[12:15]
	v_mfma_f32_16x16x32_bf16 v[8:11], v[162:165], v[224:227], v[8:11]
	v_mfma_f32_16x16x32_bf16 v[60:63], v[156:159], v[204:207], v[60:63]
	v_mfma_f32_16x16x32_bf16 v[56:59], v[180:183], v[204:207], v[56:59]
	v_mfma_f32_16x16x32_bf16 v[44:47], v[156:159], v[212:215], v[44:47]
	v_mfma_f32_16x16x32_bf16 v[40:43], v[180:183], v[212:215], v[40:43]
	v_mfma_f32_16x16x32_bf16 v[28:31], v[156:159], v[220:223], v[28:31]
	v_mfma_f32_16x16x32_bf16 v[24:27], v[180:183], v[220:223], v[24:27]
	v_mfma_f32_16x16x32_bf16 v[12:15], v[156:159], v[228:231], v[12:15]
	v_mfma_f32_16x16x32_bf16 v[8:11], v[180:183], v[228:231], v[8:11]


; #define PG8_STAGE(bufoff, gbase, voff) do { _Pragma("unroll") for (int _i = 0; _i < 2; ++_i) \
;         __builtin_amdgcn_global_load_lds((const unsigned*)((const char*)(gbase) + (voff)[_i]), (LAS unsigned*)(lds + (bufoff) + ldsw + _i * 8192), 16, 0, 0); } while (0)
; #define PG8_LDA(dst, b, h) do { _Pragma("unroll") for (int m = 0; m < 4; ++m) _Pragma("unroll") for (int k = 0; k < 2; ++k) dst[m][k] = *(const LAS bf16x8*)(lds + PG8_SA(b, h) + aoff + m * 2048 + k * 1024); } while (0)
; #define PG8_LDB(dst, b, h) do { _Pragma("unroll") for (int n = 0; n < 2; ++n) _Pragma("unroll") for (int k = 0; k < 2; ++k) dst[n][k] = *(const LAS bf16x8*)(lds + PG8_SB(b, h) + boff + n * 2048 + k * 1024); } while (0)
; #define PG8_MMA(ai, bj, At, Bt) do { __builtin_amdgcn_s_setprio(1); _Pragma("unroll") for (int m = 0; m < 4; ++m) _Pragma("unroll") for (int n = 0; n < 2; ++n) _Pragma("unroll") for (int k = 0; k < 2; ++k) \
;         acc[ai][bj][m][n] = __builtin_amdgcn_mfma_f32_16x16x32_bf16(Bt[n][k], At[m][k], acc[ai][bj][m][n], 0, 0, 0); __builtin_amdgcn_s_setprio(0); } while (0)
; #define PG8_WAIT_V(n) asm volatile("s_waitcnt vmcnt(" #n ")" ::: "memory")
; #define PG8_WAIT_L(n) asm volatile("s_waitcnt lgkmcnt(" #n ")" ::: "memory")
; #define PG8_BAR __builtin_amdgcn_s_barrier()
; #define PG8_SCHED __builtin_amdgcn_sched_barrier(0)
; template <class Epi>
; __device__ __forceinline__ void gemm_phase(LAS unsigned char* lds, const Gemm g, const StaticOrder& S, const Epi& E) {
;     ...
;             PG8_WAIT_V(8); PG8_WAIT_L(0); PG8_BAR; PG8_MMA(1, 0, At, B0); PG8_MMA(1, 1, At, B1); PG8_BAR; PG8_SCHED;
;             PG8_LDB(B0, 1, 0); PG8_LDB(B1, 1, 1); PG8_SCHED; PG8_LDA(At, 1, 0); PG8_STAGE(PG8_SA(0, 1), a2 + hsA, voffA);
;             PG8_WAIT_V(8); PG8_WAIT_L(0); PG8_BAR; PG8_MMA(0, 0, At, B0); PG8_MMA(0, 1, At, B1); PG8_BAR; PG8_SCHED;
	v_mfma_f32_16x16x32_bf16 v[52:55], v[184:187], v[200:203], v[52:55]
	v_mfma_f32_16x16x32_bf16 v[48:51], v[192:195], v[200:203], v[48:51]
	v_mfma_f32_16x16x32_bf16 v[36:39], v[184:187], v[208:211], v[36:39]
	v_mfma_f32_16x16x32_bf16 v[32:35], v[192:195], v[208:211], v[32:35]
	v_mfma_f32_16x16x32_bf16 v[20:23], v[184:187], v[216:219], v[20:23]
	v_mfma_f32_16x16x32_bf16 v[16:19], v[192:195], v[216:219], v[16:19]
	v_mfma_f32_16x16x32_bf16 v[4:7], v[184:187], v[224:227], v[4:7]
	v_mfma_f32_16x16x32_bf16 v[0:3], v[192:195], v[224:227], v[0:3]
	v_mfma_f32_16x16x32_bf16 v[52:55], v[188:191], v[204:207], v[52:55]
	v_mfma_f32_16x16x32_bf16 v[48:51], v[196:199], v[204:207], v[48:51]
	v_mfma_f32_16x16x32_bf16 v[36:39], v[188:191], v[212:215], v[36:39]
	v_mfma_f32_16x16x32_bf16 v[32:35], v[196:199], v[212:215], v[32:35]
	v_mfma_f32_16x16x32_bf16 v[20:23], v[188:191], v[220:223], v[20:23]
	v_mfma_f32_16x16x32_bf16 v[16:19], v[196:199], v[220:223], v[16:19]
	v_mfma_f32_16x16x32_bf16 v[4:7], v[188:191], v[228:231], v[4:7]
	v_mfma_f32_16x16x32_bf16 v[0:3], v[196:199], v[228:231], v[0:3]
	s_setprio 0
	s_barrier
	s_add_i32 s19, 0, 0x18000
	v_add_u32_e32 v136, s19, v166
	s_add_i32 s22, 0, 0x1c000
	ds_read_b128 v[152:155], v136
	ds_read_b128 v[156:159], v136 offset:1024
	ds_read_b128 v[162:165], v136 offset:2048
	ds_read_b128 v[180:183], v136 offset:3072
	v_add_u32_e32 v136, s22, v166
	ds_read_b128 v[184:187], v136
	ds_read_b128 v[188:191], v136 offset:1024
	ds_read_b128 v[192:195], v136 offset:2048
	ds_read_b128 v[196:199], v136 offset:3072
	s_add_u32 s24, s86, 0x40000
	s_addc_u32 s25, s87, 0
	s_mov_b32 m0, s63
	ds_read_b128 v[200:203], v169 offset:32768
	ds_read_b128 v[204:207], v169 offset:33792
	ds_read_b128 v[208:211], v169 offset:34816
	ds_read_b128 v[212:215], v169 offset:35840
	ds_read_b128 v[216:219], v169 offset:36864
	ds_read_b128 v[220:223], v169 offset:37888
	ds_read_b128 v[224:227], v169 offset:38912
	ds_read_b128 v[228:231], v169 offset:39936
	global_load_lds_dwordx4 v128, s[24:25]
	s_mov_b32 m0, s74
	s_nop 0
	global_load_lds_dwordx4 v132, s[24:25]
	s_waitcnt vmcnt(8)
	s_waitcnt lgkmcnt(0)
	s_setprio 1
	s_barrier

; #define PG8_MMA(ai, bj, At, Bt) do { __builtin_amdgcn_s_setprio(1); _Pragma("unroll") for (int m = 0; m < 4; ++m) _Pragma("unroll") for (int n = 0; n < 2; ++n) _Pragma("unroll") for (int k = 0; k < 2; ++k) \
;         acc[ai][bj][m][n] = __builtin_amdgcn_mfma_f32_16x16x32_bf16(Bt[n][k], At[m][k], acc[ai][bj][m][n], 0, 0, 0); __builtin_amdgcn_s_setprio(0); } while (0)
; #define PG8_WAIT_V(n) asm volatile("s_waitcnt vmcnt(" #n ")" ::: "memory")
; #define PG8_WAIT_L(n) asm volatile("s_waitcnt lgkmcnt(" #n ")" ::: "memory")
; #define PG8_BAR __builtin_amdgcn_s_barrier()
; #define PG8_SCHED __builtin_amdgcn_sched_barrier(0)
; template <class Epi>
; __device__ __forceinline__ void gemm_phase(LAS unsigned char* lds, const Gemm g, const StaticOrder& S, const Epi& E) {
;     ...
;             PG8_WAIT_V(8); PG8_WAIT_L(0); PG8_BAR; PG8_MMA(0, 0, At, B0); PG8_MMA(0, 1, At, B1); PG8_BAR; PG8_SCHED;
	v_mfma_f32_16x16x32_bf16 v[124:127], v[152:155], v[200:203], v[124:127]
	v_mfma_f32_16x16x32_bf16 v[120:123], v[162:165], v[200:203], v[120:123]
	v_mfma_f32_16x16x32_bf16 v[108:111], v[152:155], v[208:211], v[108:111]
	v_mfma_f32_16x16x32_bf16 v[104:107], v[162:165], v[208:211], v[104:107]
	v_mfma_f32_16x16x32_bf16 v[92:95], v[152:155], v[216:219], v[92:95]
	v_mfma_f32_16x16x32_bf16 v[88:91], v[162:165], v[216:219], v[88:91]
	v_mfma_f32_16x16x32_bf16 v[76:79], v[152:155], v[224:227], v[76:79]
	v_mfma_f32_16x16x32_bf16 v[72:75], v[162:165], v[224:227], v[72:75]
	v_mfma_f32_16x16x32_bf16 v[124:127], v[156:159], v[204:207], v[124:127]
	v_mfma_f32_16x16x32_bf16 v[120:123], v[180:183], v[204:207], v[120:123]
	v_mfma_f32_16x16x32_bf16 v[108:111], v[156:159], v[212:215], v[108:111]
	v_mfma_f32_16x16x32_bf16 v[104:107], v[180:183], v[212:215], v[104:107]
	v_mfma_f32_16x16x32_bf16 v[92:95], v[156:159], v[220:223], v[92:95]
	v_mfma_f32_16x16x32_bf16 v[88:91], v[180:183], v[220:223], v[88:91]
	v_mfma_f32_16x16x32_bf16 v[76:79], v[156:159], v[228:231], v[76:79]
	v_mfma_f32_16x16x32_bf16 v[72:75], v[180:183], v[228:231], v[72:75]


; #define PG8_STAGE(bufoff, gbase, voff) do { _Pragma("unroll") for (int _i = 0; _i < 2; ++_i) \
;         __builtin_amdgcn_global_load_lds((const unsigned*)((const char*)(gbase) + (voff)[_i]), (LAS unsigned*)(lds + (bufoff) + ldsw + _i * 8192), 16, 0, 0); } while (0)
; #define PG8_LDA(dst, b, h) do { _Pragma("unroll") for (int m = 0; m < 4; ++m) _Pragma("unroll") for (int k = 0; k < 2; ++k) dst[m][k] = *(const LAS bf16x8*)(lds + PG8_SA(b, h) + aoff + m * 2048 + k * 1024); } while (0)
; #define PG8_MMA(ai, bj, At, Bt) do { __builtin_amdgcn_s_setprio(1); _Pragma("unroll") for (int m = 0; m < 4; ++m) _Pragma("unroll") for (int n = 0; n < 2; ++n) _Pragma("unroll") for (int k = 0; k < 2; ++k) \
;         acc[ai][bj][m][n] = __builtin_amdgcn_mfma_f32_16x16x32_bf16(Bt[n][k], At[m][k], acc[ai][bj][m][n], 0, 0, 0); __builtin_amdgcn_s_setprio(0); } while (0)
; #define PG8_WAIT_V(n) asm volatile("s_waitcnt vmcnt(" #n ")" ::: "memory")
; #define PG8_WAIT_L(n) asm volatile("s_waitcnt lgkmcnt(" #n ")" ::: "memory")
; #define PG8_BAR __builtin_amdgcn_s_barrier()
; #define PG8_SCHED __builtin_amdgcn_sched_barrier(0)
; template <class Epi>
; __device__ __forceinline__ void gemm_phase(LAS unsigned char* lds, const Gemm g, const StaticOrder& S, const Epi& E) {
;     ...
;             PG8_WAIT_V(8); PG8_WAIT_L(0); PG8_BAR; PG8_MMA(0, 0, At, B0); PG8_MMA(0, 1, At, B1); PG8_BAR; PG8_SCHED;
;             PG8_LDA(At, 1, 1); PG8_STAGE(PG8_SB(1, 0), b3, voffB); PG8_STAGE(PG8_SB(1, 1), b3 + hsB, voffB); PG8_STAGE(PG8_SA(1, 0), a3, voffA);
;             PG8_WAIT_V(8); PG8_WAIT_L(0); PG8_BAR; PG8_MMA(1, 0, At, B0); PG8_MMA(1, 1, At, B1); PG8_BAR; PG8_SCHED;
	v_mfma_f32_16x16x32_bf16 v[116:119], v[184:187], v[200:203], v[116:119]
	v_mfma_f32_16x16x32_bf16 v[112:115], v[192:195], v[200:203], v[112:115]
	v_mfma_f32_16x16x32_bf16 v[100:103], v[184:187], v[208:211], v[100:103]
	v_mfma_f32_16x16x32_bf16 v[96:99], v[192:195], v[208:211], v[96:99]
	v_mfma_f32_16x16x32_bf16 v[84:87], v[184:187], v[216:219], v[84:87]
	v_mfma_f32_16x16x32_bf16 v[80:83], v[192:195], v[216:219], v[80:83]
	v_mfma_f32_16x16x32_bf16 v[68:71], v[184:187], v[224:227], v[68:71]
	v_mfma_f32_16x16x32_bf16 v[64:67], v[192:195], v[224:227], v[64:67]
	v_mfma_f32_16x16x32_bf16 v[116:119], v[188:191], v[204:207], v[116:119]
	v_mfma_f32_16x16x32_bf16 v[112:115], v[196:199], v[204:207], v[112:115]
	v_mfma_f32_16x16x32_bf16 v[100:103], v[188:191], v[212:215], v[100:103]
	v_mfma_f32_16x16x32_bf16 v[96:99], v[196:199], v[212:215], v[96:99]
	v_mfma_f32_16x16x32_bf16 v[84:87], v[188:191], v[220:223], v[84:87]
	v_mfma_f32_16x16x32_bf16 v[80:83], v[196:199], v[220:223], v[80:83]
	v_mfma_f32_16x16x32_bf16 v[68:71], v[188:191], v[228:231], v[68:71]
	v_mfma_f32_16x16x32_bf16 v[64:67], v[196:199], v[228:231], v[64:67]
	s_setprio 0
	s_barrier
	s_add_u32 s98, s12, 0x80
	s_addc_u32 s99, s13, 0
	s_add_u32 s100, s86, 0x80
	s_addc_u32 s101, s87, 0
	s_add_i32 s19, s19, s4
	s_mov_b32 m0, s19
	ds_read_b128 v[200:203], v169 offset:49152
	ds_read_b128 v[204:207], v169 offset:50176
	ds_read_b128 v[208:211], v169 offset:51200
	ds_read_b128 v[212:215], v169 offset:52224
	ds_read_b128 v[216:219], v169 offset:53248
	ds_read_b128 v[220:223], v169 offset:54272
	ds_read_b128 v[224:227], v169 offset:55296
	ds_read_b128 v[228:231], v169 offset:56320
	global_load_lds_dwordx4 v130, s[98:99]
	s_add_i32 m0, s19, 0x2000
	s_add_u32 s12, s12, 0x40080
	s_addc_u32 s13, s13, 0
	s_add_i32 s19, s22, s4
	global_load_lds_dwordx4 v134, s[98:99]
	s_mov_b32 m0, s19
	s_nop 0
	global_load_lds_dwordx4 v130, s[12:13]
	s_add_i32 m0, s19, 0x2000
	s_nop 0
	global_load_lds_dwordx4 v134, s[12:13]
	s_mov_b32 m0, s16
	s_nop 0
	global_load_lds_dwordx4 v128, s[100:101]
	s_mov_b32 m0, s33
	s_nop 0
	global_load_lds_dwordx4 v132, s[100:101]
	s_waitcnt vmcnt(8)
	s_waitcnt lgkmcnt(0)
	s_setprio 1
	s_barrier

; #define PG8_MMA(ai, bj, At, Bt) do { __builtin_amdgcn_s_setprio(1); _Pragma("unroll") for (int m = 0; m < 4; ++m) _Pragma("unroll") for (int n = 0; n < 2; ++n) _Pragma("unroll") for (int k = 0; k < 2; ++k) \
;         acc[ai][bj][m][n] = __builtin_amdgcn_mfma_f32_16x16x32_bf16(Bt[n][k], At[m][k], acc[ai][bj][m][n], 0, 0, 0); __builtin_amdgcn_s_setprio(0); } while (0)
; #define PG8_WAIT_V(n) asm volatile("s_waitcnt vmcnt(" #n ")" ::: "memory")
; #define PG8_WAIT_L(n) asm volatile("s_waitcnt lgkmcnt(" #n ")" ::: "memory")
; #define PG8_BAR __builtin_amdgcn_s_barrier()
; #define PG8_SCHED __builtin_amdgcn_sched_barrier(0)
; template <class Epi>
; __device__ __forceinline__ void gemm_phase(LAS unsigned char* lds, const Gemm g, const StaticOrder& S, const Epi& E) {
;     ...
;             PG8_WAIT_V(8); PG8_WAIT_L(0); PG8_BAR; PG8_MMA(1, 0, At, B0); PG8_MMA(1, 1, At, B1); PG8_BAR; PG8_SCHED;
	v_mfma_f32_16x16x32_bf16 v[60:63], v[152:155], v[200:203], v[60:63]
	v_mfma_f32_16x16x32_bf16 v[56:59], v[162:165], v[200:203], v[56:59]
	v_mfma_f32_16x16x32_bf16 v[44:47], v[152:155], v[208:211], v[44:47]
	v_mfma_f32_16x16x32_bf16 v[40:43], v[162:165], v[208:211], v[40:43]
	v_mfma_f32_16x16x32_bf16 v[28:31], v[152:155], v[216:219], v[28:31]
	v_mfma_f32_16x16x32_bf16 v[24:27], v[162:165], v[216:219], v[24:27]
	v_mfma_f32_16x16x32_bf16 v[12:15], v[152:155], v[224:227], v[12:15]
	v_mfma_f32_16x16x32_bf16 v[8:11], v[162:165], v[224:227], v[8:11]
	v_mfma_f32_16x16x32_bf16 v[60:63], v[156:159], v[204:207], v[60:63]
	v_mfma_f32_16x16x32_bf16 v[56:59], v[180:183], v[204:207], v[56:59]
	v_mfma_f32_16x16x32_bf16 v[44:47], v[156:159], v[212:215], v[44:47]
	v_mfma_f32_16x16x32_bf16 v[40:43], v[180:183], v[212:215], v[40:43]
	v_mfma_f32_16x16x32_bf16 v[28:31], v[156:159], v[220:223], v[28:31]
	v_mfma_f32_16x16x32_bf16 v[24:27], v[180:183], v[220:223], v[24:27]
	v_mfma_f32_16x16x32_bf16 v[12:15], v[156:159], v[228:231], v[12:15]
	v_mfma_f32_16x16x32_bf16 v[8:11], v[180:183], v[228:231], v[8:11]


; #define PG8_MMA(ai, bj, At, Bt) do { __builtin_amdgcn_s_setprio(1); _Pragma("unroll") for (int m = 0; m < 4; ++m) _Pragma("unroll") for (int n = 0; n < 2; ++n) _Pragma("unroll") for (int k = 0; k < 2; ++k) \
;         acc[ai][bj][m][n] = __builtin_amdgcn_mfma_f32_16x16x32_bf16(Bt[n][k], At[m][k], acc[ai][bj][m][n], 0, 0, 0); __builtin_amdgcn_s_setprio(0); } while (0)
; #define PG8_WAIT_V(n) asm volatile("s_waitcnt vmcnt(" #n ")" ::: "memory")
; #define PG8_WAIT_L(n) asm volatile("s_waitcnt lgkmcnt(" #n ")" ::: "memory")
; #define PG8_BAR __builtin_amdgcn_s_barrier()
; #define PG8_SCHED __builtin_amdgcn_sched_barrier(0)
; template <class Epi>
; __device__ __forceinline__ void gemm_phase(LAS unsigned char* lds, const Gemm g, const StaticOrder& S, const Epi& E) {
;     ...
;         for (int t = 0; t < nt; t += 2) {
;     ...
;             PG8_WAIT_V(8); PG8_WAIT_L(0); PG8_BAR; PG8_MMA(1, 0, At, B0); PG8_MMA(1, 1, At, B1); PG8_BAR; PG8_SCHED;
;         }
;         if (wr == 0) PG8_BAR;
	v_mfma_f32_16x16x32_bf16 v[52:55], v[184:187], v[200:203], v[52:55]
	v_mfma_f32_16x16x32_bf16 v[48:51], v[192:195], v[200:203], v[48:51]
	v_mfma_f32_16x16x32_bf16 v[36:39], v[184:187], v[208:211], v[36:39]
	v_mfma_f32_16x16x32_bf16 v[32:35], v[192:195], v[208:211], v[32:35]
	v_mfma_f32_16x16x32_bf16 v[20:23], v[184:187], v[216:219], v[20:23]
	v_mfma_f32_16x16x32_bf16 v[16:19], v[192:195], v[216:219], v[16:19]
	v_mfma_f32_16x16x32_bf16 v[4:7], v[184:187], v[224:227], v[4:7]
	v_mfma_f32_16x16x32_bf16 v[0:3], v[192:195], v[224:227], v[0:3]
	v_mfma_f32_16x16x32_bf16 v[52:55], v[188:191], v[204:207], v[52:55]
	v_mfma_f32_16x16x32_bf16 v[48:51], v[196:199], v[204:207], v[48:51]
	v_mfma_f32_16x16x32_bf16 v[36:39], v[188:191], v[212:215], v[36:39]
	v_mfma_f32_16x16x32_bf16 v[32:35], v[196:199], v[212:215], v[32:35]
	v_mfma_f32_16x16x32_bf16 v[20:23], v[188:191], v[220:223], v[20:23]
	v_mfma_f32_16x16x32_bf16 v[16:19], v[196:199], v[220:223], v[16:19]
	v_mfma_f32_16x16x32_bf16 v[4:7], v[188:191], v[228:231], v[4:7]
	v_mfma_f32_16x16x32_bf16 v[0:3], v[196:199], v[228:231], v[0:3]
	s_setprio 0
	s_barrier
	s_add_i32 s17, s17, 2
	s_add_u32 s10, s10, 0x100
	s_addc_u32 s11, s11, 0
	s_add_u32 s7, s7, 0x100
	s_addc_u32 s15, s15, 0
	s_cmp_gt_u32 s17, 13
	s_cbranch_scc0 .LBB0_414
	s_and_b64 vcc, exec, s[58:59]
	s_cbranch_vccz .LBB0_417
	s_barrier

; #define PG8_STAGE(bufoff, gbase, voff) do { _Pragma("unroll") for (int _i = 0; _i < 2; ++_i) \
;         __builtin_amdgcn_global_load_lds((const unsigned*)((const char*)(gbase) + (voff)[_i]), (LAS unsigned*)(lds + (bufoff) + ldsw + _i * 8192), 16, 0, 0); } while (0)
; #define PG8_LDA(dst, b, h) do { _Pragma("unroll") for (int m = 0; m < 4; ++m) _Pragma("unroll") for (int k = 0; k < 2; ++k) dst[m][k] = *(const LAS bf16x8*)(lds + PG8_SA(b, h) + aoff + m * 2048 + k * 1024); } while (0)
; #define PG8_LDB(dst, b, h) do { _Pragma("unroll") for (int n = 0; n < 2; ++n) _Pragma("unroll") for (int k = 0; k < 2; ++k) dst[n][k] = *(const LAS bf16x8*)(lds + PG8_SB(b, h) + boff + n * 2048 + k * 1024); } while (0)
; #define PG8_MMA(ai, bj, At, Bt) do { __builtin_amdgcn_s_setprio(1); _Pragma("unroll") for (int m = 0; m < 4; ++m) _Pragma("unroll") for (int n = 0; n < 2; ++n) _Pragma("unroll") for (int k = 0; k < 2; ++k) \
;         acc[ai][bj][m][n] = __builtin_amdgcn_mfma_f32_16x16x32_bf16(Bt[n][k], At[m][k], acc[ai][bj][m][n], 0, 0, 0); __builtin_amdgcn_s_setprio(0); } while (0)
; #define PG8_WAIT_V(n) asm volatile("s_waitcnt vmcnt(" #n ")" ::: "memory")
; #define PG8_WAIT_L(n) asm volatile("s_waitcnt lgkmcnt(" #n ")" ::: "memory")
; #define PG8_BAR __builtin_amdgcn_s_barrier()
; #define PG8_SCHED __builtin_amdgcn_sched_barrier(0)
; template <class Epi>
; __device__ __forceinline__ void gemm_phase(LAS unsigned char* lds, const Gemm g, const StaticOrder& S, const Epi& E) {
;     ...
;             const char* a2 = last ? nA : cA + ((Epi::HAS_MID && t + 2 >= nt1) ? dA2 : 0) + (size_t)(t + 2) * kstep; const char* b2 = last ? nB : cB + ((Epi::HAS_MID && t + 2 >= nt1) ? dB2 : 0) + (size_t)(t + 2) * kstep;
;             const char* a3 = a2 + kstep; const char* b3 = b2 + kstep;
;             PG8_LDB(B0, 0, 0); PG8_LDB(B1, 0, 1); PG8_SCHED; PG8_LDA(At, 0, 0); PG8_STAGE(PG8_SA(1, 1), a1 + hsA, voffA);
;             PG8_WAIT_V(8); PG8_WAIT_L(0); PG8_BAR; PG8_MMA(0, 0, At, B0); PG8_MMA(0, 1, At, B1); PG8_BAR; PG8_SCHED;
.LBB0_720:
	ds_read_b128 v[128:131], v182
	ds_read_b128 v[132:135], v182 offset:1024
	ds_read_b128 v[136:139], v182 offset:2048
	ds_read_b128 v[140:143], v182 offset:3072
	ds_read_b128 v[166:169], v183
	ds_read_b128 v[188:191], v183 offset:1024
	ds_read_b128 v[192:195], v183 offset:2048
	ds_read_b128 v[196:199], v183 offset:3072
	s_add_u32 s39, s62, 0xfffc0080
	s_addc_u32 s40, s63, -1
	s_cmp_eq_u32 s38, 12
	s_cselect_b32 s67, s6, s40
	s_cselect_b32 s66, s7, s39
	s_cselect_b32 s65, s15, s37
	s_cselect_b32 s64, s35, s36
	s_add_i32 m0, s4, 0xc000
	ds_read_b128 v[200:203], v184
	ds_read_b128 v[204:207], v184 offset:1024
	ds_read_b128 v[208:211], v184 offset:2048
	ds_read_b128 v[212:215], v184 offset:3072
	ds_read_b128 v[216:219], v184 offset:4096
	ds_read_b128 v[220:223], v184 offset:5120
	ds_read_b128 v[224:227], v184 offset:6144
	ds_read_b128 v[228:231], v184 offset:7168
	global_load_lds_dwordx4 v156, s[62:63]
	s_add_i32 m0, s4, 0xe000
	s_nop 0
	global_load_lds_dwordx4 v158, s[62:63]
	s_waitcnt vmcnt(8)
	s_waitcnt lgkmcnt(0)
	s_setprio 1
	s_barrier

; #define PG8_MMA(ai, bj, At, Bt) do { __builtin_amdgcn_s_setprio(1); _Pragma("unroll") for (int m = 0; m < 4; ++m) _Pragma("unroll") for (int n = 0; n < 2; ++n) _Pragma("unroll") for (int k = 0; k < 2; ++k) \
;         acc[ai][bj][m][n] = __builtin_amdgcn_mfma_f32_16x16x32_bf16(Bt[n][k], At[m][k], acc[ai][bj][m][n], 0, 0, 0); __builtin_amdgcn_s_setprio(0); } while (0)
; #define PG8_WAIT_V(n) asm volatile("s_waitcnt vmcnt(" #n ")" ::: "memory")
; #define PG8_WAIT_L(n) asm volatile("s_waitcnt lgkmcnt(" #n ")" ::: "memory")
; #define PG8_BAR __builtin_amdgcn_s_barrier()
; #define PG8_SCHED __builtin_amdgcn_sched_barrier(0)
; template <class Epi>
; __device__ __forceinline__ void gemm_phase(LAS unsigned char* lds, const Gemm g, const StaticOrder& S, const Epi& E) {
;     ...
;             PG8_WAIT_V(8); PG8_WAIT_L(0); PG8_BAR; PG8_MMA(0, 0, At, B0); PG8_MMA(0, 1, At, B1); PG8_BAR; PG8_SCHED;
	v_mfma_f32_16x16x32_bf16 v[124:127], v[128:131], v[200:203], v[124:127]
	v_mfma_f32_16x16x32_bf16 v[120:123], v[136:139], v[200:203], v[120:123]
	v_mfma_f32_16x16x32_bf16 v[108:111], v[128:131], v[208:211], v[108:111]
	v_mfma_f32_16x16x32_bf16 v[104:107], v[136:139], v[208:211], v[104:107]
	v_mfma_f32_16x16x32_bf16 v[92:95], v[128:131], v[216:219], v[92:95]
	v_mfma_f32_16x16x32_bf16 v[88:91], v[136:139], v[216:219], v[88:91]
	v_mfma_f32_16x16x32_bf16 v[76:79], v[128:131], v[224:227], v[76:79]
	v_mfma_f32_16x16x32_bf16 v[72:75], v[136:139], v[224:227], v[72:75]
	v_mfma_f32_16x16x32_bf16 v[124:127], v[132:135], v[204:207], v[124:127]
	v_mfma_f32_16x16x32_bf16 v[120:123], v[140:143], v[204:207], v[120:123]
	v_mfma_f32_16x16x32_bf16 v[108:111], v[132:135], v[212:215], v[108:111]
	v_mfma_f32_16x16x32_bf16 v[104:107], v[140:143], v[212:215], v[104:107]
	v_mfma_f32_16x16x32_bf16 v[92:95], v[132:135], v[220:223], v[92:95]
	v_mfma_f32_16x16x32_bf16 v[88:91], v[140:143], v[220:223], v[88:91]
	v_mfma_f32_16x16x32_bf16 v[76:79], v[132:135], v[228:231], v[76:79]
	v_mfma_f32_16x16x32_bf16 v[72:75], v[140:143], v[228:231], v[72:75]


; #define PG8_STAGE(bufoff, gbase, voff) do { _Pragma("unroll") for (int _i = 0; _i < 2; ++_i) \
;         __builtin_amdgcn_global_load_lds((const unsigned*)((const char*)(gbase) + (voff)[_i]), (LAS unsigned*)(lds + (bufoff) + ldsw + _i * 8192), 16, 0, 0); } while (0)
; #define PG8_LDA(dst, b, h) do { _Pragma("unroll") for (int m = 0; m < 4; ++m) _Pragma("unroll") for (int k = 0; k < 2; ++k) dst[m][k] = *(const LAS bf16x8*)(lds + PG8_SA(b, h) + aoff + m * 2048 + k * 1024); } while (0)
; #define PG8_MMA(ai, bj, At, Bt) do { __builtin_amdgcn_s_setprio(1); _Pragma("unroll") for (int m = 0; m < 4; ++m) _Pragma("unroll") for (int n = 0; n < 2; ++n) _Pragma("unroll") for (int k = 0; k < 2; ++k) \
;         acc[ai][bj][m][n] = __builtin_amdgcn_mfma_f32_16x16x32_bf16(Bt[n][k], At[m][k], acc[ai][bj][m][n], 0, 0, 0); __builtin_amdgcn_s_setprio(0); } while (0)
; #define PG8_WAIT_V(n) asm volatile("s_waitcnt vmcnt(" #n ")" ::: "memory")
; #define PG8_WAIT_L(n) asm volatile("s_waitcnt lgkmcnt(" #n ")" ::: "memory")
; #define PG8_BAR __builtin_amdgcn_s_barrier()
; #define PG8_SCHED __builtin_amdgcn_sched_barrier(0)
; template <class Epi>
; __device__ __forceinline__ void gemm_phase(LAS unsigned char* lds, const Gemm g, const StaticOrder& S, const Epi& E) {
;     ...
;             PG8_WAIT_V(8); PG8_WAIT_L(0); PG8_BAR; PG8_MMA(0, 0, At, B0); PG8_MMA(0, 1, At, B1); PG8_BAR; PG8_SCHED;
;             PG8_LDA(At, 0, 1); PG8_STAGE(PG8_SB(0, 0), b2, voffB); PG8_STAGE(PG8_SB(0, 1), b2 + hsB, voffB); PG8_STAGE(PG8_SA(0, 0), a2, voffA);
;             PG8_WAIT_V(8); PG8_WAIT_L(0); PG8_BAR; PG8_MMA(1, 0, At, B0); PG8_MMA(1, 1, At, B1); PG8_BAR; PG8_SCHED;
	v_mfma_f32_16x16x32_bf16 v[116:119], v[166:169], v[200:203], v[116:119]
	v_mfma_f32_16x16x32_bf16 v[112:115], v[192:195], v[200:203], v[112:115]
	v_mfma_f32_16x16x32_bf16 v[100:103], v[166:169], v[208:211], v[100:103]
	v_mfma_f32_16x16x32_bf16 v[96:99], v[192:195], v[208:211], v[96:99]
	v_mfma_f32_16x16x32_bf16 v[84:87], v[166:169], v[216:219], v[84:87]
	v_mfma_f32_16x16x32_bf16 v[80:83], v[192:195], v[216:219], v[80:83]
	v_mfma_f32_16x16x32_bf16 v[68:71], v[166:169], v[224:227], v[68:71]
	v_mfma_f32_16x16x32_bf16 v[64:67], v[192:195], v[224:227], v[64:67]
	v_mfma_f32_16x16x32_bf16 v[116:119], v[188:191], v[204:207], v[116:119]
	v_mfma_f32_16x16x32_bf16 v[112:115], v[196:199], v[204:207], v[112:115]
	v_mfma_f32_16x16x32_bf16 v[100:103], v[188:191], v[212:215], v[100:103]
	v_mfma_f32_16x16x32_bf16 v[96:99], v[196:199], v[212:215], v[96:99]
	v_mfma_f32_16x16x32_bf16 v[84:87], v[188:191], v[220:223], v[84:87]
	v_mfma_f32_16x16x32_bf16 v[80:83], v[196:199], v[220:223], v[80:83]
	v_mfma_f32_16x16x32_bf16 v[68:71], v[188:191], v[228:231], v[68:71]
	v_mfma_f32_16x16x32_bf16 v[64:67], v[196:199], v[228:231], v[64:67]
	s_setprio 0
	s_barrier
	s_add_i32 s39, s27, s3
	s_mov_b32 m0, s39
	ds_read_b128 v[200:203], v184 offset:16384
	ds_read_b128 v[204:207], v184 offset:17408
	ds_read_b128 v[208:211], v184 offset:18432
	ds_read_b128 v[212:215], v184 offset:19456
	ds_read_b128 v[216:219], v184 offset:20480
	ds_read_b128 v[220:223], v184 offset:21504
	ds_read_b128 v[224:227], v184 offset:22528
	ds_read_b128 v[228:231], v184 offset:23552
	global_load_lds_dwordx4 v146, s[64:65]
	s_add_i32 m0, s39, 0x2000
	s_add_u32 s40, s64, 0x40000
	s_addc_u32 s41, s65, 0
	s_add_i32 s39, s28, s3
	global_load_lds_dwordx4 v150, s[64:65]
	s_mov_b32 m0, s39
	s_nop 0
	global_load_lds_dwordx4 v146, s[40:41]
	s_add_i32 m0, s39, 0x2000
	s_nop 0
	global_load_lds_dwordx4 v150, s[40:41]
	s_mov_b32 m0, s4
	s_nop 0
	global_load_lds_dwordx4 v144, s[66:67]
	s_mov_b32 m0, s5
	s_nop 0
	global_load_lds_dwordx4 v148, s[66:67]
	s_waitcnt vmcnt(8)
	s_waitcnt lgkmcnt(0)
	s_setprio 1
	s_barrier

; #define PG8_MMA(ai, bj, At, Bt) do { __builtin_amdgcn_s_setprio(1); _Pragma("unroll") for (int m = 0; m < 4; ++m) _Pragma("unroll") for (int n = 0; n < 2; ++n) _Pragma("unroll") for (int k = 0; k < 2; ++k) \
;         acc[ai][bj][m][n] = __builtin_amdgcn_mfma_f32_16x16x32_bf16(Bt[n][k], At[m][k], acc[ai][bj][m][n], 0, 0, 0); __builtin_amdgcn_s_setprio(0); } while (0)
; #define PG8_WAIT_V(n) asm volatile("s_waitcnt vmcnt(" #n ")" ::: "memory")
; #define PG8_WAIT_L(n) asm volatile("s_waitcnt lgkmcnt(" #n ")" ::: "memory")
; #define PG8_BAR __builtin_amdgcn_s_barrier()
; #define PG8_SCHED __builtin_amdgcn_sched_barrier(0)
; template <class Epi>
; __device__ __forceinline__ void gemm_phase(LAS unsigned char* lds, const Gemm g, const StaticOrder& S, const Epi& E) {
;     ...
;             PG8_WAIT_V(8); PG8_WAIT_L(0); PG8_BAR; PG8_MMA(1, 0, At, B0); PG8_MMA(1, 1, At, B1); PG8_BAR; PG8_SCHED;
	v_mfma_f32_16x16x32_bf16 v[60:63], v[128:131], v[200:203], v[60:63]
	v_mfma_f32_16x16x32_bf16 v[56:59], v[136:139], v[200:203], v[56:59]
	v_mfma_f32_16x16x32_bf16 v[44:47], v[128:131], v[208:211], v[44:47]
	v_mfma_f32_16x16x32_bf16 v[40:43], v[136:139], v[208:211], v[40:43]
	v_mfma_f32_16x16x32_bf16 v[28:31], v[128:131], v[216:219], v[28:31]
	v_mfma_f32_16x16x32_bf16 v[24:27], v[136:139], v[216:219], v[24:27]
	v_mfma_f32_16x16x32_bf16 v[12:15], v[128:131], v[224:227], v[12:15]
	v_mfma_f32_16x16x32_bf16 v[8:11], v[136:139], v[224:227], v[8:11]
	v_mfma_f32_16x16x32_bf16 v[60:63], v[132:135], v[204:207], v[60:63]
	v_mfma_f32_16x16x32_bf16 v[56:59], v[140:143], v[204:207], v[56:59]
	v_mfma_f32_16x16x32_bf16 v[44:47], v[132:135], v[212:215], v[44:47]
	v_mfma_f32_16x16x32_bf16 v[40:43], v[140:143], v[212:215], v[40:43]
	v_mfma_f32_16x16x32_bf16 v[28:31], v[132:135], v[220:223], v[28:31]
	v_mfma_f32_16x16x32_bf16 v[24:27], v[140:143], v[220:223], v[24:27]
	v_mfma_f32_16x16x32_bf16 v[12:15], v[132:135], v[228:231], v[12:15]
	v_mfma_f32_16x16x32_bf16 v[8:11], v[140:143], v[228:231], v[8:11]


; #define PG8_STAGE(bufoff, gbase, voff) do { _Pragma("unroll") for (int _i = 0; _i < 2; ++_i) \
;         __builtin_amdgcn_global_load_lds((const unsigned*)((const char*)(gbase) + (voff)[_i]), (LAS unsigned*)(lds + (bufoff) + ldsw + _i * 8192), 16, 0, 0); } while (0)
; #define PG8_LDA(dst, b, h) do { _Pragma("unroll") for (int m = 0; m < 4; ++m) _Pragma("unroll") for (int k = 0; k < 2; ++k) dst[m][k] = *(const LAS bf16x8*)(lds + PG8_SA(b, h) + aoff + m * 2048 + k * 1024); } while (0)
; #define PG8_LDB(dst, b, h) do { _Pragma("unroll") for (int n = 0; n < 2; ++n) _Pragma("unroll") for (int k = 0; k < 2; ++k) dst[n][k] = *(const LAS bf16x8*)(lds + PG8_SB(b, h) + boff + n * 2048 + k * 1024); } while (0)
; #define PG8_MMA(ai, bj, At, Bt) do { __builtin_amdgcn_s_setprio(1); _Pragma("unroll") for (int m = 0; m < 4; ++m) _Pragma("unroll") for (int n = 0; n < 2; ++n) _Pragma("unroll") for (int k = 0; k < 2; ++k) \
;         acc[ai][bj][m][n] = __builtin_amdgcn_mfma_f32_16x16x32_bf16(Bt[n][k], At[m][k], acc[ai][bj][m][n], 0, 0, 0); __builtin_amdgcn_s_setprio(0); } while (0)
; #define PG8_WAIT_V(n) asm volatile("s_waitcnt vmcnt(" #n ")" ::: "memory")
; #define PG8_WAIT_L(n) asm volatile("s_waitcnt lgkmcnt(" #n ")" ::: "memory")
; #define PG8_BAR __builtin_amdgcn_s_barrier()
; #define PG8_SCHED __builtin_amdgcn_sched_barrier(0)
; template <class Epi>
; __device__ __forceinline__ void gemm_phase(LAS unsigned char* lds, const Gemm g, const StaticOrder& S, const Epi& E) {
;     ...
;             PG8_WAIT_V(8); PG8_WAIT_L(0); PG8_BAR; PG8_MMA(1, 0, At, B0); PG8_MMA(1, 1, At, B1); PG8_BAR; PG8_SCHED;
;             PG8_LDB(B0, 1, 0); PG8_LDB(B1, 1, 1); PG8_SCHED; PG8_LDA(At, 1, 0); PG8_STAGE(PG8_SA(0, 1), a2 + hsA, voffA);
;             PG8_WAIT_V(8); PG8_WAIT_L(0); PG8_BAR; PG8_MMA(0, 0, At, B0); PG8_MMA(0, 1, At, B1); PG8_BAR; PG8_SCHED;
	v_mfma_f32_16x16x32_bf16 v[52:55], v[166:169], v[200:203], v[52:55]
	v_mfma_f32_16x16x32_bf16 v[48:51], v[192:195], v[200:203], v[48:51]
	v_mfma_f32_16x16x32_bf16 v[36:39], v[166:169], v[208:211], v[36:39]
	v_mfma_f32_16x16x32_bf16 v[32:35], v[192:195], v[208:211], v[32:35]
	v_mfma_f32_16x16x32_bf16 v[20:23], v[166:169], v[216:219], v[20:23]
	v_mfma_f32_16x16x32_bf16 v[16:19], v[192:195], v[216:219], v[16:19]
	v_mfma_f32_16x16x32_bf16 v[4:7], v[166:169], v[224:227], v[4:7]
	v_mfma_f32_16x16x32_bf16 v[0:3], v[192:195], v[224:227], v[0:3]
	v_mfma_f32_16x16x32_bf16 v[52:55], v[188:191], v[204:207], v[52:55]
	v_mfma_f32_16x16x32_bf16 v[48:51], v[196:199], v[204:207], v[48:51]
	v_mfma_f32_16x16x32_bf16 v[36:39], v[188:191], v[212:215], v[36:39]
	v_mfma_f32_16x16x32_bf16 v[32:35], v[196:199], v[212:215], v[32:35]
	v_mfma_f32_16x16x32_bf16 v[20:23], v[188:191], v[220:223], v[20:23]
	v_mfma_f32_16x16x32_bf16 v[16:19], v[196:199], v[220:223], v[16:19]
	v_mfma_f32_16x16x32_bf16 v[4:7], v[188:191], v[228:231], v[4:7]
	v_mfma_f32_16x16x32_bf16 v[0:3], v[196:199], v[228:231], v[0:3]
	s_setprio 0
	s_barrier
	s_add_i32 s39, 0, 0x18000
	s_add_i32 s42, 0, 0x1c000
	v_add_u32_e32 v140, s39, v173
	v_add_u32_e32 v152, s42, v173
	ds_read_b128 v[128:131], v140
	ds_read_b128 v[132:135], v140 offset:1024
	ds_read_b128 v[136:139], v140 offset:2048
	ds_read_b128 v[140:143], v140 offset:3072
	ds_read_b128 v[166:169], v152
	ds_read_b128 v[188:191], v152 offset:1024
	ds_read_b128 v[192:195], v152 offset:2048
	ds_read_b128 v[196:199], v152 offset:3072
	s_add_u32 s40, s66, 0x40000
	s_addc_u32 s41, s67, 0
	s_mov_b32 m0, s16
	ds_read_b128 v[200:203], v184 offset:32768
	ds_read_b128 v[204:207], v184 offset:33792
	ds_read_b128 v[208:211], v184 offset:34816
	ds_read_b128 v[212:215], v184 offset:35840
	ds_read_b128 v[216:219], v184 offset:36864
	ds_read_b128 v[220:223], v184 offset:37888
	ds_read_b128 v[224:227], v184 offset:38912
	ds_read_b128 v[228:231], v184 offset:39936
	global_load_lds_dwordx4 v144, s[40:41]
	s_mov_b32 m0, s17
	s_nop 0
	global_load_lds_dwordx4 v148, s[40:41]
	s_waitcnt vmcnt(8)
	s_waitcnt lgkmcnt(0)
	s_setprio 1
	s_barrier

; #define PG8_MMA(ai, bj, At, Bt) do { __builtin_amdgcn_s_setprio(1); _Pragma("unroll") for (int m = 0; m < 4; ++m) _Pragma("unroll") for (int n = 0; n < 2; ++n) _Pragma("unroll") for (int k = 0; k < 2; ++k) \
;         acc[ai][bj][m][n] = __builtin_amdgcn_mfma_f32_16x16x32_bf16(Bt[n][k], At[m][k], acc[ai][bj][m][n], 0, 0, 0); __builtin_amdgcn_s_setprio(0); } while (0)
; #define PG8_WAIT_V(n) asm volatile("s_waitcnt vmcnt(" #n ")" ::: "memory")
; #define PG8_WAIT_L(n) asm volatile("s_waitcnt lgkmcnt(" #n ")" ::: "memory")
; #define PG8_BAR __builtin_amdgcn_s_barrier()
; #define PG8_SCHED __builtin_amdgcn_sched_barrier(0)
; template <class Epi>
; __device__ __forceinline__ void gemm_phase(LAS unsigned char* lds, const Gemm g, const StaticOrder& S, const Epi& E) {
;     ...
;             PG8_WAIT_V(8); PG8_WAIT_L(0); PG8_BAR; PG8_MMA(0, 0, At, B0); PG8_MMA(0, 1, At, B1); PG8_BAR; PG8_SCHED;
	v_mfma_f32_16x16x32_bf16 v[124:127], v[128:131], v[200:203], v[124:127]
	v_mfma_f32_16x16x32_bf16 v[120:123], v[136:139], v[200:203], v[120:123]
	v_mfma_f32_16x16x32_bf16 v[108:111], v[128:131], v[208:211], v[108:111]
	v_mfma_f32_16x16x32_bf16 v[104:107], v[136:139], v[208:211], v[104:107]
	v_mfma_f32_16x16x32_bf16 v[92:95], v[128:131], v[216:219], v[92:95]
	v_mfma_f32_16x16x32_bf16 v[88:91], v[136:139], v[216:219], v[88:91]
	v_mfma_f32_16x16x32_bf16 v[76:79], v[128:131], v[224:227], v[76:79]
	v_mfma_f32_16x16x32_bf16 v[72:75], v[136:139], v[224:227], v[72:75]
	v_mfma_f32_16x16x32_bf16 v[124:127], v[132:135], v[204:207], v[124:127]
	v_mfma_f32_16x16x32_bf16 v[120:123], v[140:143], v[204:207], v[120:123]
	v_mfma_f32_16x16x32_bf16 v[108:111], v[132:135], v[212:215], v[108:111]
	v_mfma_f32_16x16x32_bf16 v[104:107], v[140:143], v[212:215], v[104:107]
	v_mfma_f32_16x16x32_bf16 v[92:95], v[132:135], v[220:223], v[92:95]
	v_mfma_f32_16x16x32_bf16 v[88:91], v[140:143], v[220:223], v[88:91]
	v_mfma_f32_16x16x32_bf16 v[76:79], v[132:135], v[228:231], v[76:79]
	v_mfma_f32_16x16x32_bf16 v[72:75], v[140:143], v[228:231], v[72:75]


; #define PG8_STAGE(bufoff, gbase, voff) do { _Pragma("unroll") for (int _i = 0; _i < 2; ++_i) \
;         __builtin_amdgcn_global_load_lds((const unsigned*)((const char*)(gbase) + (voff)[_i]), (LAS unsigned*)(lds + (bufoff) + ldsw + _i * 8192), 16, 0, 0); } while (0)
; #define PG8_LDA(dst, b, h) do { _Pragma("unroll") for (int m = 0; m < 4; ++m) _Pragma("unroll") for (int k = 0; k < 2; ++k) dst[m][k] = *(const LAS bf16x8*)(lds + PG8_SA(b, h) + aoff + m * 2048 + k * 1024); } while (0)
; #define PG8_MMA(ai, bj, At, Bt) do { __builtin_amdgcn_s_setprio(1); _Pragma("unroll") for (int m = 0; m < 4; ++m) _Pragma("unroll") for (int n = 0; n < 2; ++n) _Pragma("unroll") for (int k = 0; k < 2; ++k) \
;         acc[ai][bj][m][n] = __builtin_amdgcn_mfma_f32_16x16x32_bf16(Bt[n][k], At[m][k], acc[ai][bj][m][n], 0, 0, 0); __builtin_amdgcn_s_setprio(0); } while (0)
; #define PG8_WAIT_V(n) asm volatile("s_waitcnt vmcnt(" #n ")" ::: "memory")
; #define PG8_WAIT_L(n) asm volatile("s_waitcnt lgkmcnt(" #n ")" ::: "memory")
; #define PG8_BAR __builtin_amdgcn_s_barrier()
; #define PG8_SCHED __builtin_amdgcn_sched_barrier(0)
; template <class Epi>
; __device__ __forceinline__ void gemm_phase(LAS unsigned char* lds, const Gemm g, const StaticOrder& S, const Epi& E) {
;     ...
;             PG8_WAIT_V(8); PG8_WAIT_L(0); PG8_BAR; PG8_MMA(0, 0, At, B0); PG8_MMA(0, 1, At, B1); PG8_BAR; PG8_SCHED;
;             PG8_LDA(At, 1, 1); PG8_STAGE(PG8_SB(1, 0), b3, voffB); PG8_STAGE(PG8_SB(1, 1), b3 + hsB, voffB); PG8_STAGE(PG8_SA(1, 0), a3, voffA);
;             PG8_WAIT_V(8); PG8_WAIT_L(0); PG8_BAR; PG8_MMA(1, 0, At, B0); PG8_MMA(1, 1, At, B1); PG8_BAR; PG8_SCHED;
	v_mfma_f32_16x16x32_bf16 v[116:119], v[166:169], v[200:203], v[116:119]
	v_mfma_f32_16x16x32_bf16 v[112:115], v[192:195], v[200:203], v[112:115]
	v_mfma_f32_16x16x32_bf16 v[100:103], v[166:169], v[208:211], v[100:103]
	v_mfma_f32_16x16x32_bf16 v[96:99], v[192:195], v[208:211], v[96:99]
	v_mfma_f32_16x16x32_bf16 v[84:87], v[166:169], v[216:219], v[84:87]
	v_mfma_f32_16x16x32_bf16 v[80:83], v[192:195], v[216:219], v[80:83]
	v_mfma_f32_16x16x32_bf16 v[68:71], v[166:169], v[224:227], v[68:71]
	v_mfma_f32_16x16x32_bf16 v[64:67], v[192:195], v[224:227], v[64:67]
	v_mfma_f32_16x16x32_bf16 v[116:119], v[188:191], v[204:207], v[116:119]
	v_mfma_f32_16x16x32_bf16 v[112:115], v[196:199], v[204:207], v[112:115]
	v_mfma_f32_16x16x32_bf16 v[100:103], v[188:191], v[212:215], v[100:103]
	v_mfma_f32_16x16x32_bf16 v[96:99], v[196:199], v[212:215], v[96:99]
	v_mfma_f32_16x16x32_bf16 v[84:87], v[188:191], v[220:223], v[84:87]
	v_mfma_f32_16x16x32_bf16 v[80:83], v[196:199], v[220:223], v[80:83]
	v_mfma_f32_16x16x32_bf16 v[68:71], v[188:191], v[228:231], v[68:71]
	v_mfma_f32_16x16x32_bf16 v[64:67], v[196:199], v[228:231], v[64:67]
	s_setprio 0
	s_barrier
	s_add_u32 s98, s64, 0x80
	s_addc_u32 s99, s65, 0
	s_add_u32 s100, s66, 0x80
	s_addc_u32 s101, s67, 0
	s_add_i32 s39, s39, s3
	s_mov_b32 m0, s39
	ds_read_b128 v[200:203], v184 offset:49152
	ds_read_b128 v[204:207], v184 offset:50176
	ds_read_b128 v[208:211], v184 offset:51200
	ds_read_b128 v[212:215], v184 offset:52224
	ds_read_b128 v[216:219], v184 offset:53248
	ds_read_b128 v[220:223], v184 offset:54272
	ds_read_b128 v[224:227], v184 offset:55296
	ds_read_b128 v[228:231], v184 offset:56320
	global_load_lds_dwordx4 v146, s[98:99]
	s_add_i32 m0, s39, 0x2000
	s_add_u32 s40, s64, 0x40080
	s_addc_u32 s41, s65, 0
	s_add_i32 s39, s42, s3
	global_load_lds_dwordx4 v150, s[98:99]
	s_mov_b32 m0, s39
	s_nop 0
	global_load_lds_dwordx4 v146, s[40:41]
	s_add_i32 m0, s39, 0x2000
	s_nop 0
	global_load_lds_dwordx4 v150, s[40:41]
	s_mov_b32 m0, s22
	s_nop 0
	global_load_lds_dwordx4 v144, s[100:101]
	s_mov_b32 m0, s23
	s_nop 0
	global_load_lds_dwordx4 v148, s[100:101]
	s_waitcnt vmcnt(8)
	s_waitcnt lgkmcnt(0)
	s_setprio 1
	s_barrier

; #define PG8_MMA(ai, bj, At, Bt) do { __builtin_amdgcn_s_setprio(1); _Pragma("unroll") for (int m = 0; m < 4; ++m) _Pragma("unroll") for (int n = 0; n < 2; ++n) _Pragma("unroll") for (int k = 0; k < 2; ++k) \
;         acc[ai][bj][m][n] = __builtin_amdgcn_mfma_f32_16x16x32_bf16(Bt[n][k], At[m][k], acc[ai][bj][m][n], 0, 0, 0); __builtin_amdgcn_s_setprio(0); } while (0)
; #define PG8_WAIT_V(n) asm volatile("s_waitcnt vmcnt(" #n ")" ::: "memory")
; #define PG8_WAIT_L(n) asm volatile("s_waitcnt lgkmcnt(" #n ")" ::: "memory")
; #define PG8_BAR __builtin_amdgcn_s_barrier()
; #define PG8_SCHED __builtin_amdgcn_sched_barrier(0)
; template <class Epi>
; __device__ __forceinline__ void gemm_phase(LAS unsigned char* lds, const Gemm g, const StaticOrder& S, const Epi& E) {
;     ...
;             PG8_WAIT_V(8); PG8_WAIT_L(0); PG8_BAR; PG8_MMA(1, 0, At, B0); PG8_MMA(1, 1, At, B1); PG8_BAR; PG8_SCHED;
	v_mfma_f32_16x16x32_bf16 v[60:63], v[128:131], v[200:203], v[60:63]
	v_mfma_f32_16x16x32_bf16 v[56:59], v[136:139], v[200:203], v[56:59]
	v_mfma_f32_16x16x32_bf16 v[44:47], v[128:131], v[208:211], v[44:47]
	v_mfma_f32_16x16x32_bf16 v[40:43], v[136:139], v[208:211], v[40:43]
	v_mfma_f32_16x16x32_bf16 v[28:31], v[128:131], v[216:219], v[28:31]
	v_mfma_f32_16x16x32_bf16 v[24:27], v[136:139], v[216:219], v[24:27]
	v_mfma_f32_16x16x32_bf16 v[12:15], v[128:131], v[224:227], v[12:15]
	v_mfma_f32_16x16x32_bf16 v[8:11], v[136:139], v[224:227], v[8:11]
	v_mfma_f32_16x16x32_bf16 v[60:63], v[132:135], v[204:207], v[60:63]
	v_mfma_f32_16x16x32_bf16 v[56:59], v[140:143], v[204:207], v[56:59]
	v_mfma_f32_16x16x32_bf16 v[44:47], v[132:135], v[212:215], v[44:47]
	v_mfma_f32_16x16x32_bf16 v[40:43], v[140:143], v[212:215], v[40:43]
	v_mfma_f32_16x16x32_bf16 v[28:31], v[132:135], v[220:223], v[28:31]
	v_mfma_f32_16x16x32_bf16 v[24:27], v[140:143], v[220:223], v[24:27]
	v_mfma_f32_16x16x32_bf16 v[12:15], v[132:135], v[228:231], v[12:15]
	v_mfma_f32_16x16x32_bf16 v[8:11], v[140:143], v[228:231], v[8:11]


; #define PG8_MMA(ai, bj, At, Bt) do { __builtin_amdgcn_s_setprio(1); _Pragma("unroll") for (int m = 0; m < 4; ++m) _Pragma("unroll") for (int n = 0; n < 2; ++n) _Pragma("unroll") for (int k = 0; k < 2; ++k) \
;         acc[ai][bj][m][n] = __builtin_amdgcn_mfma_f32_16x16x32_bf16(Bt[n][k], At[m][k], acc[ai][bj][m][n], 0, 0, 0); __builtin_amdgcn_s_setprio(0); } while (0)
; #define PG8_WAIT_V(n) asm volatile("s_waitcnt vmcnt(" #n ")" ::: "memory")
; #define PG8_WAIT_L(n) asm volatile("s_waitcnt lgkmcnt(" #n ")" ::: "memory")
; #define PG8_BAR __builtin_amdgcn_s_barrier()
; #define PG8_SCHED __builtin_amdgcn_sched_barrier(0)
; template <class Epi>
; __device__ __forceinline__ void gemm_phase(LAS unsigned char* lds, const Gemm g, const StaticOrder& S, const Epi& E) {
;     ...
;         for (int t = 0; t < nt; t += 2) {
;     ...
;             PG8_WAIT_V(8); PG8_WAIT_L(0); PG8_BAR; PG8_MMA(1, 0, At, B0); PG8_MMA(1, 1, At, B1); PG8_BAR; PG8_SCHED;
;         }
;         if (wr == 0) PG8_BAR;
	v_mfma_f32_16x16x32_bf16 v[52:55], v[166:169], v[200:203], v[52:55]
	v_mfma_f32_16x16x32_bf16 v[48:51], v[192:195], v[200:203], v[48:51]
	v_mfma_f32_16x16x32_bf16 v[36:39], v[166:169], v[208:211], v[36:39]
	v_mfma_f32_16x16x32_bf16 v[32:35], v[192:195], v[208:211], v[32:35]
	v_mfma_f32_16x16x32_bf16 v[20:23], v[166:169], v[216:219], v[20:23]
	v_mfma_f32_16x16x32_bf16 v[16:19], v[192:195], v[216:219], v[16:19]
	v_mfma_f32_16x16x32_bf16 v[4:7], v[166:169], v[224:227], v[4:7]
	v_mfma_f32_16x16x32_bf16 v[0:3], v[192:195], v[224:227], v[0:3]
	v_mfma_f32_16x16x32_bf16 v[52:55], v[188:191], v[204:207], v[52:55]
	v_mfma_f32_16x16x32_bf16 v[48:51], v[196:199], v[204:207], v[48:51]
	v_mfma_f32_16x16x32_bf16 v[36:39], v[188:191], v[212:215], v[36:39]
	v_mfma_f32_16x16x32_bf16 v[32:35], v[196:199], v[212:215], v[32:35]
	v_mfma_f32_16x16x32_bf16 v[20:23], v[188:191], v[220:223], v[20:23]
	v_mfma_f32_16x16x32_bf16 v[16:19], v[196:199], v[220:223], v[16:19]
	v_mfma_f32_16x16x32_bf16 v[4:7], v[188:191], v[228:231], v[4:7]
	v_mfma_f32_16x16x32_bf16 v[0:3], v[196:199], v[228:231], v[0:3]
	s_setprio 0
	s_barrier
	s_add_i32 s38, s38, 2
	s_add_u32 s62, s62, 0x100
	s_addc_u32 s63, s63, 0
	s_add_u32 s36, s36, 0x100
	s_addc_u32 s37, s37, 0
	s_cmp_gt_u32 s38, 13
	s_cbranch_scc0 .LBB0_720
	s_and_b64 vcc, exec, s[12:13]
	s_cbranch_vccz .LBB0_723
	s_barrier

; #define PG8_STAGE(bufoff, gbase, voff) do { _Pragma("unroll") for (int _i = 0; _i < 2; ++_i) \
;         __builtin_amdgcn_global_load_lds((const unsigned*)((const char*)(gbase) + (voff)[_i]), (LAS unsigned*)(lds + (bufoff) + ldsw + _i * 8192), 16, 0, 0); } while (0)
; #define PG8_LDA(dst, b, h) do { _Pragma("unroll") for (int m = 0; m < 4; ++m) _Pragma("unroll") for (int k = 0; k < 2; ++k) dst[m][k] = *(const LAS bf16x8*)(lds + PG8_SA(b, h) + aoff + m * 2048 + k * 1024); } while (0)
; #define PG8_LDB(dst, b, h) do { _Pragma("unroll") for (int n = 0; n < 2; ++n) _Pragma("unroll") for (int k = 0; k < 2; ++k) dst[n][k] = *(const LAS bf16x8*)(lds + PG8_SB(b, h) + boff + n * 2048 + k * 1024); } while (0)
; #define PG8_MMA(ai, bj, At, Bt) do { __builtin_amdgcn_s_setprio(1); _Pragma("unroll") for (int m = 0; m < 4; ++m) _Pragma("unroll") for (int n = 0; n < 2; ++n) _Pragma("unroll") for (int k = 0; k < 2; ++k) \
;         acc[ai][bj][m][n] = __builtin_amdgcn_mfma_f32_16x16x32_bf16(Bt[n][k], At[m][k], acc[ai][bj][m][n], 0, 0, 0); __builtin_amdgcn_s_setprio(0); } while (0)
; #define PG8_WAIT_V(n) asm volatile("s_waitcnt vmcnt(" #n ")" ::: "memory")
; #define PG8_WAIT_L(n) asm volatile("s_waitcnt lgkmcnt(" #n ")" ::: "memory")
; #define PG8_BAR __builtin_amdgcn_s_barrier()
; #define PG8_SCHED __builtin_amdgcn_sched_barrier(0)
; template <class Epi>
; __device__ __forceinline__ void gemm_phase(LAS unsigned char* lds, const Gemm g, const StaticOrder& S, const Epi& E) {
;     ...
;             const char* a1 = cA + ((Epi::HAS_MID && t >= nt1) ? dA2 : 0) + (size_t)(t + 1) * kstep;
;             const char* a2 = last ? nA : cA + ((Epi::HAS_MID && t + 2 >= nt1) ? dA2 : 0) + (size_t)(t + 2) * kstep; const char* b2 = last ? nB : cB + ((Epi::HAS_MID && t + 2 >= nt1) ? dB2 : 0) + (size_t)(t + 2) * kstep;
;             const char* a3 = a2 + kstep; const char* b3 = b2 + kstep;
;             PG8_LDB(B0, 0, 0); PG8_LDB(B1, 0, 1); PG8_SCHED; PG8_LDA(At, 0, 0); PG8_STAGE(PG8_SA(1, 1), a1 + hsA, voffA);
;             PG8_WAIT_V(8); PG8_WAIT_L(0); PG8_BAR; PG8_MMA(0, 0, At, B0); PG8_MMA(0, 1, At, B1); PG8_BAR; PG8_SCHED;
.LBB0_1083:
	s_add_i32 s33, s33, 2
	s_add_u32 s0, s52, s54
	s_addc_u32 s1, s53, s55
	s_add_u32 s0, s0, 0x100
	v_add_u32_e32 v153, s74, v171
	s_addc_u32 s1, s1, 0
	ds_read_b128 v[128:131], v153
	ds_read_b128 v[132:135], v153 offset:1024
	ds_read_b128 v[164:167], v153 offset:2048
	ds_read_b128 v[184:187], v153 offset:3072
	v_add_u32_e32 v153, s75, v171
	s_cmp_gt_u32 s33, 13
	ds_read_b128 v[188:191], v153
	ds_read_b128 v[192:195], v153 offset:1024
	ds_read_b128 v[196:199], v153 offset:2048
	ds_read_b128 v[200:203], v153 offset:3072
	s_cselect_b32 s17, 0x1ff800, 0
	s_add_u32 s17, s17, s54
	s_addc_u32 s24, 0, s55
	s_add_u32 s17, s22, s17
	s_addc_u32 s24, s23, s24
	s_cmpk_eq_i32 s54, 0xf00
	s_cselect_b32 s59, s6, s1
	s_cselect_b32 s58, s7, s0
	s_cselect_b32 s57, s16, s24
	s_cselect_b32 s56, s18, s17
	v_lshl_add_u64 v[168:169], v[158:159], 0, s[54:55]
	s_add_i32 m0, s61, 0xc000
	ds_read_b128 v[204:207], v173
	ds_read_b128 v[208:211], v173 offset:1024
	ds_read_b128 v[212:215], v173 offset:2048
	ds_read_b128 v[216:219], v173 offset:3072
	ds_read_b128 v[220:223], v173 offset:4096
	ds_read_b128 v[224:227], v173 offset:5120
	ds_read_b128 v[228:231], v173 offset:6144
	ds_read_b128 v[232:235], v173 offset:7168
	global_load_lds_dwordx4 v[168:169], off
	v_lshl_add_u64 v[168:169], v[162:163], 0, s[54:55]
	s_add_i32 m0, s61, 0xe000
	s_nop 0
	global_load_lds_dwordx4 v[168:169], off
	s_waitcnt vmcnt(8)
	s_waitcnt lgkmcnt(0)
	s_setprio 1
	s_barrier

; #define PG8_MMA(ai, bj, At, Bt) do { __builtin_amdgcn_s_setprio(1); _Pragma("unroll") for (int m = 0; m < 4; ++m) _Pragma("unroll") for (int n = 0; n < 2; ++n) _Pragma("unroll") for (int k = 0; k < 2; ++k) \
;         acc[ai][bj][m][n] = __builtin_amdgcn_mfma_f32_16x16x32_bf16(Bt[n][k], At[m][k], acc[ai][bj][m][n], 0, 0, 0); __builtin_amdgcn_s_setprio(0); } while (0)
; #define PG8_WAIT_V(n) asm volatile("s_waitcnt vmcnt(" #n ")" ::: "memory")
; #define PG8_WAIT_L(n) asm volatile("s_waitcnt lgkmcnt(" #n ")" ::: "memory")
; #define PG8_BAR __builtin_amdgcn_s_barrier()
; #define PG8_SCHED __builtin_amdgcn_sched_barrier(0)
; template <class Epi>
; __device__ __forceinline__ void gemm_phase(LAS unsigned char* lds, const Gemm g, const StaticOrder& S, const Epi& E) {
;     ...
;             PG8_WAIT_V(8); PG8_WAIT_L(0); PG8_BAR; PG8_MMA(0, 0, At, B0); PG8_MMA(0, 1, At, B1); PG8_BAR; PG8_SCHED;
	v_mfma_f32_16x16x32_bf16 v[124:127], v[128:131], v[204:207], v[124:127]
	v_mfma_f32_16x16x32_bf16 v[120:123], v[164:167], v[204:207], v[120:123]
	v_mfma_f32_16x16x32_bf16 v[108:111], v[128:131], v[212:215], v[108:111]
	v_mfma_f32_16x16x32_bf16 v[104:107], v[164:167], v[212:215], v[104:107]
	v_mfma_f32_16x16x32_bf16 v[92:95], v[128:131], v[220:223], v[92:95]
	v_mfma_f32_16x16x32_bf16 v[88:91], v[164:167], v[220:223], v[88:91]
	v_mfma_f32_16x16x32_bf16 v[76:79], v[128:131], v[228:231], v[76:79]
	v_mfma_f32_16x16x32_bf16 v[72:75], v[164:167], v[228:231], v[72:75]
	v_mfma_f32_16x16x32_bf16 v[124:127], v[132:135], v[208:211], v[124:127]
	v_mfma_f32_16x16x32_bf16 v[120:123], v[184:187], v[208:211], v[120:123]
	v_mfma_f32_16x16x32_bf16 v[108:111], v[132:135], v[216:219], v[108:111]
	v_mfma_f32_16x16x32_bf16 v[104:107], v[184:187], v[216:219], v[104:107]
	v_mfma_f32_16x16x32_bf16 v[92:95], v[132:135], v[224:227], v[92:95]
	v_mfma_f32_16x16x32_bf16 v[88:91], v[184:187], v[224:227], v[88:91]
	v_mfma_f32_16x16x32_bf16 v[76:79], v[132:135], v[232:235], v[76:79]
	v_mfma_f32_16x16x32_bf16 v[72:75], v[184:187], v[232:235], v[72:75]


; #define PG8_STAGE(bufoff, gbase, voff) do { _Pragma("unroll") for (int _i = 0; _i < 2; ++_i) \
;         __builtin_amdgcn_global_load_lds((const unsigned*)((const char*)(gbase) + (voff)[_i]), (LAS unsigned*)(lds + (bufoff) + ldsw + _i * 8192), 16, 0, 0); } while (0)
; #define PG8_LDA(dst, b, h) do { _Pragma("unroll") for (int m = 0; m < 4; ++m) _Pragma("unroll") for (int k = 0; k < 2; ++k) dst[m][k] = *(const LAS bf16x8*)(lds + PG8_SA(b, h) + aoff + m * 2048 + k * 1024); } while (0)
; #define PG8_MMA(ai, bj, At, Bt) do { __builtin_amdgcn_s_setprio(1); _Pragma("unroll") for (int m = 0; m < 4; ++m) _Pragma("unroll") for (int n = 0; n < 2; ++n) _Pragma("unroll") for (int k = 0; k < 2; ++k) \
;         acc[ai][bj][m][n] = __builtin_amdgcn_mfma_f32_16x16x32_bf16(Bt[n][k], At[m][k], acc[ai][bj][m][n], 0, 0, 0); __builtin_amdgcn_s_setprio(0); } while (0)
; #define PG8_WAIT_V(n) asm volatile("s_waitcnt vmcnt(" #n ")" ::: "memory")
; #define PG8_WAIT_L(n) asm volatile("s_waitcnt lgkmcnt(" #n ")" ::: "memory")
; #define PG8_BAR __builtin_amdgcn_s_barrier()
; #define PG8_SCHED __builtin_amdgcn_sched_barrier(0)
; template <class Epi>
; __device__ __forceinline__ void gemm_phase(LAS unsigned char* lds, const Gemm g, const StaticOrder& S, const Epi& E) {
;     ...
;             PG8_WAIT_V(8); PG8_WAIT_L(0); PG8_BAR; PG8_MMA(0, 0, At, B0); PG8_MMA(0, 1, At, B1); PG8_BAR; PG8_SCHED;
;             PG8_LDA(At, 0, 1); PG8_STAGE(PG8_SB(0, 0), b2, voffB); PG8_STAGE(PG8_SB(0, 1), b2 + hsB, voffB); PG8_STAGE(PG8_SA(0, 0), a2, voffA);
;             PG8_WAIT_V(8); PG8_WAIT_L(0); PG8_BAR; PG8_MMA(1, 0, At, B0); PG8_MMA(1, 1, At, B1); PG8_BAR; PG8_SCHED;
	v_mfma_f32_16x16x32_bf16 v[116:119], v[188:191], v[204:207], v[116:119]
	v_mfma_f32_16x16x32_bf16 v[112:115], v[196:199], v[204:207], v[112:115]
	v_mfma_f32_16x16x32_bf16 v[100:103], v[188:191], v[212:215], v[100:103]
	v_mfma_f32_16x16x32_bf16 v[96:99], v[196:199], v[212:215], v[96:99]
	v_mfma_f32_16x16x32_bf16 v[84:87], v[188:191], v[220:223], v[84:87]
	v_mfma_f32_16x16x32_bf16 v[80:83], v[196:199], v[220:223], v[80:83]
	v_mfma_f32_16x16x32_bf16 v[68:71], v[188:191], v[228:231], v[68:71]
	v_mfma_f32_16x16x32_bf16 v[64:67], v[196:199], v[228:231], v[64:67]
	v_mfma_f32_16x16x32_bf16 v[116:119], v[192:195], v[208:211], v[116:119]
	v_mfma_f32_16x16x32_bf16 v[112:115], v[200:203], v[208:211], v[112:115]
	v_mfma_f32_16x16x32_bf16 v[100:103], v[192:195], v[216:219], v[100:103]
	v_mfma_f32_16x16x32_bf16 v[96:99], v[200:203], v[216:219], v[96:99]
	v_mfma_f32_16x16x32_bf16 v[84:87], v[192:195], v[224:227], v[84:87]
	v_mfma_f32_16x16x32_bf16 v[80:83], v[200:203], v[224:227], v[80:83]
	v_mfma_f32_16x16x32_bf16 v[68:71], v[192:195], v[232:235], v[68:71]
	v_mfma_f32_16x16x32_bf16 v[64:67], v[200:203], v[232:235], v[64:67]
	s_setprio 0
	s_barrier
	s_add_i32 s0, s74, s60
	v_lshl_add_u64 v[168:169], s[56:57], 0, v[138:139]
	s_mov_b32 m0, s0
	ds_read_b128 v[204:207], v173 offset:16384
	ds_read_b128 v[208:211], v173 offset:17408
	ds_read_b128 v[212:215], v173 offset:18432
	ds_read_b128 v[216:219], v173 offset:19456
	ds_read_b128 v[220:223], v173 offset:20480
	ds_read_b128 v[224:227], v173 offset:21504
	ds_read_b128 v[228:231], v173 offset:22528
	ds_read_b128 v[232:235], v173 offset:23552
	global_load_lds_dwordx4 v[168:169], off
	s_add_i32 m0, s0, 0x2000
	s_add_u32 s0, s56, 0x40000
	v_lshl_add_u64 v[236:237], s[56:57], 0, v[142:143]
	s_addc_u32 s1, s57, 0
	s_add_i32 s17, s75, s60
	global_load_lds_dwordx4 v[236:237], off
	v_lshl_add_u64 v[238:239], s[0:1], 0, v[138:139]
	s_mov_b32 m0, s17
	v_lshl_add_u64 v[240:241], s[58:59], 0, v[140:141]
	global_load_lds_dwordx4 v[238:239], off
	v_lshl_add_u64 v[238:239], s[0:1], 0, v[142:143]
	s_add_i32 m0, s17, 0x2000
	s_nop 0
	global_load_lds_dwordx4 v[238:239], off
	v_lshl_add_u64 v[238:239], s[58:59], 0, v[136:137]
	s_mov_b32 m0, s61
	s_nop 0
	global_load_lds_dwordx4 v[238:239], off
	s_mov_b32 m0, s4
	s_nop 0
	global_load_lds_dwordx4 v[240:241], off
	s_waitcnt vmcnt(8)
	s_waitcnt lgkmcnt(0)
	s_setprio 1
	s_barrier

; #define PG8_MMA(ai, bj, At, Bt) do { __builtin_amdgcn_s_setprio(1); _Pragma("unroll") for (int m = 0; m < 4; ++m) _Pragma("unroll") for (int n = 0; n < 2; ++n) _Pragma("unroll") for (int k = 0; k < 2; ++k) \
;         acc[ai][bj][m][n] = __builtin_amdgcn_mfma_f32_16x16x32_bf16(Bt[n][k], At[m][k], acc[ai][bj][m][n], 0, 0, 0); __builtin_amdgcn_s_setprio(0); } while (0)
; #define PG8_WAIT_V(n) asm volatile("s_waitcnt vmcnt(" #n ")" ::: "memory")
; #define PG8_WAIT_L(n) asm volatile("s_waitcnt lgkmcnt(" #n ")" ::: "memory")
; #define PG8_BAR __builtin_amdgcn_s_barrier()
; #define PG8_SCHED __builtin_amdgcn_sched_barrier(0)
; template <class Epi>
; __device__ __forceinline__ void gemm_phase(LAS unsigned char* lds, const Gemm g, const StaticOrder& S, const Epi& E) {
;     ...
;             PG8_WAIT_V(8); PG8_WAIT_L(0); PG8_BAR; PG8_MMA(1, 0, At, B0); PG8_MMA(1, 1, At, B1); PG8_BAR; PG8_SCHED;
	v_mfma_f32_16x16x32_bf16 v[60:63], v[128:131], v[204:207], v[60:63]
	v_mfma_f32_16x16x32_bf16 v[56:59], v[164:167], v[204:207], v[56:59]
	v_mfma_f32_16x16x32_bf16 v[44:47], v[128:131], v[212:215], v[44:47]
	v_mfma_f32_16x16x32_bf16 v[40:43], v[164:167], v[212:215], v[40:43]
	v_mfma_f32_16x16x32_bf16 v[28:31], v[128:131], v[220:223], v[28:31]
	v_mfma_f32_16x16x32_bf16 v[24:27], v[164:167], v[220:223], v[24:27]
	v_mfma_f32_16x16x32_bf16 v[12:15], v[128:131], v[228:231], v[12:15]
	v_mfma_f32_16x16x32_bf16 v[8:11], v[164:167], v[228:231], v[8:11]
	v_mfma_f32_16x16x32_bf16 v[60:63], v[132:135], v[208:211], v[60:63]
	v_mfma_f32_16x16x32_bf16 v[56:59], v[184:187], v[208:211], v[56:59]
	v_mfma_f32_16x16x32_bf16 v[44:47], v[132:135], v[216:219], v[44:47]
	v_mfma_f32_16x16x32_bf16 v[40:43], v[184:187], v[216:219], v[40:43]
	v_mfma_f32_16x16x32_bf16 v[28:31], v[132:135], v[224:227], v[28:31]
	v_mfma_f32_16x16x32_bf16 v[24:27], v[184:187], v[224:227], v[24:27]
	v_mfma_f32_16x16x32_bf16 v[12:15], v[132:135], v[232:235], v[12:15]
	v_mfma_f32_16x16x32_bf16 v[8:11], v[184:187], v[232:235], v[8:11]


; #define PG8_STAGE(bufoff, gbase, voff) do { _Pragma("unroll") for (int _i = 0; _i < 2; ++_i) \
;         __builtin_amdgcn_global_load_lds((const unsigned*)((const char*)(gbase) + (voff)[_i]), (LAS unsigned*)(lds + (bufoff) + ldsw + _i * 8192), 16, 0, 0); } while (0)
; #define PG8_LDA(dst, b, h) do { _Pragma("unroll") for (int m = 0; m < 4; ++m) _Pragma("unroll") for (int k = 0; k < 2; ++k) dst[m][k] = *(const LAS bf16x8*)(lds + PG8_SA(b, h) + aoff + m * 2048 + k * 1024); } while (0)
; #define PG8_LDB(dst, b, h) do { _Pragma("unroll") for (int n = 0; n < 2; ++n) _Pragma("unroll") for (int k = 0; k < 2; ++k) dst[n][k] = *(const LAS bf16x8*)(lds + PG8_SB(b, h) + boff + n * 2048 + k * 1024); } while (0)
; #define PG8_MMA(ai, bj, At, Bt) do { __builtin_amdgcn_s_setprio(1); _Pragma("unroll") for (int m = 0; m < 4; ++m) _Pragma("unroll") for (int n = 0; n < 2; ++n) _Pragma("unroll") for (int k = 0; k < 2; ++k) \
;         acc[ai][bj][m][n] = __builtin_amdgcn_mfma_f32_16x16x32_bf16(Bt[n][k], At[m][k], acc[ai][bj][m][n], 0, 0, 0); __builtin_amdgcn_s_setprio(0); } while (0)
; #define PG8_WAIT_V(n) asm volatile("s_waitcnt vmcnt(" #n ")" ::: "memory")
; #define PG8_WAIT_L(n) asm volatile("s_waitcnt lgkmcnt(" #n ")" ::: "memory")
; #define PG8_BAR __builtin_amdgcn_s_barrier()
; #define PG8_SCHED __builtin_amdgcn_sched_barrier(0)
; template <class Epi>
; __device__ __forceinline__ void gemm_phase(LAS unsigned char* lds, const Gemm g, const StaticOrder& S, const Epi& E) {
;     ...
;             PG8_WAIT_V(8); PG8_WAIT_L(0); PG8_BAR; PG8_MMA(1, 0, At, B0); PG8_MMA(1, 1, At, B1); PG8_BAR; PG8_SCHED;
;             PG8_LDB(B0, 1, 0); PG8_LDB(B1, 1, 1); PG8_SCHED; PG8_LDA(At, 1, 0); PG8_STAGE(PG8_SA(0, 1), a2 + hsA, voffA);
;             PG8_WAIT_V(8); PG8_WAIT_L(0); PG8_BAR; PG8_MMA(0, 0, At, B0); PG8_MMA(0, 1, At, B1); PG8_BAR; PG8_SCHED;
	v_mfma_f32_16x16x32_bf16 v[52:55], v[188:191], v[204:207], v[52:55]
	v_mfma_f32_16x16x32_bf16 v[48:51], v[196:199], v[204:207], v[48:51]
	v_mfma_f32_16x16x32_bf16 v[36:39], v[188:191], v[212:215], v[36:39]
	v_mfma_f32_16x16x32_bf16 v[32:35], v[196:199], v[212:215], v[32:35]
	v_mfma_f32_16x16x32_bf16 v[20:23], v[188:191], v[220:223], v[20:23]
	v_mfma_f32_16x16x32_bf16 v[16:19], v[196:199], v[220:223], v[16:19]
	v_mfma_f32_16x16x32_bf16 v[4:7], v[188:191], v[228:231], v[4:7]
	v_mfma_f32_16x16x32_bf16 v[0:3], v[196:199], v[228:231], v[0:3]
	v_mfma_f32_16x16x32_bf16 v[52:55], v[192:195], v[208:211], v[52:55]
	v_mfma_f32_16x16x32_bf16 v[48:51], v[200:203], v[208:211], v[48:51]
	v_mfma_f32_16x16x32_bf16 v[36:39], v[192:195], v[216:219], v[36:39]
	v_mfma_f32_16x16x32_bf16 v[32:35], v[200:203], v[216:219], v[32:35]
	v_mfma_f32_16x16x32_bf16 v[20:23], v[192:195], v[224:227], v[20:23]
	v_mfma_f32_16x16x32_bf16 v[16:19], v[200:203], v[224:227], v[16:19]
	v_mfma_f32_16x16x32_bf16 v[4:7], v[192:195], v[232:235], v[4:7]
	v_mfma_f32_16x16x32_bf16 v[0:3], v[200:203], v[232:235], v[0:3]
	s_setprio 0
	s_barrier
	s_add_i32 s17, 0, 0x18000
	v_add_u32_e32 v153, s17, v171
	s_add_i32 s24, 0, 0x1c000
	ds_read_b128 v[128:131], v153
	ds_read_b128 v[132:135], v153 offset:1024
	ds_read_b128 v[164:167], v153 offset:2048
	ds_read_b128 v[184:187], v153 offset:3072
	v_add_u32_e32 v153, s24, v171
	ds_read_b128 v[188:191], v153
	ds_read_b128 v[192:195], v153 offset:1024
	ds_read_b128 v[196:199], v153 offset:2048
	ds_read_b128 v[200:203], v153 offset:3072
	s_add_u32 s0, s58, 0x100000
	s_addc_u32 s1, s59, 0
	s_mov_b32 m0, s5
	v_lshl_add_u64 v[242:243], s[0:1], 0, v[136:137]
	ds_read_b128 v[204:207], v173 offset:32768
	ds_read_b128 v[208:211], v173 offset:33792
	ds_read_b128 v[212:215], v173 offset:34816
	ds_read_b128 v[216:219], v173 offset:35840
	ds_read_b128 v[220:223], v173 offset:36864
	ds_read_b128 v[224:227], v173 offset:37888
	ds_read_b128 v[228:231], v173 offset:38912
	ds_read_b128 v[232:235], v173 offset:39936
	global_load_lds_dwordx4 v[242:243], off
	v_lshl_add_u64 v[242:243], s[0:1], 0, v[140:141]
	s_mov_b32 m0, s62
	s_nop 0
	global_load_lds_dwordx4 v[242:243], off
	s_waitcnt vmcnt(8)
	s_waitcnt lgkmcnt(0)
	s_setprio 1
	s_barrier

; #define PG8_MMA(ai, bj, At, Bt) do { __builtin_amdgcn_s_setprio(1); _Pragma("unroll") for (int m = 0; m < 4; ++m) _Pragma("unroll") for (int n = 0; n < 2; ++n) _Pragma("unroll") for (int k = 0; k < 2; ++k) \
;         acc[ai][bj][m][n] = __builtin_amdgcn_mfma_f32_16x16x32_bf16(Bt[n][k], At[m][k], acc[ai][bj][m][n], 0, 0, 0); __builtin_amdgcn_s_setprio(0); } while (0)
; #define PG8_WAIT_V(n) asm volatile("s_waitcnt vmcnt(" #n ")" ::: "memory")
; #define PG8_WAIT_L(n) asm volatile("s_waitcnt lgkmcnt(" #n ")" ::: "memory")
; #define PG8_BAR __builtin_amdgcn_s_barrier()
; #define PG8_SCHED __builtin_amdgcn_sched_barrier(0)
; template <class Epi>
; __device__ __forceinline__ void gemm_phase(LAS unsigned char* lds, const Gemm g, const StaticOrder& S, const Epi& E) {
;     ...
;             PG8_WAIT_V(8); PG8_WAIT_L(0); PG8_BAR; PG8_MMA(0, 0, At, B0); PG8_MMA(0, 1, At, B1); PG8_BAR; PG8_SCHED;
	v_mfma_f32_16x16x32_bf16 v[124:127], v[128:131], v[204:207], v[124:127]
	v_mfma_f32_16x16x32_bf16 v[120:123], v[164:167], v[204:207], v[120:123]
	v_mfma_f32_16x16x32_bf16 v[108:111], v[128:131], v[212:215], v[108:111]
	v_mfma_f32_16x16x32_bf16 v[104:107], v[164:167], v[212:215], v[104:107]
	v_mfma_f32_16x16x32_bf16 v[92:95], v[128:131], v[220:223], v[92:95]
	v_mfma_f32_16x16x32_bf16 v[88:91], v[164:167], v[220:223], v[88:91]
	v_mfma_f32_16x16x32_bf16 v[76:79], v[128:131], v[228:231], v[76:79]
	v_mfma_f32_16x16x32_bf16 v[72:75], v[164:167], v[228:231], v[72:75]
	v_mfma_f32_16x16x32_bf16 v[124:127], v[132:135], v[208:211], v[124:127]
	v_mfma_f32_16x16x32_bf16 v[120:123], v[184:187], v[208:211], v[120:123]
	v_mfma_f32_16x16x32_bf16 v[108:111], v[132:135], v[216:219], v[108:111]
	v_mfma_f32_16x16x32_bf16 v[104:107], v[184:187], v[216:219], v[104:107]
	v_mfma_f32_16x16x32_bf16 v[92:95], v[132:135], v[224:227], v[92:95]
	v_mfma_f32_16x16x32_bf16 v[88:91], v[184:187], v[224:227], v[88:91]
	v_mfma_f32_16x16x32_bf16 v[76:79], v[132:135], v[232:235], v[76:79]
	v_mfma_f32_16x16x32_bf16 v[72:75], v[184:187], v[232:235], v[72:75]


; #define PG8_STAGE(bufoff, gbase, voff) do { _Pragma("unroll") for (int _i = 0; _i < 2; ++_i) \
;         __builtin_amdgcn_global_load_lds((const unsigned*)((const char*)(gbase) + (voff)[_i]), (LAS unsigned*)(lds + (bufoff) + ldsw + _i * 8192), 16, 0, 0); } while (0)
; #define PG8_LDA(dst, b, h) do { _Pragma("unroll") for (int m = 0; m < 4; ++m) _Pragma("unroll") for (int k = 0; k < 2; ++k) dst[m][k] = *(const LAS bf16x8*)(lds + PG8_SA(b, h) + aoff + m * 2048 + k * 1024); } while (0)
; #define PG8_MMA(ai, bj, At, Bt) do { __builtin_amdgcn_s_setprio(1); _Pragma("unroll") for (int m = 0; m < 4; ++m) _Pragma("unroll") for (int n = 0; n < 2; ++n) _Pragma("unroll") for (int k = 0; k < 2; ++k) \
;         acc[ai][bj][m][n] = __builtin_amdgcn_mfma_f32_16x16x32_bf16(Bt[n][k], At[m][k], acc[ai][bj][m][n], 0, 0, 0); __builtin_amdgcn_s_setprio(0); } while (0)
; #define PG8_WAIT_V(n) asm volatile("s_waitcnt vmcnt(" #n ")" ::: "memory")
; #define PG8_WAIT_L(n) asm volatile("s_waitcnt lgkmcnt(" #n ")" ::: "memory")
; #define PG8_BAR __builtin_amdgcn_s_barrier()
; #define PG8_SCHED __builtin_amdgcn_sched_barrier(0)
; template <class Epi>
; __device__ __forceinline__ void gemm_phase(LAS unsigned char* lds, const Gemm g, const StaticOrder& S, const Epi& E) {
;     ...
;             PG8_WAIT_V(8); PG8_WAIT_L(0); PG8_BAR; PG8_MMA(0, 0, At, B0); PG8_MMA(0, 1, At, B1); PG8_BAR; PG8_SCHED;
;             PG8_LDA(At, 1, 1); PG8_STAGE(PG8_SB(1, 0), b3, voffB); PG8_STAGE(PG8_SB(1, 1), b3 + hsB, voffB); PG8_STAGE(PG8_SA(1, 0), a3, voffA);
;             PG8_WAIT_V(8); PG8_WAIT_L(0); PG8_BAR; PG8_MMA(1, 0, At, B0); PG8_MMA(1, 1, At, B1); PG8_BAR; PG8_SCHED;
	v_mfma_f32_16x16x32_bf16 v[116:119], v[188:191], v[204:207], v[116:119]
	v_mfma_f32_16x16x32_bf16 v[112:115], v[196:199], v[204:207], v[112:115]
	v_mfma_f32_16x16x32_bf16 v[100:103], v[188:191], v[212:215], v[100:103]
	v_mfma_f32_16x16x32_bf16 v[96:99], v[196:199], v[212:215], v[96:99]
	v_mfma_f32_16x16x32_bf16 v[84:87], v[188:191], v[220:223], v[84:87]
	v_mfma_f32_16x16x32_bf16 v[80:83], v[196:199], v[220:223], v[80:83]
	v_mfma_f32_16x16x32_bf16 v[68:71], v[188:191], v[228:231], v[68:71]
	v_mfma_f32_16x16x32_bf16 v[64:67], v[196:199], v[228:231], v[64:67]
	v_mfma_f32_16x16x32_bf16 v[116:119], v[192:195], v[208:211], v[116:119]
	v_mfma_f32_16x16x32_bf16 v[112:115], v[200:203], v[208:211], v[112:115]
	v_mfma_f32_16x16x32_bf16 v[100:103], v[192:195], v[216:219], v[100:103]
	v_mfma_f32_16x16x32_bf16 v[96:99], v[200:203], v[216:219], v[96:99]
	v_mfma_f32_16x16x32_bf16 v[84:87], v[192:195], v[224:227], v[84:87]
	v_mfma_f32_16x16x32_bf16 v[80:83], v[200:203], v[224:227], v[80:83]
	v_mfma_f32_16x16x32_bf16 v[68:71], v[192:195], v[232:235], v[68:71]
	v_mfma_f32_16x16x32_bf16 v[64:67], v[200:203], v[232:235], v[64:67]
	s_setprio 0
	s_barrier
	s_add_i32 s0, s17, s60
	v_lshl_add_u64 v[168:169], v[168:169], 0, s[10:11]
	s_mov_b32 m0, s0
	ds_read_b128 v[204:207], v173 offset:49152
	ds_read_b128 v[208:211], v173 offset:50176
	ds_read_b128 v[212:215], v173 offset:51200
	ds_read_b128 v[216:219], v173 offset:52224
	ds_read_b128 v[220:223], v173 offset:53248
	ds_read_b128 v[224:227], v173 offset:54272
	ds_read_b128 v[228:231], v173 offset:55296
	ds_read_b128 v[232:235], v173 offset:56320
	global_load_lds_dwordx4 v[168:169], off
	s_add_i32 m0, s0, 0x2000
	s_add_u32 s0, s56, 0x40080
	v_lshl_add_u64 v[168:169], v[236:237], 0, s[10:11]
	s_addc_u32 s1, s57, 0
	s_add_i32 s17, s24, s60
	global_load_lds_dwordx4 v[168:169], off
	v_lshl_add_u64 v[168:169], s[0:1], 0, v[138:139]
	s_mov_b32 m0, s17
	s_nop 0
	global_load_lds_dwordx4 v[168:169], off
	v_lshl_add_u64 v[168:169], s[0:1], 0, v[142:143]
	s_add_i32 m0, s17, 0x2000
	s_nop 0
	global_load_lds_dwordx4 v[168:169], off
	v_lshl_add_u64 v[168:169], v[238:239], 0, s[10:11]
	s_mov_b32 m0, s64
	s_nop 0
	global_load_lds_dwordx4 v[168:169], off
	v_lshl_add_u64 v[168:169], v[240:241], 0, s[10:11]
	s_mov_b32 m0, s65
	s_nop 0
	global_load_lds_dwordx4 v[168:169], off
	s_waitcnt vmcnt(8)
	s_waitcnt lgkmcnt(0)
	s_setprio 1
	s_barrier

; #define PG8_MMA(ai, bj, At, Bt) do { __builtin_amdgcn_s_setprio(1); _Pragma("unroll") for (int m = 0; m < 4; ++m) _Pragma("unroll") for (int n = 0; n < 2; ++n) _Pragma("unroll") for (int k = 0; k < 2; ++k) \
;         acc[ai][bj][m][n] = __builtin_amdgcn_mfma_f32_16x16x32_bf16(Bt[n][k], At[m][k], acc[ai][bj][m][n], 0, 0, 0); __builtin_amdgcn_s_setprio(0); } while (0)
; #define PG8_WAIT_V(n) asm volatile("s_waitcnt vmcnt(" #n ")" ::: "memory")
; #define PG8_WAIT_L(n) asm volatile("s_waitcnt lgkmcnt(" #n ")" ::: "memory")
; #define PG8_BAR __builtin_amdgcn_s_barrier()
; #define PG8_SCHED __builtin_amdgcn_sched_barrier(0)
; template <class Epi>
; __device__ __forceinline__ void gemm_phase(LAS unsigned char* lds, const Gemm g, const StaticOrder& S, const Epi& E) {
;     ...
;             PG8_WAIT_V(8); PG8_WAIT_L(0); PG8_BAR; PG8_MMA(1, 0, At, B0); PG8_MMA(1, 1, At, B1); PG8_BAR; PG8_SCHED;
	v_mfma_f32_16x16x32_bf16 v[60:63], v[128:131], v[204:207], v[60:63]
	v_mfma_f32_16x16x32_bf16 v[56:59], v[164:167], v[204:207], v[56:59]
	v_mfma_f32_16x16x32_bf16 v[44:47], v[128:131], v[212:215], v[44:47]
	v_mfma_f32_16x16x32_bf16 v[40:43], v[164:167], v[212:215], v[40:43]
	v_mfma_f32_16x16x32_bf16 v[28:31], v[128:131], v[220:223], v[28:31]
	v_mfma_f32_16x16x32_bf16 v[24:27], v[164:167], v[220:223], v[24:27]
	v_mfma_f32_16x16x32_bf16 v[12:15], v[128:131], v[228:231], v[12:15]
	v_mfma_f32_16x16x32_bf16 v[8:11], v[164:167], v[228:231], v[8:11]
	v_mfma_f32_16x16x32_bf16 v[60:63], v[132:135], v[208:211], v[60:63]
	v_mfma_f32_16x16x32_bf16 v[56:59], v[184:187], v[208:211], v[56:59]
	v_mfma_f32_16x16x32_bf16 v[44:47], v[132:135], v[216:219], v[44:47]
	v_mfma_f32_16x16x32_bf16 v[40:43], v[184:187], v[216:219], v[40:43]
	v_mfma_f32_16x16x32_bf16 v[28:31], v[132:135], v[224:227], v[28:31]
	v_mfma_f32_16x16x32_bf16 v[24:27], v[184:187], v[224:227], v[24:27]
	v_mfma_f32_16x16x32_bf16 v[12:15], v[132:135], v[232:235], v[12:15]
	v_mfma_f32_16x16x32_bf16 v[8:11], v[184:187], v[232:235], v[8:11]


; #define PG8_MMA(ai, bj, At, Bt) do { __builtin_amdgcn_s_setprio(1); _Pragma("unroll") for (int m = 0; m < 4; ++m) _Pragma("unroll") for (int n = 0; n < 2; ++n) _Pragma("unroll") for (int k = 0; k < 2; ++k) \
;         acc[ai][bj][m][n] = __builtin_amdgcn_mfma_f32_16x16x32_bf16(Bt[n][k], At[m][k], acc[ai][bj][m][n], 0, 0, 0); __builtin_amdgcn_s_setprio(0); } while (0)
; #define PG8_WAIT_V(n) asm volatile("s_waitcnt vmcnt(" #n ")" ::: "memory")
; #define PG8_WAIT_L(n) asm volatile("s_waitcnt lgkmcnt(" #n ")" ::: "memory")
; #define PG8_BAR __builtin_amdgcn_s_barrier()
; #define PG8_SCHED __builtin_amdgcn_sched_barrier(0)
; template <class Epi>
; __device__ __forceinline__ void gemm_phase(LAS unsigned char* lds, const Gemm g, const StaticOrder& S, const Epi& E) {
;     ...
;         for (int t = 0; t < nt; t += 2) {
;     ...
;             PG8_WAIT_V(8); PG8_WAIT_L(0); PG8_BAR; PG8_MMA(1, 0, At, B0); PG8_MMA(1, 1, At, B1); PG8_BAR; PG8_SCHED;
;         }
	v_mfma_f32_16x16x32_bf16 v[52:55], v[188:191], v[204:207], v[52:55]
	v_mfma_f32_16x16x32_bf16 v[48:51], v[196:199], v[204:207], v[48:51]
	v_mfma_f32_16x16x32_bf16 v[36:39], v[188:191], v[212:215], v[36:39]
	v_mfma_f32_16x16x32_bf16 v[32:35], v[196:199], v[212:215], v[32:35]
	v_mfma_f32_16x16x32_bf16 v[20:23], v[188:191], v[220:223], v[20:23]
	v_mfma_f32_16x16x32_bf16 v[16:19], v[196:199], v[220:223], v[16:19]
	v_mfma_f32_16x16x32_bf16 v[4:7], v[188:191], v[228:231], v[4:7]
	v_mfma_f32_16x16x32_bf16 v[0:3], v[196:199], v[228:231], v[0:3]
	v_mfma_f32_16x16x32_bf16 v[52:55], v[192:195], v[208:211], v[52:55]
	v_mfma_f32_16x16x32_bf16 v[48:51], v[200:203], v[208:211], v[48:51]
	v_mfma_f32_16x16x32_bf16 v[36:39], v[192:195], v[216:219], v[36:39]
	v_mfma_f32_16x16x32_bf16 v[32:35], v[200:203], v[216:219], v[32:35]
	v_mfma_f32_16x16x32_bf16 v[20:23], v[192:195], v[224:227], v[20:23]
	v_mfma_f32_16x16x32_bf16 v[16:19], v[200:203], v[224:227], v[16:19]
	v_mfma_f32_16x16x32_bf16 v[4:7], v[192:195], v[232:235], v[4:7]
	v_mfma_f32_16x16x32_bf16 v[0:3], v[200:203], v[232:235], v[0:3]
	s_setprio 0
	s_barrier
	s_add_u32 s54, s54, 0x100
	s_addc_u32 s55, 0, s55
	s_cmp_gt_u32 s33, 29
	s_cbranch_scc1 .LBB0_1086

; #define PG8_STAGE(bufoff, gbase, voff) do { _Pragma("unroll") for (int _i = 0; _i < 2; ++_i) \
;         __builtin_amdgcn_global_load_lds((const unsigned*)((const char*)(gbase) + (voff)[_i]), (LAS unsigned*)(lds + (bufoff) + ldsw + _i * 8192), 16, 0, 0); } while (0)
; #define PG8_LDA(dst, b, h) do { _Pragma("unroll") for (int m = 0; m < 4; ++m) _Pragma("unroll") for (int k = 0; k < 2; ++k) dst[m][k] = *(const LAS bf16x8*)(lds + PG8_SA(b, h) + aoff + m * 2048 + k * 1024); } while (0)
; #define PG8_LDB(dst, b, h) do { _Pragma("unroll") for (int n = 0; n < 2; ++n) _Pragma("unroll") for (int k = 0; k < 2; ++k) dst[n][k] = *(const LAS bf16x8*)(lds + PG8_SB(b, h) + boff + n * 2048 + k * 1024); } while (0)
; #define PG8_MMA(ai, bj, At, Bt) do { __builtin_amdgcn_s_setprio(1); _Pragma("unroll") for (int m = 0; m < 4; ++m) _Pragma("unroll") for (int n = 0; n < 2; ++n) _Pragma("unroll") for (int k = 0; k < 2; ++k) \
;         acc[ai][bj][m][n] = __builtin_amdgcn_mfma_f32_16x16x32_bf16(Bt[n][k], At[m][k], acc[ai][bj][m][n], 0, 0, 0); __builtin_amdgcn_s_setprio(0); } while (0)
; #define PG8_WAIT_V(n) asm volatile("s_waitcnt vmcnt(" #n ")" ::: "memory")
; #define PG8_WAIT_L(n) asm volatile("s_waitcnt lgkmcnt(" #n ")" ::: "memory")
; #define PG8_BAR __builtin_amdgcn_s_barrier()
; #define PG8_SCHED __builtin_amdgcn_sched_barrier(0)
; template <class Epi>
; __device__ __forceinline__ void gemm_phase(LAS unsigned char* lds, const Gemm g, const StaticOrder& S, const Epi& E) {
;     ...
;             const char* a2 = last ? nA : cA + ((Epi::HAS_MID && t + 2 >= nt1) ? dA2 : 0) + (size_t)(t + 2) * kstep; const char* b2 = last ? nB : cB + ((Epi::HAS_MID && t + 2 >= nt1) ? dB2 : 0) + (size_t)(t + 2) * kstep;
;             const char* a3 = a2 + kstep; const char* b3 = b2 + kstep;
;             PG8_LDB(B0, 0, 0); PG8_LDB(B1, 0, 1); PG8_SCHED; PG8_LDA(At, 0, 0); PG8_STAGE(PG8_SA(1, 1), a1 + hsA, voffA);
;             PG8_WAIT_V(8); PG8_WAIT_L(0); PG8_BAR; PG8_MMA(0, 0, At, B0); PG8_MMA(0, 1, At, B1); PG8_BAR; PG8_SCHED;
.LBB0_1234:
	ds_read_b128 v[144:147], v155
	ds_read_b128 v[148:151], v155 offset:1024
	ds_read_b128 v[162:165], v155 offset:2048
	ds_read_b128 v[166:169], v155 offset:3072
	ds_read_b128 v[170:173], v156
	ds_read_b128 v[174:177], v156 offset:1024
	ds_read_b128 v[184:187], v156 offset:2048
	ds_read_b128 v[188:191], v156 offset:3072
	s_add_u32 s39, s48, 0xfffc0080
	s_addc_u32 s41, s49, -1
	s_cmp_eq_u32 s35, 12
	s_cselect_b32 s53, s0, s41
	s_cselect_b32 s52, s1, s39
	s_cselect_b32 s51, s6, s34
	s_cselect_b32 s50, s7, s13
	s_add_i32 m0, s5, 0xc000
	ds_read_b128 v[192:195], v157
	ds_read_b128 v[196:199], v157 offset:1024
	ds_read_b128 v[200:203], v157 offset:2048
	ds_read_b128 v[204:207], v157 offset:3072
	ds_read_b128 v[208:211], v157 offset:4096
	ds_read_b128 v[212:215], v157 offset:5120
	ds_read_b128 v[216:219], v157 offset:6144
	ds_read_b128 v[220:223], v157 offset:7168
	global_load_lds_dwordx4 v136, s[48:49]
	s_add_i32 m0, s5, 0xe000
	s_nop 0
	global_load_lds_dwordx4 v138, s[48:49]
	s_waitcnt vmcnt(8)
	s_waitcnt lgkmcnt(0)
	s_setprio 1
	s_barrier

; #define PG8_MMA(ai, bj, At, Bt) do { __builtin_amdgcn_s_setprio(1); _Pragma("unroll") for (int m = 0; m < 4; ++m) _Pragma("unroll") for (int n = 0; n < 2; ++n) _Pragma("unroll") for (int k = 0; k < 2; ++k) \
;         acc[ai][bj][m][n] = __builtin_amdgcn_mfma_f32_16x16x32_bf16(Bt[n][k], At[m][k], acc[ai][bj][m][n], 0, 0, 0); __builtin_amdgcn_s_setprio(0); } while (0)
; #define PG8_WAIT_V(n) asm volatile("s_waitcnt vmcnt(" #n ")" ::: "memory")
; #define PG8_WAIT_L(n) asm volatile("s_waitcnt lgkmcnt(" #n ")" ::: "memory")
; #define PG8_BAR __builtin_amdgcn_s_barrier()
; #define PG8_SCHED __builtin_amdgcn_sched_barrier(0)
; template <class Epi>
; __device__ __forceinline__ void gemm_phase(LAS unsigned char* lds, const Gemm g, const StaticOrder& S, const Epi& E) {
;     ...
;             PG8_WAIT_V(8); PG8_WAIT_L(0); PG8_BAR; PG8_MMA(0, 0, At, B0); PG8_MMA(0, 1, At, B1); PG8_BAR; PG8_SCHED;
	v_mfma_f32_16x16x32_bf16 v[124:127], v[144:147], v[192:195], v[124:127]
	v_mfma_f32_16x16x32_bf16 v[120:123], v[162:165], v[192:195], v[120:123]
	v_mfma_f32_16x16x32_bf16 v[108:111], v[144:147], v[200:203], v[108:111]
	v_mfma_f32_16x16x32_bf16 v[104:107], v[162:165], v[200:203], v[104:107]
	v_mfma_f32_16x16x32_bf16 v[92:95], v[144:147], v[208:211], v[92:95]
	v_mfma_f32_16x16x32_bf16 v[88:91], v[162:165], v[208:211], v[88:91]
	v_mfma_f32_16x16x32_bf16 v[76:79], v[144:147], v[216:219], v[76:79]
	v_mfma_f32_16x16x32_bf16 v[72:75], v[162:165], v[216:219], v[72:75]
	v_mfma_f32_16x16x32_bf16 v[124:127], v[148:151], v[196:199], v[124:127]
	v_mfma_f32_16x16x32_bf16 v[120:123], v[166:169], v[196:199], v[120:123]
	v_mfma_f32_16x16x32_bf16 v[108:111], v[148:151], v[204:207], v[108:111]
	v_mfma_f32_16x16x32_bf16 v[104:107], v[166:169], v[204:207], v[104:107]
	v_mfma_f32_16x16x32_bf16 v[92:95], v[148:151], v[212:215], v[92:95]
	v_mfma_f32_16x16x32_bf16 v[88:91], v[166:169], v[212:215], v[88:91]
	v_mfma_f32_16x16x32_bf16 v[76:79], v[148:151], v[220:223], v[76:79]
	v_mfma_f32_16x16x32_bf16 v[72:75], v[166:169], v[220:223], v[72:75]


; #define PG8_STAGE(bufoff, gbase, voff) do { _Pragma("unroll") for (int _i = 0; _i < 2; ++_i) \
;         __builtin_amdgcn_global_load_lds((const unsigned*)((const char*)(gbase) + (voff)[_i]), (LAS unsigned*)(lds + (bufoff) + ldsw + _i * 8192), 16, 0, 0); } while (0)
; #define PG8_LDA(dst, b, h) do { _Pragma("unroll") for (int m = 0; m < 4; ++m) _Pragma("unroll") for (int k = 0; k < 2; ++k) dst[m][k] = *(const LAS bf16x8*)(lds + PG8_SA(b, h) + aoff + m * 2048 + k * 1024); } while (0)
; #define PG8_MMA(ai, bj, At, Bt) do { __builtin_amdgcn_s_setprio(1); _Pragma("unroll") for (int m = 0; m < 4; ++m) _Pragma("unroll") for (int n = 0; n < 2; ++n) _Pragma("unroll") for (int k = 0; k < 2; ++k) \
;         acc[ai][bj][m][n] = __builtin_amdgcn_mfma_f32_16x16x32_bf16(Bt[n][k], At[m][k], acc[ai][bj][m][n], 0, 0, 0); __builtin_amdgcn_s_setprio(0); } while (0)
; #define PG8_WAIT_V(n) asm volatile("s_waitcnt vmcnt(" #n ")" ::: "memory")
; #define PG8_WAIT_L(n) asm volatile("s_waitcnt lgkmcnt(" #n ")" ::: "memory")
; #define PG8_BAR __builtin_amdgcn_s_barrier()
; #define PG8_SCHED __builtin_amdgcn_sched_barrier(0)
; template <class Epi>
; __device__ __forceinline__ void gemm_phase(LAS unsigned char* lds, const Gemm g, const StaticOrder& S, const Epi& E) {
;     ...
;             PG8_WAIT_V(8); PG8_WAIT_L(0); PG8_BAR; PG8_MMA(0, 0, At, B0); PG8_MMA(0, 1, At, B1); PG8_BAR; PG8_SCHED;
;             PG8_LDA(At, 0, 1); PG8_STAGE(PG8_SB(0, 0), b2, voffB); PG8_STAGE(PG8_SB(0, 1), b2 + hsB, voffB); PG8_STAGE(PG8_SA(0, 0), a2, voffA);
;             PG8_WAIT_V(8); PG8_WAIT_L(0); PG8_BAR; PG8_MMA(1, 0, At, B0); PG8_MMA(1, 1, At, B1); PG8_BAR; PG8_SCHED;
	v_mfma_f32_16x16x32_bf16 v[116:119], v[170:173], v[192:195], v[116:119]
	v_mfma_f32_16x16x32_bf16 v[112:115], v[184:187], v[192:195], v[112:115]
	v_mfma_f32_16x16x32_bf16 v[100:103], v[170:173], v[200:203], v[100:103]
	v_mfma_f32_16x16x32_bf16 v[96:99], v[184:187], v[200:203], v[96:99]
	v_mfma_f32_16x16x32_bf16 v[84:87], v[170:173], v[208:211], v[84:87]
	v_mfma_f32_16x16x32_bf16 v[80:83], v[184:187], v[208:211], v[80:83]
	v_mfma_f32_16x16x32_bf16 v[68:71], v[170:173], v[216:219], v[68:71]
	v_mfma_f32_16x16x32_bf16 v[64:67], v[184:187], v[216:219], v[64:67]
	v_mfma_f32_16x16x32_bf16 v[116:119], v[174:177], v[196:199], v[116:119]
	v_mfma_f32_16x16x32_bf16 v[112:115], v[188:191], v[196:199], v[112:115]
	v_mfma_f32_16x16x32_bf16 v[100:103], v[174:177], v[204:207], v[100:103]
	v_mfma_f32_16x16x32_bf16 v[96:99], v[188:191], v[204:207], v[96:99]
	v_mfma_f32_16x16x32_bf16 v[84:87], v[174:177], v[212:215], v[84:87]
	v_mfma_f32_16x16x32_bf16 v[80:83], v[188:191], v[212:215], v[80:83]
	v_mfma_f32_16x16x32_bf16 v[68:71], v[174:177], v[220:223], v[68:71]
	v_mfma_f32_16x16x32_bf16 v[64:67], v[188:191], v[220:223], v[64:67]
	s_setprio 0
	s_barrier
	s_add_i32 s39, s31, s4
	s_mov_b32 m0, s39
	ds_read_b128 v[192:195], v157 offset:16384
	ds_read_b128 v[196:199], v157 offset:17408
	ds_read_b128 v[200:203], v157 offset:18432
	ds_read_b128 v[204:207], v157 offset:19456
	ds_read_b128 v[208:211], v157 offset:20480
	ds_read_b128 v[212:215], v157 offset:21504
	ds_read_b128 v[216:219], v157 offset:22528
	ds_read_b128 v[220:223], v157 offset:23552
	global_load_lds_dwordx4 v130, s[50:51]
	s_add_i32 m0, s39, 0x2000
	s_add_u32 s54, s50, 0x40000
	s_addc_u32 s55, s51, 0
	s_add_i32 s39, s33, s4
	global_load_lds_dwordx4 v134, s[50:51]
	s_mov_b32 m0, s39
	s_nop 0
	global_load_lds_dwordx4 v130, s[54:55]
	s_add_i32 m0, s39, 0x2000
	s_nop 0
	global_load_lds_dwordx4 v134, s[54:55]
	s_mov_b32 m0, s5
	s_nop 0
	global_load_lds_dwordx4 v128, s[52:53]
	s_mov_b32 m0, s16
	s_nop 0
	global_load_lds_dwordx4 v132, s[52:53]
	s_waitcnt vmcnt(8)
	s_waitcnt lgkmcnt(0)
	s_setprio 1
	s_barrier

; #define PG8_MMA(ai, bj, At, Bt) do { __builtin_amdgcn_s_setprio(1); _Pragma("unroll") for (int m = 0; m < 4; ++m) _Pragma("unroll") for (int n = 0; n < 2; ++n) _Pragma("unroll") for (int k = 0; k < 2; ++k) \
;         acc[ai][bj][m][n] = __builtin_amdgcn_mfma_f32_16x16x32_bf16(Bt[n][k], At[m][k], acc[ai][bj][m][n], 0, 0, 0); __builtin_amdgcn_s_setprio(0); } while (0)
; #define PG8_WAIT_V(n) asm volatile("s_waitcnt vmcnt(" #n ")" ::: "memory")
; #define PG8_WAIT_L(n) asm volatile("s_waitcnt lgkmcnt(" #n ")" ::: "memory")
; #define PG8_BAR __builtin_amdgcn_s_barrier()
; #define PG8_SCHED __builtin_amdgcn_sched_barrier(0)
; template <class Epi>
; __device__ __forceinline__ void gemm_phase(LAS unsigned char* lds, const Gemm g, const StaticOrder& S, const Epi& E) {
;     ...
;             PG8_WAIT_V(8); PG8_WAIT_L(0); PG8_BAR; PG8_MMA(1, 0, At, B0); PG8_MMA(1, 1, At, B1); PG8_BAR; PG8_SCHED;
	v_mfma_f32_16x16x32_bf16 v[60:63], v[144:147], v[192:195], v[60:63]
	v_mfma_f32_16x16x32_bf16 v[56:59], v[162:165], v[192:195], v[56:59]
	v_mfma_f32_16x16x32_bf16 v[44:47], v[144:147], v[200:203], v[44:47]
	v_mfma_f32_16x16x32_bf16 v[40:43], v[162:165], v[200:203], v[40:43]
	v_mfma_f32_16x16x32_bf16 v[28:31], v[144:147], v[208:211], v[28:31]
	v_mfma_f32_16x16x32_bf16 v[24:27], v[162:165], v[208:211], v[24:27]
	v_mfma_f32_16x16x32_bf16 v[12:15], v[144:147], v[216:219], v[12:15]
	v_mfma_f32_16x16x32_bf16 v[8:11], v[162:165], v[216:219], v[8:11]
	v_mfma_f32_16x16x32_bf16 v[60:63], v[148:151], v[196:199], v[60:63]
	v_mfma_f32_16x16x32_bf16 v[56:59], v[166:169], v[196:199], v[56:59]
	v_mfma_f32_16x16x32_bf16 v[44:47], v[148:151], v[204:207], v[44:47]
	v_mfma_f32_16x16x32_bf16 v[40:43], v[166:169], v[204:207], v[40:43]
	v_mfma_f32_16x16x32_bf16 v[28:31], v[148:151], v[212:215], v[28:31]
	v_mfma_f32_16x16x32_bf16 v[24:27], v[166:169], v[212:215], v[24:27]
	v_mfma_f32_16x16x32_bf16 v[12:15], v[148:151], v[220:223], v[12:15]
	v_mfma_f32_16x16x32_bf16 v[8:11], v[166:169], v[220:223], v[8:11]


; #define PG8_STAGE(bufoff, gbase, voff) do { _Pragma("unroll") for (int _i = 0; _i < 2; ++_i) \
;         __builtin_amdgcn_global_load_lds((const unsigned*)((const char*)(gbase) + (voff)[_i]), (LAS unsigned*)(lds + (bufoff) + ldsw + _i * 8192), 16, 0, 0); } while (0)
; #define PG8_LDA(dst, b, h) do { _Pragma("unroll") for (int m = 0; m < 4; ++m) _Pragma("unroll") for (int k = 0; k < 2; ++k) dst[m][k] = *(const LAS bf16x8*)(lds + PG8_SA(b, h) + aoff + m * 2048 + k * 1024); } while (0)
; #define PG8_LDB(dst, b, h) do { _Pragma("unroll") for (int n = 0; n < 2; ++n) _Pragma("unroll") for (int k = 0; k < 2; ++k) dst[n][k] = *(const LAS bf16x8*)(lds + PG8_SB(b, h) + boff + n * 2048 + k * 1024); } while (0)
; #define PG8_MMA(ai, bj, At, Bt) do { __builtin_amdgcn_s_setprio(1); _Pragma("unroll") for (int m = 0; m < 4; ++m) _Pragma("unroll") for (int n = 0; n < 2; ++n) _Pragma("unroll") for (int k = 0; k < 2; ++k) \
;         acc[ai][bj][m][n] = __builtin_amdgcn_mfma_f32_16x16x32_bf16(Bt[n][k], At[m][k], acc[ai][bj][m][n], 0, 0, 0); __builtin_amdgcn_s_setprio(0); } while (0)
; #define PG8_WAIT_V(n) asm volatile("s_waitcnt vmcnt(" #n ")" ::: "memory")
; #define PG8_WAIT_L(n) asm volatile("s_waitcnt lgkmcnt(" #n ")" ::: "memory")
; #define PG8_BAR __builtin_amdgcn_s_barrier()
; #define PG8_SCHED __builtin_amdgcn_sched_barrier(0)
; template <class Epi>
; __device__ __forceinline__ void gemm_phase(LAS unsigned char* lds, const Gemm g, const StaticOrder& S, const Epi& E) {
;     ...
;             PG8_WAIT_V(8); PG8_WAIT_L(0); PG8_BAR; PG8_MMA(1, 0, At, B0); PG8_MMA(1, 1, At, B1); PG8_BAR; PG8_SCHED;
;             PG8_LDB(B0, 1, 0); PG8_LDB(B1, 1, 1); PG8_SCHED; PG8_LDA(At, 1, 0); PG8_STAGE(PG8_SA(0, 1), a2 + hsA, voffA);
;             PG8_WAIT_V(8); PG8_WAIT_L(0); PG8_BAR; PG8_MMA(0, 0, At, B0); PG8_MMA(0, 1, At, B1); PG8_BAR; PG8_SCHED;
	v_mfma_f32_16x16x32_bf16 v[52:55], v[170:173], v[192:195], v[52:55]
	v_mfma_f32_16x16x32_bf16 v[48:51], v[184:187], v[192:195], v[48:51]
	v_mfma_f32_16x16x32_bf16 v[36:39], v[170:173], v[200:203], v[36:39]
	v_mfma_f32_16x16x32_bf16 v[32:35], v[184:187], v[200:203], v[32:35]
	v_mfma_f32_16x16x32_bf16 v[20:23], v[170:173], v[208:211], v[20:23]
	v_mfma_f32_16x16x32_bf16 v[16:19], v[184:187], v[208:211], v[16:19]
	v_mfma_f32_16x16x32_bf16 v[4:7], v[170:173], v[216:219], v[4:7]
	v_mfma_f32_16x16x32_bf16 v[0:3], v[184:187], v[216:219], v[0:3]
	v_mfma_f32_16x16x32_bf16 v[52:55], v[174:177], v[196:199], v[52:55]
	v_mfma_f32_16x16x32_bf16 v[48:51], v[188:191], v[196:199], v[48:51]
	v_mfma_f32_16x16x32_bf16 v[36:39], v[174:177], v[204:207], v[36:39]
	v_mfma_f32_16x16x32_bf16 v[32:35], v[188:191], v[204:207], v[32:35]
	v_mfma_f32_16x16x32_bf16 v[20:23], v[174:177], v[212:215], v[20:23]
	v_mfma_f32_16x16x32_bf16 v[16:19], v[188:191], v[212:215], v[16:19]
	v_mfma_f32_16x16x32_bf16 v[4:7], v[174:177], v[220:223], v[4:7]
	v_mfma_f32_16x16x32_bf16 v[0:3], v[188:191], v[220:223], v[0:3]
	s_setprio 0
	s_barrier
	s_add_i32 s39, 0, 0x18000
	v_add_u32_e32 v160, s39, v153
	s_add_i32 s41, 0, 0x1c000
	ds_read_b128 v[144:147], v160
	ds_read_b128 v[148:151], v160 offset:1024
	ds_read_b128 v[162:165], v160 offset:2048
	ds_read_b128 v[166:169], v160 offset:3072
	v_add_u32_e32 v160, s41, v153
	ds_read_b128 v[170:173], v160
	ds_read_b128 v[174:177], v160 offset:1024
	ds_read_b128 v[184:187], v160 offset:2048
	ds_read_b128 v[188:191], v160 offset:3072
	s_add_u32 s52, s52, 0x40000
	s_addc_u32 s53, s53, 0
	s_mov_b32 m0, s17
	ds_read_b128 v[192:195], v157 offset:32768
	ds_read_b128 v[196:199], v157 offset:33792
	ds_read_b128 v[200:203], v157 offset:34816
	ds_read_b128 v[204:207], v157 offset:35840
	ds_read_b128 v[208:211], v157 offset:36864
	ds_read_b128 v[212:215], v157 offset:37888
	ds_read_b128 v[216:219], v157 offset:38912
	ds_read_b128 v[220:223], v157 offset:39936
	global_load_lds_dwordx4 v128, s[52:53]
	s_mov_b32 m0, s18
	s_nop 0
	global_load_lds_dwordx4 v132, s[52:53]
	s_waitcnt vmcnt(8)
	s_waitcnt lgkmcnt(0)
	s_setprio 1
	s_barrier

; #define PG8_MMA(ai, bj, At, Bt) do { __builtin_amdgcn_s_setprio(1); _Pragma("unroll") for (int m = 0; m < 4; ++m) _Pragma("unroll") for (int n = 0; n < 2; ++n) _Pragma("unroll") for (int k = 0; k < 2; ++k) \
;         acc[ai][bj][m][n] = __builtin_amdgcn_mfma_f32_16x16x32_bf16(Bt[n][k], At[m][k], acc[ai][bj][m][n], 0, 0, 0); __builtin_amdgcn_s_setprio(0); } while (0)
; #define PG8_WAIT_V(n) asm volatile("s_waitcnt vmcnt(" #n ")" ::: "memory")
; #define PG8_WAIT_L(n) asm volatile("s_waitcnt lgkmcnt(" #n ")" ::: "memory")
; #define PG8_BAR __builtin_amdgcn_s_barrier()
; #define PG8_SCHED __builtin_amdgcn_sched_barrier(0)
; template <class Epi>
; __device__ __forceinline__ void gemm_phase(LAS unsigned char* lds, const Gemm g, const StaticOrder& S, const Epi& E) {
;     ...
;             PG8_WAIT_V(8); PG8_WAIT_L(0); PG8_BAR; PG8_MMA(0, 0, At, B0); PG8_MMA(0, 1, At, B1); PG8_BAR; PG8_SCHED;
	v_mfma_f32_16x16x32_bf16 v[124:127], v[144:147], v[192:195], v[124:127]
	v_mfma_f32_16x16x32_bf16 v[120:123], v[162:165], v[192:195], v[120:123]
	v_mfma_f32_16x16x32_bf16 v[108:111], v[144:147], v[200:203], v[108:111]
	v_mfma_f32_16x16x32_bf16 v[104:107], v[162:165], v[200:203], v[104:107]
	v_mfma_f32_16x16x32_bf16 v[92:95], v[144:147], v[208:211], v[92:95]
	v_mfma_f32_16x16x32_bf16 v[88:91], v[162:165], v[208:211], v[88:91]
	v_mfma_f32_16x16x32_bf16 v[76:79], v[144:147], v[216:219], v[76:79]
	v_mfma_f32_16x16x32_bf16 v[72:75], v[162:165], v[216:219], v[72:75]
	v_mfma_f32_16x16x32_bf16 v[124:127], v[148:151], v[196:199], v[124:127]
	v_mfma_f32_16x16x32_bf16 v[120:123], v[166:169], v[196:199], v[120:123]
	v_mfma_f32_16x16x32_bf16 v[108:111], v[148:151], v[204:207], v[108:111]
	v_mfma_f32_16x16x32_bf16 v[104:107], v[166:169], v[204:207], v[104:107]
	v_mfma_f32_16x16x32_bf16 v[92:95], v[148:151], v[212:215], v[92:95]
	v_mfma_f32_16x16x32_bf16 v[88:91], v[166:169], v[212:215], v[88:91]
	v_mfma_f32_16x16x32_bf16 v[76:79], v[148:151], v[220:223], v[76:79]
	v_mfma_f32_16x16x32_bf16 v[72:75], v[166:169], v[220:223], v[72:75]


; #define PG8_STAGE(bufoff, gbase, voff) do { _Pragma("unroll") for (int _i = 0; _i < 2; ++_i) \
;         __builtin_amdgcn_global_load_lds((const unsigned*)((const char*)(gbase) + (voff)[_i]), (LAS unsigned*)(lds + (bufoff) + ldsw + _i * 8192), 16, 0, 0); } while (0)
; #define PG8_LDA(dst, b, h) do { _Pragma("unroll") for (int m = 0; m < 4; ++m) _Pragma("unroll") for (int k = 0; k < 2; ++k) dst[m][k] = *(const LAS bf16x8*)(lds + PG8_SA(b, h) + aoff + m * 2048 + k * 1024); } while (0)
; #define PG8_MMA(ai, bj, At, Bt) do { __builtin_amdgcn_s_setprio(1); _Pragma("unroll") for (int m = 0; m < 4; ++m) _Pragma("unroll") for (int n = 0; n < 2; ++n) _Pragma("unroll") for (int k = 0; k < 2; ++k) \
;         acc[ai][bj][m][n] = __builtin_amdgcn_mfma_f32_16x16x32_bf16(Bt[n][k], At[m][k], acc[ai][bj][m][n], 0, 0, 0); __builtin_amdgcn_s_setprio(0); } while (0)
; #define PG8_WAIT_V(n) asm volatile("s_waitcnt vmcnt(" #n ")" ::: "memory")
; #define PG8_WAIT_L(n) asm volatile("s_waitcnt lgkmcnt(" #n ")" ::: "memory")
; #define PG8_BAR __builtin_amdgcn_s_barrier()
; #define PG8_SCHED __builtin_amdgcn_sched_barrier(0)
; template <class Epi>
; __device__ __forceinline__ void gemm_phase(LAS unsigned char* lds, const Gemm g, const StaticOrder& S, const Epi& E) {
;     ...
;             PG8_WAIT_V(8); PG8_WAIT_L(0); PG8_BAR; PG8_MMA(0, 0, At, B0); PG8_MMA(0, 1, At, B1); PG8_BAR; PG8_SCHED;
;             PG8_LDA(At, 1, 1); PG8_STAGE(PG8_SB(1, 0), b3, voffB); PG8_STAGE(PG8_SB(1, 1), b3 + hsB, voffB); PG8_STAGE(PG8_SA(1, 0), a3, voffA);
;             PG8_WAIT_V(8); PG8_WAIT_L(0); PG8_BAR; PG8_MMA(1, 0, At, B0); PG8_MMA(1, 1, At, B1); PG8_BAR; PG8_SCHED;
	v_mfma_f32_16x16x32_bf16 v[116:119], v[170:173], v[192:195], v[116:119]
	v_mfma_f32_16x16x32_bf16 v[112:115], v[184:187], v[192:195], v[112:115]
	v_mfma_f32_16x16x32_bf16 v[100:103], v[170:173], v[200:203], v[100:103]
	v_mfma_f32_16x16x32_bf16 v[96:99], v[184:187], v[200:203], v[96:99]
	v_mfma_f32_16x16x32_bf16 v[84:87], v[170:173], v[208:211], v[84:87]
	v_mfma_f32_16x16x32_bf16 v[80:83], v[184:187], v[208:211], v[80:83]
	v_mfma_f32_16x16x32_bf16 v[68:71], v[170:173], v[216:219], v[68:71]
	v_mfma_f32_16x16x32_bf16 v[64:67], v[184:187], v[216:219], v[64:67]
	v_mfma_f32_16x16x32_bf16 v[116:119], v[174:177], v[196:199], v[116:119]
	v_mfma_f32_16x16x32_bf16 v[112:115], v[188:191], v[196:199], v[112:115]
	v_mfma_f32_16x16x32_bf16 v[100:103], v[174:177], v[204:207], v[100:103]
	v_mfma_f32_16x16x32_bf16 v[96:99], v[188:191], v[204:207], v[96:99]
	v_mfma_f32_16x16x32_bf16 v[84:87], v[174:177], v[212:215], v[84:87]
	v_mfma_f32_16x16x32_bf16 v[80:83], v[188:191], v[212:215], v[80:83]
	v_mfma_f32_16x16x32_bf16 v[68:71], v[174:177], v[220:223], v[68:71]
	v_mfma_f32_16x16x32_bf16 v[64:67], v[188:191], v[220:223], v[64:67]
	s_setprio 0
	s_barrier
	s_add_u32 s98, s50, 0x80
	s_addc_u32 s99, s51, 0
	s_add_u32 s100, s52, 0xfffc0080
	s_addc_u32 s101, s53, -1
	s_add_i32 s39, s39, s4
	s_mov_b32 m0, s39
	ds_read_b128 v[192:195], v157 offset:49152
	ds_read_b128 v[196:199], v157 offset:50176
	ds_read_b128 v[200:203], v157 offset:51200
	ds_read_b128 v[204:207], v157 offset:52224
	ds_read_b128 v[208:211], v157 offset:53248
	ds_read_b128 v[212:215], v157 offset:54272
	ds_read_b128 v[216:219], v157 offset:55296
	ds_read_b128 v[220:223], v157 offset:56320
	global_load_lds_dwordx4 v130, s[98:99]
	s_add_i32 m0, s39, 0x2000
	s_add_u32 s50, s50, 0x40080
	s_addc_u32 s51, s51, 0
	s_add_i32 s39, s41, s4
	global_load_lds_dwordx4 v134, s[98:99]
	s_mov_b32 m0, s39
	s_nop 0
	global_load_lds_dwordx4 v130, s[50:51]
	s_add_i32 m0, s39, 0x2000
	s_nop 0
	global_load_lds_dwordx4 v134, s[50:51]
	s_mov_b32 m0, s22
	s_nop 0
	global_load_lds_dwordx4 v128, s[100:101]
	s_mov_b32 m0, s23
	s_nop 0
	global_load_lds_dwordx4 v132, s[100:101]
	s_waitcnt vmcnt(8)
	s_waitcnt lgkmcnt(0)
	s_setprio 1
	s_barrier

; #define PG8_MMA(ai, bj, At, Bt) do { __builtin_amdgcn_s_setprio(1); _Pragma("unroll") for (int m = 0; m < 4; ++m) _Pragma("unroll") for (int n = 0; n < 2; ++n) _Pragma("unroll") for (int k = 0; k < 2; ++k) \
;         acc[ai][bj][m][n] = __builtin_amdgcn_mfma_f32_16x16x32_bf16(Bt[n][k], At[m][k], acc[ai][bj][m][n], 0, 0, 0); __builtin_amdgcn_s_setprio(0); } while (0)
; #define PG8_WAIT_V(n) asm volatile("s_waitcnt vmcnt(" #n ")" ::: "memory")
; #define PG8_WAIT_L(n) asm volatile("s_waitcnt lgkmcnt(" #n ")" ::: "memory")
; #define PG8_BAR __builtin_amdgcn_s_barrier()
; #define PG8_SCHED __builtin_amdgcn_sched_barrier(0)
; template <class Epi>
; __device__ __forceinline__ void gemm_phase(LAS unsigned char* lds, const Gemm g, const StaticOrder& S, const Epi& E) {
;     ...
;             PG8_WAIT_V(8); PG8_WAIT_L(0); PG8_BAR; PG8_MMA(1, 0, At, B0); PG8_MMA(1, 1, At, B1); PG8_BAR; PG8_SCHED;
	v_mfma_f32_16x16x32_bf16 v[60:63], v[144:147], v[192:195], v[60:63]
	v_mfma_f32_16x16x32_bf16 v[56:59], v[162:165], v[192:195], v[56:59]
	v_mfma_f32_16x16x32_bf16 v[44:47], v[144:147], v[200:203], v[44:47]
	v_mfma_f32_16x16x32_bf16 v[40:43], v[162:165], v[200:203], v[40:43]
	v_mfma_f32_16x16x32_bf16 v[28:31], v[144:147], v[208:211], v[28:31]
	v_mfma_f32_16x16x32_bf16 v[24:27], v[162:165], v[208:211], v[24:27]
	v_mfma_f32_16x16x32_bf16 v[12:15], v[144:147], v[216:219], v[12:15]
	v_mfma_f32_16x16x32_bf16 v[8:11], v[162:165], v[216:219], v[8:11]
	v_mfma_f32_16x16x32_bf16 v[60:63], v[148:151], v[196:199], v[60:63]
	v_mfma_f32_16x16x32_bf16 v[56:59], v[166:169], v[196:199], v[56:59]
	v_mfma_f32_16x16x32_bf16 v[44:47], v[148:151], v[204:207], v[44:47]
	v_mfma_f32_16x16x32_bf16 v[40:43], v[166:169], v[204:207], v[40:43]
	v_mfma_f32_16x16x32_bf16 v[28:31], v[148:151], v[212:215], v[28:31]
	v_mfma_f32_16x16x32_bf16 v[24:27], v[166:169], v[212:215], v[24:27]
	v_mfma_f32_16x16x32_bf16 v[12:15], v[148:151], v[220:223], v[12:15]
	v_mfma_f32_16x16x32_bf16 v[8:11], v[166:169], v[220:223], v[8:11]


; #define PG8_MMA(ai, bj, At, Bt) do { __builtin_amdgcn_s_setprio(1); _Pragma("unroll") for (int m = 0; m < 4; ++m) _Pragma("unroll") for (int n = 0; n < 2; ++n) _Pragma("unroll") for (int k = 0; k < 2; ++k) \
;         acc[ai][bj][m][n] = __builtin_amdgcn_mfma_f32_16x16x32_bf16(Bt[n][k], At[m][k], acc[ai][bj][m][n], 0, 0, 0); __builtin_amdgcn_s_setprio(0); } while (0)
; #define PG8_WAIT_V(n) asm volatile("s_waitcnt vmcnt(" #n ")" ::: "memory")
; #define PG8_WAIT_L(n) asm volatile("s_waitcnt lgkmcnt(" #n ")" ::: "memory")
; #define PG8_BAR __builtin_amdgcn_s_barrier()
; #define PG8_SCHED __builtin_amdgcn_sched_barrier(0)
; template <class Epi>
; __device__ __forceinline__ void gemm_phase(LAS unsigned char* lds, const Gemm g, const StaticOrder& S, const Epi& E) {
;     ...
;         for (int t = 0; t < nt; t += 2) {
;     ...
;             PG8_WAIT_V(8); PG8_WAIT_L(0); PG8_BAR; PG8_MMA(1, 0, At, B0); PG8_MMA(1, 1, At, B1); PG8_BAR; PG8_SCHED;
;         }
;         if (wr == 0) PG8_BAR;
	v_mfma_f32_16x16x32_bf16 v[52:55], v[170:173], v[192:195], v[52:55]
	v_mfma_f32_16x16x32_bf16 v[48:51], v[184:187], v[192:195], v[48:51]
	v_mfma_f32_16x16x32_bf16 v[36:39], v[170:173], v[200:203], v[36:39]
	v_mfma_f32_16x16x32_bf16 v[32:35], v[184:187], v[200:203], v[32:35]
	v_mfma_f32_16x16x32_bf16 v[20:23], v[170:173], v[208:211], v[20:23]
	v_mfma_f32_16x16x32_bf16 v[16:19], v[184:187], v[208:211], v[16:19]
	v_mfma_f32_16x16x32_bf16 v[4:7], v[170:173], v[216:219], v[4:7]
	v_mfma_f32_16x16x32_bf16 v[0:3], v[184:187], v[216:219], v[0:3]
	v_mfma_f32_16x16x32_bf16 v[52:55], v[174:177], v[196:199], v[52:55]
	v_mfma_f32_16x16x32_bf16 v[48:51], v[188:191], v[196:199], v[48:51]
	v_mfma_f32_16x16x32_bf16 v[36:39], v[174:177], v[204:207], v[36:39]
	v_mfma_f32_16x16x32_bf16 v[32:35], v[188:191], v[204:207], v[32:35]
	v_mfma_f32_16x16x32_bf16 v[20:23], v[174:177], v[212:215], v[20:23]
	v_mfma_f32_16x16x32_bf16 v[16:19], v[188:191], v[212:215], v[16:19]
	v_mfma_f32_16x16x32_bf16 v[4:7], v[174:177], v[220:223], v[4:7]
	v_mfma_f32_16x16x32_bf16 v[0:3], v[188:191], v[220:223], v[0:3]
	s_setprio 0
	s_barrier
	s_add_i32 s35, s35, 2
	s_add_u32 s48, s48, 0x100
	s_addc_u32 s49, s49, 0
	s_add_u32 s13, s13, 0x100
	s_addc_u32 s34, s34, 0
	s_cmp_gt_u32 s35, 13
	s_cbranch_scc0 .LBB0_1234
	s_and_b64 vcc, exec, s[26:27]
	s_cbranch_vccz .LBB0_1237
	s_barrier

; #define PG8_STAGE(bufoff, gbase, voff) do { _Pragma("unroll") for (int _i = 0; _i < 2; ++_i) \
;         __builtin_amdgcn_global_load_lds((const unsigned*)((const char*)(gbase) + (voff)[_i]), (LAS unsigned*)(lds + (bufoff) + ldsw + _i * 8192), 16, 0, 0); } while (0)
; #define PG8_LDA(dst, b, h) do { _Pragma("unroll") for (int m = 0; m < 4; ++m) _Pragma("unroll") for (int k = 0; k < 2; ++k) dst[m][k] = *(const LAS bf16x8*)(lds + PG8_SA(b, h) + aoff + m * 2048 + k * 1024); } while (0)
; #define PG8_LDB(dst, b, h) do { _Pragma("unroll") for (int n = 0; n < 2; ++n) _Pragma("unroll") for (int k = 0; k < 2; ++k) dst[n][k] = *(const LAS bf16x8*)(lds + PG8_SB(b, h) + boff + n * 2048 + k * 1024); } while (0)
; #define PG8_MMA(ai, bj, At, Bt) do { __builtin_amdgcn_s_setprio(1); _Pragma("unroll") for (int m = 0; m < 4; ++m) _Pragma("unroll") for (int n = 0; n < 2; ++n) _Pragma("unroll") for (int k = 0; k < 2; ++k) \
;         acc[ai][bj][m][n] = __builtin_amdgcn_mfma_f32_16x16x32_bf16(Bt[n][k], At[m][k], acc[ai][bj][m][n], 0, 0, 0); __builtin_amdgcn_s_setprio(0); } while (0)
; #define PG8_WAIT_V(n) asm volatile("s_waitcnt vmcnt(" #n ")" ::: "memory")
; #define PG8_WAIT_L(n) asm volatile("s_waitcnt lgkmcnt(" #n ")" ::: "memory")
; #define PG8_BAR __builtin_amdgcn_s_barrier()
; #define PG8_SCHED __builtin_amdgcn_sched_barrier(0)
; template <class Epi>
; __device__ __forceinline__ void gemm_phase(LAS unsigned char* lds, const Gemm g, const StaticOrder& S, const Epi& E) {
;     ...
;             const char* a2 = last ? nA : cA + ((Epi::HAS_MID && t + 2 >= nt1) ? dA2 : 0) + (size_t)(t + 2) * kstep; const char* b2 = last ? nB : cB + ((Epi::HAS_MID && t + 2 >= nt1) ? dB2 : 0) + (size_t)(t + 2) * kstep;
;             const char* a3 = a2 + kstep; const char* b3 = b2 + kstep;
;             PG8_LDB(B0, 0, 0); PG8_LDB(B1, 0, 1); PG8_SCHED; PG8_LDA(At, 0, 0); PG8_STAGE(PG8_SA(1, 1), a1 + hsA, voffA);
;             PG8_WAIT_V(8); PG8_WAIT_L(0); PG8_BAR; PG8_MMA(0, 0, At, B0); PG8_MMA(0, 1, At, B1); PG8_BAR; PG8_SCHED;
.LBB0_1350:
	ds_read_b128 v[144:147], v155
	ds_read_b128 v[148:151], v155 offset:1024
	ds_read_b128 v[162:165], v155 offset:2048
	ds_read_b128 v[166:169], v155 offset:3072
	ds_read_b128 v[170:173], v156
	ds_read_b128 v[174:177], v156 offset:1024
	ds_read_b128 v[184:187], v156 offset:2048
	ds_read_b128 v[188:191], v156 offset:3072
	s_add_u32 s40, s38, 0xfffc0080
	s_addc_u32 s41, s39, -1
	s_cmp_eq_u32 s48, 12
	s_cselect_b32 s43, s25, s41
	s_cselect_b32 s42, s44, s40
	s_cselect_b32 s41, s15, s47
	s_cselect_b32 s40, s45, s46
	s_add_i32 m0, s17, 0xc000
	ds_read_b128 v[192:195], v157
	ds_read_b128 v[196:199], v157 offset:1024
	ds_read_b128 v[200:203], v157 offset:2048
	ds_read_b128 v[204:207], v157 offset:3072
	ds_read_b128 v[208:211], v157 offset:4096
	ds_read_b128 v[212:215], v157 offset:5120
	ds_read_b128 v[216:219], v157 offset:6144
	ds_read_b128 v[220:223], v157 offset:7168
	global_load_lds_dwordx4 v136, s[38:39]
	s_add_i32 m0, s17, 0xe000
	s_nop 0
	global_load_lds_dwordx4 v138, s[38:39]
	s_waitcnt vmcnt(8)
	s_waitcnt lgkmcnt(0)
	s_setprio 1
	s_barrier

; #define PG8_MMA(ai, bj, At, Bt) do { __builtin_amdgcn_s_setprio(1); _Pragma("unroll") for (int m = 0; m < 4; ++m) _Pragma("unroll") for (int n = 0; n < 2; ++n) _Pragma("unroll") for (int k = 0; k < 2; ++k) \
;         acc[ai][bj][m][n] = __builtin_amdgcn_mfma_f32_16x16x32_bf16(Bt[n][k], At[m][k], acc[ai][bj][m][n], 0, 0, 0); __builtin_amdgcn_s_setprio(0); } while (0)
; #define PG8_WAIT_V(n) asm volatile("s_waitcnt vmcnt(" #n ")" ::: "memory")
; #define PG8_WAIT_L(n) asm volatile("s_waitcnt lgkmcnt(" #n ")" ::: "memory")
; #define PG8_BAR __builtin_amdgcn_s_barrier()
; #define PG8_SCHED __builtin_amdgcn_sched_barrier(0)
; template <class Epi>
; __device__ __forceinline__ void gemm_phase(LAS unsigned char* lds, const Gemm g, const StaticOrder& S, const Epi& E) {
;     ...
;             PG8_WAIT_V(8); PG8_WAIT_L(0); PG8_BAR; PG8_MMA(0, 0, At, B0); PG8_MMA(0, 1, At, B1); PG8_BAR; PG8_SCHED;
	v_mfma_f32_16x16x32_bf16 v[124:127], v[144:147], v[192:195], v[124:127]
	v_mfma_f32_16x16x32_bf16 v[120:123], v[162:165], v[192:195], v[120:123]
	v_mfma_f32_16x16x32_bf16 v[108:111], v[144:147], v[200:203], v[108:111]
	v_mfma_f32_16x16x32_bf16 v[104:107], v[162:165], v[200:203], v[104:107]
	v_mfma_f32_16x16x32_bf16 v[92:95], v[144:147], v[208:211], v[92:95]
	v_mfma_f32_16x16x32_bf16 v[88:91], v[162:165], v[208:211], v[88:91]
	v_mfma_f32_16x16x32_bf16 v[76:79], v[144:147], v[216:219], v[76:79]
	v_mfma_f32_16x16x32_bf16 v[72:75], v[162:165], v[216:219], v[72:75]
	v_mfma_f32_16x16x32_bf16 v[124:127], v[148:151], v[196:199], v[124:127]
	v_mfma_f32_16x16x32_bf16 v[120:123], v[166:169], v[196:199], v[120:123]
	v_mfma_f32_16x16x32_bf16 v[108:111], v[148:151], v[204:207], v[108:111]
	v_mfma_f32_16x16x32_bf16 v[104:107], v[166:169], v[204:207], v[104:107]
	v_mfma_f32_16x16x32_bf16 v[92:95], v[148:151], v[212:215], v[92:95]
	v_mfma_f32_16x16x32_bf16 v[88:91], v[166:169], v[212:215], v[88:91]
	v_mfma_f32_16x16x32_bf16 v[76:79], v[148:151], v[220:223], v[76:79]
	v_mfma_f32_16x16x32_bf16 v[72:75], v[166:169], v[220:223], v[72:75]


; #define PG8_STAGE(bufoff, gbase, voff) do { _Pragma("unroll") for (int _i = 0; _i < 2; ++_i) \
;         __builtin_amdgcn_global_load_lds((const unsigned*)((const char*)(gbase) + (voff)[_i]), (LAS unsigned*)(lds + (bufoff) + ldsw + _i * 8192), 16, 0, 0); } while (0)
; #define PG8_LDA(dst, b, h) do { _Pragma("unroll") for (int m = 0; m < 4; ++m) _Pragma("unroll") for (int k = 0; k < 2; ++k) dst[m][k] = *(const LAS bf16x8*)(lds + PG8_SA(b, h) + aoff + m * 2048 + k * 1024); } while (0)
; #define PG8_MMA(ai, bj, At, Bt) do { __builtin_amdgcn_s_setprio(1); _Pragma("unroll") for (int m = 0; m < 4; ++m) _Pragma("unroll") for (int n = 0; n < 2; ++n) _Pragma("unroll") for (int k = 0; k < 2; ++k) \
;         acc[ai][bj][m][n] = __builtin_amdgcn_mfma_f32_16x16x32_bf16(Bt[n][k], At[m][k], acc[ai][bj][m][n], 0, 0, 0); __builtin_amdgcn_s_setprio(0); } while (0)
; #define PG8_WAIT_V(n) asm volatile("s_waitcnt vmcnt(" #n ")" ::: "memory")
; #define PG8_WAIT_L(n) asm volatile("s_waitcnt lgkmcnt(" #n ")" ::: "memory")
; #define PG8_BAR __builtin_amdgcn_s_barrier()
; #define PG8_SCHED __builtin_amdgcn_sched_barrier(0)
; template <class Epi>
; __device__ __forceinline__ void gemm_phase(LAS unsigned char* lds, const Gemm g, const StaticOrder& S, const Epi& E) {
;     ...
;             PG8_WAIT_V(8); PG8_WAIT_L(0); PG8_BAR; PG8_MMA(0, 0, At, B0); PG8_MMA(0, 1, At, B1); PG8_BAR; PG8_SCHED;
;             PG8_LDA(At, 0, 1); PG8_STAGE(PG8_SB(0, 0), b2, voffB); PG8_STAGE(PG8_SB(0, 1), b2 + hsB, voffB); PG8_STAGE(PG8_SA(0, 0), a2, voffA);
;             PG8_WAIT_V(8); PG8_WAIT_L(0); PG8_BAR; PG8_MMA(1, 0, At, B0); PG8_MMA(1, 1, At, B1); PG8_BAR; PG8_SCHED;
	v_mfma_f32_16x16x32_bf16 v[116:119], v[170:173], v[192:195], v[116:119]
	v_mfma_f32_16x16x32_bf16 v[112:115], v[184:187], v[192:195], v[112:115]
	v_mfma_f32_16x16x32_bf16 v[100:103], v[170:173], v[200:203], v[100:103]
	v_mfma_f32_16x16x32_bf16 v[96:99], v[184:187], v[200:203], v[96:99]
	v_mfma_f32_16x16x32_bf16 v[84:87], v[170:173], v[208:211], v[84:87]
	v_mfma_f32_16x16x32_bf16 v[80:83], v[184:187], v[208:211], v[80:83]
	v_mfma_f32_16x16x32_bf16 v[68:71], v[170:173], v[216:219], v[68:71]
	v_mfma_f32_16x16x32_bf16 v[64:67], v[184:187], v[216:219], v[64:67]
	v_mfma_f32_16x16x32_bf16 v[116:119], v[174:177], v[196:199], v[116:119]
	v_mfma_f32_16x16x32_bf16 v[112:115], v[188:191], v[196:199], v[112:115]
	v_mfma_f32_16x16x32_bf16 v[100:103], v[174:177], v[204:207], v[100:103]
	v_mfma_f32_16x16x32_bf16 v[96:99], v[188:191], v[204:207], v[96:99]
	v_mfma_f32_16x16x32_bf16 v[84:87], v[174:177], v[212:215], v[84:87]
	v_mfma_f32_16x16x32_bf16 v[80:83], v[188:191], v[212:215], v[80:83]
	v_mfma_f32_16x16x32_bf16 v[68:71], v[174:177], v[220:223], v[68:71]
	v_mfma_f32_16x16x32_bf16 v[64:67], v[188:191], v[220:223], v[64:67]
	s_setprio 0
	s_barrier
	s_add_i32 s49, s30, s4
	s_mov_b32 m0, s49
	ds_read_b128 v[192:195], v157 offset:16384
	ds_read_b128 v[196:199], v157 offset:17408
	ds_read_b128 v[200:203], v157 offset:18432
	ds_read_b128 v[204:207], v157 offset:19456
	ds_read_b128 v[208:211], v157 offset:20480
	ds_read_b128 v[212:215], v157 offset:21504
	ds_read_b128 v[216:219], v157 offset:22528
	ds_read_b128 v[220:223], v157 offset:23552
	global_load_lds_dwordx4 v132, s[40:41]
	s_add_i32 m0, s49, 0x2000
	s_add_u32 s50, s40, 0x40000
	s_addc_u32 s51, s41, 0
	s_add_i32 s49, s31, s4
	global_load_lds_dwordx4 v128, s[40:41]
	s_mov_b32 m0, s49
	s_nop 0
	global_load_lds_dwordx4 v132, s[50:51]
	s_add_i32 m0, s49, 0x2000
	s_nop 0
	global_load_lds_dwordx4 v128, s[50:51]
	s_mov_b32 m0, s17
	s_nop 0
	global_load_lds_dwordx4 v134, s[42:43]
	s_mov_b32 m0, s18
	s_nop 0
	global_load_lds_dwordx4 v130, s[42:43]
	s_waitcnt vmcnt(8)
	s_waitcnt lgkmcnt(0)
	s_setprio 1
	s_barrier

; #define PG8_MMA(ai, bj, At, Bt) do { __builtin_amdgcn_s_setprio(1); _Pragma("unroll") for (int m = 0; m < 4; ++m) _Pragma("unroll") for (int n = 0; n < 2; ++n) _Pragma("unroll") for (int k = 0; k < 2; ++k) \
;         acc[ai][bj][m][n] = __builtin_amdgcn_mfma_f32_16x16x32_bf16(Bt[n][k], At[m][k], acc[ai][bj][m][n], 0, 0, 0); __builtin_amdgcn_s_setprio(0); } while (0)
; #define PG8_WAIT_V(n) asm volatile("s_waitcnt vmcnt(" #n ")" ::: "memory")
; #define PG8_WAIT_L(n) asm volatile("s_waitcnt lgkmcnt(" #n ")" ::: "memory")
; #define PG8_BAR __builtin_amdgcn_s_barrier()
; #define PG8_SCHED __builtin_amdgcn_sched_barrier(0)
; template <class Epi>
; __device__ __forceinline__ void gemm_phase(LAS unsigned char* lds, const Gemm g, const StaticOrder& S, const Epi& E) {
;     ...
;             PG8_WAIT_V(8); PG8_WAIT_L(0); PG8_BAR; PG8_MMA(1, 0, At, B0); PG8_MMA(1, 1, At, B1); PG8_BAR; PG8_SCHED;
	v_mfma_f32_16x16x32_bf16 v[60:63], v[144:147], v[192:195], v[60:63]
	v_mfma_f32_16x16x32_bf16 v[56:59], v[162:165], v[192:195], v[56:59]
	v_mfma_f32_16x16x32_bf16 v[44:47], v[144:147], v[200:203], v[44:47]
	v_mfma_f32_16x16x32_bf16 v[40:43], v[162:165], v[200:203], v[40:43]
	v_mfma_f32_16x16x32_bf16 v[28:31], v[144:147], v[208:211], v[28:31]
	v_mfma_f32_16x16x32_bf16 v[24:27], v[162:165], v[208:211], v[24:27]
	v_mfma_f32_16x16x32_bf16 v[12:15], v[144:147], v[216:219], v[12:15]
	v_mfma_f32_16x16x32_bf16 v[8:11], v[162:165], v[216:219], v[8:11]
	v_mfma_f32_16x16x32_bf16 v[60:63], v[148:151], v[196:199], v[60:63]
	v_mfma_f32_16x16x32_bf16 v[56:59], v[166:169], v[196:199], v[56:59]
	v_mfma_f32_16x16x32_bf16 v[44:47], v[148:151], v[204:207], v[44:47]
	v_mfma_f32_16x16x32_bf16 v[40:43], v[166:169], v[204:207], v[40:43]
	v_mfma_f32_16x16x32_bf16 v[28:31], v[148:151], v[212:215], v[28:31]
	v_mfma_f32_16x16x32_bf16 v[24:27], v[166:169], v[212:215], v[24:27]
	v_mfma_f32_16x16x32_bf16 v[12:15], v[148:151], v[220:223], v[12:15]
	v_mfma_f32_16x16x32_bf16 v[8:11], v[166:169], v[220:223], v[8:11]


; #define PG8_STAGE(bufoff, gbase, voff) do { _Pragma("unroll") for (int _i = 0; _i < 2; ++_i) \
;         __builtin_amdgcn_global_load_lds((const unsigned*)((const char*)(gbase) + (voff)[_i]), (LAS unsigned*)(lds + (bufoff) + ldsw + _i * 8192), 16, 0, 0); } while (0)
; #define PG8_LDA(dst, b, h) do { _Pragma("unroll") for (int m = 0; m < 4; ++m) _Pragma("unroll") for (int k = 0; k < 2; ++k) dst[m][k] = *(const LAS bf16x8*)(lds + PG8_SA(b, h) + aoff + m * 2048 + k * 1024); } while (0)
; #define PG8_LDB(dst, b, h) do { _Pragma("unroll") for (int n = 0; n < 2; ++n) _Pragma("unroll") for (int k = 0; k < 2; ++k) dst[n][k] = *(const LAS bf16x8*)(lds + PG8_SB(b, h) + boff + n * 2048 + k * 1024); } while (0)
; #define PG8_MMA(ai, bj, At, Bt) do { __builtin_amdgcn_s_setprio(1); _Pragma("unroll") for (int m = 0; m < 4; ++m) _Pragma("unroll") for (int n = 0; n < 2; ++n) _Pragma("unroll") for (int k = 0; k < 2; ++k) \
;         acc[ai][bj][m][n] = __builtin_amdgcn_mfma_f32_16x16x32_bf16(Bt[n][k], At[m][k], acc[ai][bj][m][n], 0, 0, 0); __builtin_amdgcn_s_setprio(0); } while (0)
; #define PG8_WAIT_V(n) asm volatile("s_waitcnt vmcnt(" #n ")" ::: "memory")
; #define PG8_WAIT_L(n) asm volatile("s_waitcnt lgkmcnt(" #n ")" ::: "memory")
; #define PG8_BAR __builtin_amdgcn_s_barrier()
; #define PG8_SCHED __builtin_amdgcn_sched_barrier(0)
; template <class Epi>
; __device__ __forceinline__ void gemm_phase(LAS unsigned char* lds, const Gemm g, const StaticOrder& S, const Epi& E) {
;     ...
;             PG8_WAIT_V(8); PG8_WAIT_L(0); PG8_BAR; PG8_MMA(1, 0, At, B0); PG8_MMA(1, 1, At, B1); PG8_BAR; PG8_SCHED;
;             PG8_LDB(B0, 1, 0); PG8_LDB(B1, 1, 1); PG8_SCHED; PG8_LDA(At, 1, 0); PG8_STAGE(PG8_SA(0, 1), a2 + hsA, voffA);
;             PG8_WAIT_V(8); PG8_WAIT_L(0); PG8_BAR; PG8_MMA(0, 0, At, B0); PG8_MMA(0, 1, At, B1); PG8_BAR; PG8_SCHED;
	v_mfma_f32_16x16x32_bf16 v[52:55], v[170:173], v[192:195], v[52:55]
	v_mfma_f32_16x16x32_bf16 v[48:51], v[184:187], v[192:195], v[48:51]
	v_mfma_f32_16x16x32_bf16 v[36:39], v[170:173], v[200:203], v[36:39]
	v_mfma_f32_16x16x32_bf16 v[32:35], v[184:187], v[200:203], v[32:35]
	v_mfma_f32_16x16x32_bf16 v[20:23], v[170:173], v[208:211], v[20:23]
	v_mfma_f32_16x16x32_bf16 v[16:19], v[184:187], v[208:211], v[16:19]
	v_mfma_f32_16x16x32_bf16 v[4:7], v[170:173], v[216:219], v[4:7]
	v_mfma_f32_16x16x32_bf16 v[0:3], v[184:187], v[216:219], v[0:3]
	v_mfma_f32_16x16x32_bf16 v[52:55], v[174:177], v[196:199], v[52:55]
	v_mfma_f32_16x16x32_bf16 v[48:51], v[188:191], v[196:199], v[48:51]
	v_mfma_f32_16x16x32_bf16 v[36:39], v[174:177], v[204:207], v[36:39]
	v_mfma_f32_16x16x32_bf16 v[32:35], v[188:191], v[204:207], v[32:35]
	v_mfma_f32_16x16x32_bf16 v[20:23], v[174:177], v[212:215], v[20:23]
	v_mfma_f32_16x16x32_bf16 v[16:19], v[188:191], v[212:215], v[16:19]
	v_mfma_f32_16x16x32_bf16 v[4:7], v[174:177], v[220:223], v[4:7]
	v_mfma_f32_16x16x32_bf16 v[0:3], v[188:191], v[220:223], v[0:3]
	s_setprio 0
	s_barrier
	s_add_i32 s49, 0, 0x18000
	v_add_u32_e32 v159, s49, v153
	s_add_i32 s50, 0, 0x1c000
	ds_read_b128 v[144:147], v159
	ds_read_b128 v[148:151], v159 offset:1024
	ds_read_b128 v[162:165], v159 offset:2048
	ds_read_b128 v[166:169], v159 offset:3072
	v_add_u32_e32 v159, s50, v153
	ds_read_b128 v[170:173], v159
	ds_read_b128 v[174:177], v159 offset:1024
	ds_read_b128 v[184:187], v159 offset:2048
	ds_read_b128 v[188:191], v159 offset:3072
	s_add_u32 s42, s42, 0x40000
	s_addc_u32 s43, s43, 0
	s_mov_b32 m0, s19
	ds_read_b128 v[192:195], v157 offset:32768
	ds_read_b128 v[196:199], v157 offset:33792
	ds_read_b128 v[200:203], v157 offset:34816
	ds_read_b128 v[204:207], v157 offset:35840
	ds_read_b128 v[208:211], v157 offset:36864
	ds_read_b128 v[212:215], v157 offset:37888
	ds_read_b128 v[216:219], v157 offset:38912
	ds_read_b128 v[220:223], v157 offset:39936
	global_load_lds_dwordx4 v134, s[42:43]
	s_mov_b32 m0, s22
	s_nop 0
	global_load_lds_dwordx4 v130, s[42:43]
	s_waitcnt vmcnt(8)
	s_waitcnt lgkmcnt(0)
	s_setprio 1
	s_barrier

; #define PG8_MMA(ai, bj, At, Bt) do { __builtin_amdgcn_s_setprio(1); _Pragma("unroll") for (int m = 0; m < 4; ++m) _Pragma("unroll") for (int n = 0; n < 2; ++n) _Pragma("unroll") for (int k = 0; k < 2; ++k) \
;         acc[ai][bj][m][n] = __builtin_amdgcn_mfma_f32_16x16x32_bf16(Bt[n][k], At[m][k], acc[ai][bj][m][n], 0, 0, 0); __builtin_amdgcn_s_setprio(0); } while (0)
; #define PG8_WAIT_V(n) asm volatile("s_waitcnt vmcnt(" #n ")" ::: "memory")
; #define PG8_WAIT_L(n) asm volatile("s_waitcnt lgkmcnt(" #n ")" ::: "memory")
; #define PG8_BAR __builtin_amdgcn_s_barrier()
; #define PG8_SCHED __builtin_amdgcn_sched_barrier(0)
; template <class Epi>
; __device__ __forceinline__ void gemm_phase(LAS unsigned char* lds, const Gemm g, const StaticOrder& S, const Epi& E) {
;     ...
;             PG8_WAIT_V(8); PG8_WAIT_L(0); PG8_BAR; PG8_MMA(0, 0, At, B0); PG8_MMA(0, 1, At, B1); PG8_BAR; PG8_SCHED;
	v_mfma_f32_16x16x32_bf16 v[124:127], v[144:147], v[192:195], v[124:127]
	v_mfma_f32_16x16x32_bf16 v[120:123], v[162:165], v[192:195], v[120:123]
	v_mfma_f32_16x16x32_bf16 v[108:111], v[144:147], v[200:203], v[108:111]
	v_mfma_f32_16x16x32_bf16 v[104:107], v[162:165], v[200:203], v[104:107]
	v_mfma_f32_16x16x32_bf16 v[92:95], v[144:147], v[208:211], v[92:95]
	v_mfma_f32_16x16x32_bf16 v[88:91], v[162:165], v[208:211], v[88:91]
	v_mfma_f32_16x16x32_bf16 v[76:79], v[144:147], v[216:219], v[76:79]
	v_mfma_f32_16x16x32_bf16 v[72:75], v[162:165], v[216:219], v[72:75]
	v_mfma_f32_16x16x32_bf16 v[124:127], v[148:151], v[196:199], v[124:127]
	v_mfma_f32_16x16x32_bf16 v[120:123], v[166:169], v[196:199], v[120:123]
	v_mfma_f32_16x16x32_bf16 v[108:111], v[148:151], v[204:207], v[108:111]
	v_mfma_f32_16x16x32_bf16 v[104:107], v[166:169], v[204:207], v[104:107]
	v_mfma_f32_16x16x32_bf16 v[92:95], v[148:151], v[212:215], v[92:95]
	v_mfma_f32_16x16x32_bf16 v[88:91], v[166:169], v[212:215], v[88:91]
	v_mfma_f32_16x16x32_bf16 v[76:79], v[148:151], v[220:223], v[76:79]
	v_mfma_f32_16x16x32_bf16 v[72:75], v[166:169], v[220:223], v[72:75]


; #define PG8_STAGE(bufoff, gbase, voff) do { _Pragma("unroll") for (int _i = 0; _i < 2; ++_i) \
;         __builtin_amdgcn_global_load_lds((const unsigned*)((const char*)(gbase) + (voff)[_i]), (LAS unsigned*)(lds + (bufoff) + ldsw + _i * 8192), 16, 0, 0); } while (0)
; #define PG8_LDA(dst, b, h) do { _Pragma("unroll") for (int m = 0; m < 4; ++m) _Pragma("unroll") for (int k = 0; k < 2; ++k) dst[m][k] = *(const LAS bf16x8*)(lds + PG8_SA(b, h) + aoff + m * 2048 + k * 1024); } while (0)
; #define PG8_MMA(ai, bj, At, Bt) do { __builtin_amdgcn_s_setprio(1); _Pragma("unroll") for (int m = 0; m < 4; ++m) _Pragma("unroll") for (int n = 0; n < 2; ++n) _Pragma("unroll") for (int k = 0; k < 2; ++k) \
;         acc[ai][bj][m][n] = __builtin_amdgcn_mfma_f32_16x16x32_bf16(Bt[n][k], At[m][k], acc[ai][bj][m][n], 0, 0, 0); __builtin_amdgcn_s_setprio(0); } while (0)
; #define PG8_WAIT_V(n) asm volatile("s_waitcnt vmcnt(" #n ")" ::: "memory")
; #define PG8_WAIT_L(n) asm volatile("s_waitcnt lgkmcnt(" #n ")" ::: "memory")
; #define PG8_BAR __builtin_amdgcn_s_barrier()
; #define PG8_SCHED __builtin_amdgcn_sched_barrier(0)
; template <class Epi>
; __device__ __forceinline__ void gemm_phase(LAS unsigned char* lds, const Gemm g, const StaticOrder& S, const Epi& E) {
;     ...
;             PG8_WAIT_V(8); PG8_WAIT_L(0); PG8_BAR; PG8_MMA(0, 0, At, B0); PG8_MMA(0, 1, At, B1); PG8_BAR; PG8_SCHED;
;             PG8_LDA(At, 1, 1); PG8_STAGE(PG8_SB(1, 0), b3, voffB); PG8_STAGE(PG8_SB(1, 1), b3 + hsB, voffB); PG8_STAGE(PG8_SA(1, 0), a3, voffA);
;             PG8_WAIT_V(8); PG8_WAIT_L(0); PG8_BAR; PG8_MMA(1, 0, At, B0); PG8_MMA(1, 1, At, B1); PG8_BAR; PG8_SCHED;
	v_mfma_f32_16x16x32_bf16 v[116:119], v[170:173], v[192:195], v[116:119]
	v_mfma_f32_16x16x32_bf16 v[112:115], v[184:187], v[192:195], v[112:115]
	v_mfma_f32_16x16x32_bf16 v[100:103], v[170:173], v[200:203], v[100:103]
	v_mfma_f32_16x16x32_bf16 v[96:99], v[184:187], v[200:203], v[96:99]
	v_mfma_f32_16x16x32_bf16 v[84:87], v[170:173], v[208:211], v[84:87]
	v_mfma_f32_16x16x32_bf16 v[80:83], v[184:187], v[208:211], v[80:83]
	v_mfma_f32_16x16x32_bf16 v[68:71], v[170:173], v[216:219], v[68:71]
	v_mfma_f32_16x16x32_bf16 v[64:67], v[184:187], v[216:219], v[64:67]
	v_mfma_f32_16x16x32_bf16 v[116:119], v[174:177], v[196:199], v[116:119]
	v_mfma_f32_16x16x32_bf16 v[112:115], v[188:191], v[196:199], v[112:115]
	v_mfma_f32_16x16x32_bf16 v[100:103], v[174:177], v[204:207], v[100:103]
	v_mfma_f32_16x16x32_bf16 v[96:99], v[188:191], v[204:207], v[96:99]
	v_mfma_f32_16x16x32_bf16 v[84:87], v[174:177], v[212:215], v[84:87]
	v_mfma_f32_16x16x32_bf16 v[80:83], v[188:191], v[212:215], v[80:83]
	v_mfma_f32_16x16x32_bf16 v[68:71], v[174:177], v[220:223], v[68:71]
	v_mfma_f32_16x16x32_bf16 v[64:67], v[188:191], v[220:223], v[64:67]
	s_setprio 0
	s_barrier
	s_add_u32 s98, s40, 0x80
	s_addc_u32 s99, s41, 0
	s_add_u32 s100, s42, 0xfffc0080
	s_addc_u32 s101, s43, -1
	s_add_i32 s42, s49, s4
	s_mov_b32 m0, s42
	ds_read_b128 v[192:195], v157 offset:49152
	ds_read_b128 v[196:199], v157 offset:50176
	ds_read_b128 v[200:203], v157 offset:51200
	ds_read_b128 v[204:207], v157 offset:52224
	ds_read_b128 v[208:211], v157 offset:53248
	ds_read_b128 v[212:215], v157 offset:54272
	ds_read_b128 v[216:219], v157 offset:55296
	ds_read_b128 v[220:223], v157 offset:56320
	global_load_lds_dwordx4 v132, s[98:99]
	s_add_i32 m0, s42, 0x2000
	s_add_u32 s40, s40, 0x40080
	s_addc_u32 s41, s41, 0
	s_add_i32 s42, s50, s4
	global_load_lds_dwordx4 v128, s[98:99]
	s_mov_b32 m0, s42
	s_nop 0
	global_load_lds_dwordx4 v132, s[40:41]
	s_add_i32 m0, s42, 0x2000
	s_nop 0
	global_load_lds_dwordx4 v128, s[40:41]
	s_mov_b32 m0, s0
	s_nop 0
	global_load_lds_dwordx4 v134, s[100:101]
	s_mov_b32 m0, s1
	s_nop 0
	global_load_lds_dwordx4 v130, s[100:101]
	s_waitcnt vmcnt(8)
	s_waitcnt lgkmcnt(0)
	s_setprio 1
	s_barrier

; #define PG8_MMA(ai, bj, At, Bt) do { __builtin_amdgcn_s_setprio(1); _Pragma("unroll") for (int m = 0; m < 4; ++m) _Pragma("unroll") for (int n = 0; n < 2; ++n) _Pragma("unroll") for (int k = 0; k < 2; ++k) \
;         acc[ai][bj][m][n] = __builtin_amdgcn_mfma_f32_16x16x32_bf16(Bt[n][k], At[m][k], acc[ai][bj][m][n], 0, 0, 0); __builtin_amdgcn_s_setprio(0); } while (0)
; #define PG8_WAIT_V(n) asm volatile("s_waitcnt vmcnt(" #n ")" ::: "memory")
; #define PG8_WAIT_L(n) asm volatile("s_waitcnt lgkmcnt(" #n ")" ::: "memory")
; #define PG8_BAR __builtin_amdgcn_s_barrier()
; #define PG8_SCHED __builtin_amdgcn_sched_barrier(0)
; template <class Epi>
; __device__ __forceinline__ void gemm_phase(LAS unsigned char* lds, const Gemm g, const StaticOrder& S, const Epi& E) {
;     ...
;             PG8_WAIT_V(8); PG8_WAIT_L(0); PG8_BAR; PG8_MMA(1, 0, At, B0); PG8_MMA(1, 1, At, B1); PG8_BAR; PG8_SCHED;
	v_mfma_f32_16x16x32_bf16 v[60:63], v[144:147], v[192:195], v[60:63]
	v_mfma_f32_16x16x32_bf16 v[56:59], v[162:165], v[192:195], v[56:59]
	v_mfma_f32_16x16x32_bf16 v[44:47], v[144:147], v[200:203], v[44:47]
	v_mfma_f32_16x16x32_bf16 v[40:43], v[162:165], v[200:203], v[40:43]
	v_mfma_f32_16x16x32_bf16 v[28:31], v[144:147], v[208:211], v[28:31]
	v_mfma_f32_16x16x32_bf16 v[24:27], v[162:165], v[208:211], v[24:27]
	v_mfma_f32_16x16x32_bf16 v[12:15], v[144:147], v[216:219], v[12:15]
	v_mfma_f32_16x16x32_bf16 v[8:11], v[162:165], v[216:219], v[8:11]
	v_mfma_f32_16x16x32_bf16 v[60:63], v[148:151], v[196:199], v[60:63]
	v_mfma_f32_16x16x32_bf16 v[56:59], v[166:169], v[196:199], v[56:59]
	v_mfma_f32_16x16x32_bf16 v[44:47], v[148:151], v[204:207], v[44:47]
	v_mfma_f32_16x16x32_bf16 v[40:43], v[166:169], v[204:207], v[40:43]
	v_mfma_f32_16x16x32_bf16 v[28:31], v[148:151], v[212:215], v[28:31]
	v_mfma_f32_16x16x32_bf16 v[24:27], v[166:169], v[212:215], v[24:27]
	v_mfma_f32_16x16x32_bf16 v[12:15], v[148:151], v[220:223], v[12:15]
	v_mfma_f32_16x16x32_bf16 v[8:11], v[166:169], v[220:223], v[8:11]


; #define PG8_MMA(ai, bj, At, Bt) do { __builtin_amdgcn_s_setprio(1); _Pragma("unroll") for (int m = 0; m < 4; ++m) _Pragma("unroll") for (int n = 0; n < 2; ++n) _Pragma("unroll") for (int k = 0; k < 2; ++k) \
;         acc[ai][bj][m][n] = __builtin_amdgcn_mfma_f32_16x16x32_bf16(Bt[n][k], At[m][k], acc[ai][bj][m][n], 0, 0, 0); __builtin_amdgcn_s_setprio(0); } while (0)
; #define PG8_WAIT_V(n) asm volatile("s_waitcnt vmcnt(" #n ")" ::: "memory")
; #define PG8_WAIT_L(n) asm volatile("s_waitcnt lgkmcnt(" #n ")" ::: "memory")
; #define PG8_BAR __builtin_amdgcn_s_barrier()
; #define PG8_SCHED __builtin_amdgcn_sched_barrier(0)
; template <class Epi>
; __device__ __forceinline__ void gemm_phase(LAS unsigned char* lds, const Gemm g, const StaticOrder& S, const Epi& E) {
;     ...
;             PG8_WAIT_V(8); PG8_WAIT_L(0); PG8_BAR; PG8_MMA(1, 0, At, B0); PG8_MMA(1, 1, At, B1); PG8_BAR; PG8_SCHED;
;         }
;         if (wr == 0) PG8_BAR;
	v_mfma_f32_16x16x32_bf16 v[52:55], v[170:173], v[192:195], v[52:55]
	v_mfma_f32_16x16x32_bf16 v[48:51], v[184:187], v[192:195], v[48:51]
	v_mfma_f32_16x16x32_bf16 v[36:39], v[170:173], v[200:203], v[36:39]
	v_mfma_f32_16x16x32_bf16 v[32:35], v[184:187], v[200:203], v[32:35]
	v_mfma_f32_16x16x32_bf16 v[20:23], v[170:173], v[208:211], v[20:23]
	v_mfma_f32_16x16x32_bf16 v[16:19], v[184:187], v[208:211], v[16:19]
	v_mfma_f32_16x16x32_bf16 v[4:7], v[170:173], v[216:219], v[4:7]
	v_mfma_f32_16x16x32_bf16 v[0:3], v[184:187], v[216:219], v[0:3]
	v_mfma_f32_16x16x32_bf16 v[52:55], v[174:177], v[196:199], v[52:55]
	v_mfma_f32_16x16x32_bf16 v[48:51], v[188:191], v[196:199], v[48:51]
	v_mfma_f32_16x16x32_bf16 v[36:39], v[174:177], v[204:207], v[36:39]
	v_mfma_f32_16x16x32_bf16 v[32:35], v[188:191], v[204:207], v[32:35]
	v_mfma_f32_16x16x32_bf16 v[20:23], v[174:177], v[212:215], v[20:23]
	v_mfma_f32_16x16x32_bf16 v[16:19], v[188:191], v[212:215], v[16:19]
	v_mfma_f32_16x16x32_bf16 v[4:7], v[174:177], v[220:223], v[4:7]
	v_mfma_f32_16x16x32_bf16 v[0:3], v[188:191], v[220:223], v[0:3]
	s_setprio 0
	s_barrier
	s_add_i32 s48, s48, 2
	s_add_u32 s38, s38, 0x100
	s_addc_u32 s39, s39, 0
	s_add_u32 s46, s46, 0x100
	s_addc_u32 s47, s47, 0
	s_cmp_gt_u32 s48, 13
	s_cbranch_scc0 .LBB0_1350
	s_and_b64 vcc, exec, s[12:13]
	s_cbranch_vccz .LBB0_1353
	s_barrier

; #define PG8_STAGE(bufoff, gbase, voff) do { _Pragma("unroll") for (int _i = 0; _i < 2; ++_i) \
;         __builtin_amdgcn_global_load_lds((const unsigned*)((const char*)(gbase) + (voff)[_i]), (LAS unsigned*)(lds + (bufoff) + ldsw + _i * 8192), 16, 0, 0); } while (0)
; #define PG8_LDA(dst, b, h) do { _Pragma("unroll") for (int m = 0; m < 4; ++m) _Pragma("unroll") for (int k = 0; k < 2; ++k) dst[m][k] = *(const LAS bf16x8*)(lds + PG8_SA(b, h) + aoff + m * 2048 + k * 1024); } while (0)
; #define PG8_LDB(dst, b, h) do { _Pragma("unroll") for (int n = 0; n < 2; ++n) _Pragma("unroll") for (int k = 0; k < 2; ++k) dst[n][k] = *(const LAS bf16x8*)(lds + PG8_SB(b, h) + boff + n * 2048 + k * 1024); } while (0)
; #define PG8_MMA(ai, bj, At, Bt) do { __builtin_amdgcn_s_setprio(1); _Pragma("unroll") for (int m = 0; m < 4; ++m) _Pragma("unroll") for (int n = 0; n < 2; ++n) _Pragma("unroll") for (int k = 0; k < 2; ++k) \
;         acc[ai][bj][m][n] = __builtin_amdgcn_mfma_f32_16x16x32_bf16(Bt[n][k], At[m][k], acc[ai][bj][m][n], 0, 0, 0); __builtin_amdgcn_s_setprio(0); } while (0)
; #define PG8_WAIT_V(n) asm volatile("s_waitcnt vmcnt(" #n ")" ::: "memory")
; #define PG8_WAIT_L(n) asm volatile("s_waitcnt lgkmcnt(" #n ")" ::: "memory")
; #define PG8_BAR __builtin_amdgcn_s_barrier()
; #define PG8_SCHED __builtin_amdgcn_sched_barrier(0)
; template <class Epi>
; __device__ __forceinline__ void gemm_phase(LAS unsigned char* lds, const Gemm g, const StaticOrder& S, const Epi& E) {
;     ...
;         for (int t = 0; t < nt; t += 2) {
;             const bool last = (t == nt - 2);
;             if constexpr (Epi::HAS_MID) { if (t == nt1) E.mid(acc, cur, wr, wc, fr, fq); }
;             const char* a1 = cA + ((Epi::HAS_MID && t >= nt1) ? dA2 : 0) + (size_t)(t + 1) * kstep;
;             const char* a2 = last ? nA : cA + ((Epi::HAS_MID && t + 2 >= nt1) ? dA2 : 0) + (size_t)(t + 2) * kstep; const char* b2 = last ? nB : cB + ((Epi::HAS_MID && t + 2 >= nt1) ? dB2 : 0) + (size_t)(t + 2) * kstep;
;             const char* a3 = a2 + kstep; const char* b3 = b2 + kstep;
;             PG8_LDB(B0, 0, 0); PG8_LDB(B1, 0, 1); PG8_SCHED; PG8_LDA(At, 0, 0); PG8_STAGE(PG8_SA(1, 1), a1 + hsA, voffA);
;             PG8_WAIT_V(8); PG8_WAIT_L(0); PG8_BAR; PG8_MMA(0, 0, At, B0); PG8_MMA(0, 1, At, B1); PG8_BAR; PG8_SCHED;
.LBB0_1433:
	ds_read_b128 v[144:147], v202
	ds_read_b128 v[148:151], v202 offset:1024
	ds_read_b128 v[152:155], v202 offset:2048
	ds_read_b128 v[156:159], v202 offset:3072
	ds_read_b128 v[160:163], v203
	ds_read_b128 v[164:167], v203 offset:1024
	ds_read_b128 v[168:171], v203 offset:2048
	ds_read_b128 v[172:175], v203 offset:3072
	s_add_u32 s34, s26, 0x100
	s_addc_u32 s35, s27, 0
	s_cmp_eq_u32 s51, 40
	s_cselect_b32 s39, s1, s35
	s_cselect_b32 s38, s0, s34
	s_cselect_b32 s37, s23, s50
	s_cselect_b32 s36, s22, s25
	s_add_i32 m0, s17, 0xc000
	ds_read_b128 v[216:219], v204
	ds_read_b128 v[220:223], v204 offset:1024
	ds_read_b128 v[224:227], v204 offset:2048
	ds_read_b128 v[228:231], v204 offset:3072
	ds_read_b128 v[232:235], v204 offset:4096
	ds_read_b128 v[236:239], v204 offset:5120
	ds_read_b128 v[240:243], v204 offset:6144
	ds_read_b128 v[244:247], v204 offset:7168
	global_load_lds_dwordx4 v136, s[26:27]
	s_add_i32 m0, s17, 0xe000
	s_nop 0
	global_load_lds_dwordx4 v138, s[26:27]
	s_waitcnt vmcnt(8)
	s_waitcnt lgkmcnt(0)
	s_setprio 1
	s_barrier

; #define PG8_MMA(ai, bj, At, Bt) do { __builtin_amdgcn_s_setprio(1); _Pragma("unroll") for (int m = 0; m < 4; ++m) _Pragma("unroll") for (int n = 0; n < 2; ++n) _Pragma("unroll") for (int k = 0; k < 2; ++k) \
;         acc[ai][bj][m][n] = __builtin_amdgcn_mfma_f32_16x16x32_bf16(Bt[n][k], At[m][k], acc[ai][bj][m][n], 0, 0, 0); __builtin_amdgcn_s_setprio(0); } while (0)
; #define PG8_WAIT_V(n) asm volatile("s_waitcnt vmcnt(" #n ")" ::: "memory")
; #define PG8_WAIT_L(n) asm volatile("s_waitcnt lgkmcnt(" #n ")" ::: "memory")
; #define PG8_BAR __builtin_amdgcn_s_barrier()
; #define PG8_SCHED __builtin_amdgcn_sched_barrier(0)
; template <class Epi>
; __device__ __forceinline__ void gemm_phase(LAS unsigned char* lds, const Gemm g, const StaticOrder& S, const Epi& E) {
;     ...
;             PG8_WAIT_V(8); PG8_WAIT_L(0); PG8_BAR; PG8_MMA(0, 0, At, B0); PG8_MMA(0, 1, At, B1); PG8_BAR; PG8_SCHED;
	v_mfma_f32_16x16x32_bf16 v[124:127], v[144:147], v[216:219], v[124:127]
	v_mfma_f32_16x16x32_bf16 v[120:123], v[152:155], v[216:219], v[120:123]
	v_mfma_f32_16x16x32_bf16 v[108:111], v[144:147], v[224:227], v[108:111]
	v_mfma_f32_16x16x32_bf16 v[104:107], v[152:155], v[224:227], v[104:107]
	v_mfma_f32_16x16x32_bf16 v[92:95], v[144:147], v[232:235], v[92:95]
	v_mfma_f32_16x16x32_bf16 v[88:91], v[152:155], v[232:235], v[88:91]
	v_mfma_f32_16x16x32_bf16 v[76:79], v[144:147], v[240:243], v[76:79]
	v_mfma_f32_16x16x32_bf16 v[72:75], v[152:155], v[240:243], v[72:75]
	v_mfma_f32_16x16x32_bf16 v[124:127], v[148:151], v[220:223], v[124:127]
	v_mfma_f32_16x16x32_bf16 v[120:123], v[156:159], v[220:223], v[120:123]
	v_mfma_f32_16x16x32_bf16 v[108:111], v[148:151], v[228:231], v[108:111]
	v_mfma_f32_16x16x32_bf16 v[104:107], v[156:159], v[228:231], v[104:107]
	v_mfma_f32_16x16x32_bf16 v[92:95], v[148:151], v[236:239], v[92:95]
	v_mfma_f32_16x16x32_bf16 v[88:91], v[156:159], v[236:239], v[88:91]
	v_mfma_f32_16x16x32_bf16 v[76:79], v[148:151], v[244:247], v[76:79]
	v_mfma_f32_16x16x32_bf16 v[72:75], v[156:159], v[244:247], v[72:75]


; #define PG8_STAGE(bufoff, gbase, voff) do { _Pragma("unroll") for (int _i = 0; _i < 2; ++_i) \
;         __builtin_amdgcn_global_load_lds((const unsigned*)((const char*)(gbase) + (voff)[_i]), (LAS unsigned*)(lds + (bufoff) + ldsw + _i * 8192), 16, 0, 0); } while (0)
; #define PG8_LDA(dst, b, h) do { _Pragma("unroll") for (int m = 0; m < 4; ++m) _Pragma("unroll") for (int k = 0; k < 2; ++k) dst[m][k] = *(const LAS bf16x8*)(lds + PG8_SA(b, h) + aoff + m * 2048 + k * 1024); } while (0)
; #define PG8_MMA(ai, bj, At, Bt) do { __builtin_amdgcn_s_setprio(1); _Pragma("unroll") for (int m = 0; m < 4; ++m) _Pragma("unroll") for (int n = 0; n < 2; ++n) _Pragma("unroll") for (int k = 0; k < 2; ++k) \
;         acc[ai][bj][m][n] = __builtin_amdgcn_mfma_f32_16x16x32_bf16(Bt[n][k], At[m][k], acc[ai][bj][m][n], 0, 0, 0); __builtin_amdgcn_s_setprio(0); } while (0)
; #define PG8_WAIT_V(n) asm volatile("s_waitcnt vmcnt(" #n ")" ::: "memory")
; #define PG8_WAIT_L(n) asm volatile("s_waitcnt lgkmcnt(" #n ")" ::: "memory")
; #define PG8_BAR __builtin_amdgcn_s_barrier()
; #define PG8_SCHED __builtin_amdgcn_sched_barrier(0)
; template <class Epi>
; __device__ __forceinline__ void gemm_phase(LAS unsigned char* lds, const Gemm g, const StaticOrder& S, const Epi& E) {
;     ...
;             PG8_WAIT_V(8); PG8_WAIT_L(0); PG8_BAR; PG8_MMA(0, 0, At, B0); PG8_MMA(0, 1, At, B1); PG8_BAR; PG8_SCHED;
;             PG8_LDA(At, 0, 1); PG8_STAGE(PG8_SB(0, 0), b2, voffB); PG8_STAGE(PG8_SB(0, 1), b2 + hsB, voffB); PG8_STAGE(PG8_SA(0, 0), a2, voffA);
;             PG8_WAIT_V(8); PG8_WAIT_L(0); PG8_BAR; PG8_MMA(1, 0, At, B0); PG8_MMA(1, 1, At, B1); PG8_BAR; PG8_SCHED;
	v_mfma_f32_16x16x32_bf16 v[116:119], v[160:163], v[216:219], v[116:119]
	v_mfma_f32_16x16x32_bf16 v[112:115], v[168:171], v[216:219], v[112:115]
	v_mfma_f32_16x16x32_bf16 v[100:103], v[160:163], v[224:227], v[100:103]
	v_mfma_f32_16x16x32_bf16 v[96:99], v[168:171], v[224:227], v[96:99]
	v_mfma_f32_16x16x32_bf16 v[84:87], v[160:163], v[232:235], v[84:87]
	v_mfma_f32_16x16x32_bf16 v[80:83], v[168:171], v[232:235], v[80:83]
	v_mfma_f32_16x16x32_bf16 v[68:71], v[160:163], v[240:243], v[68:71]
	v_mfma_f32_16x16x32_bf16 v[64:67], v[168:171], v[240:243], v[64:67]
	v_mfma_f32_16x16x32_bf16 v[116:119], v[164:167], v[220:223], v[116:119]
	v_mfma_f32_16x16x32_bf16 v[112:115], v[172:175], v[220:223], v[112:115]
	v_mfma_f32_16x16x32_bf16 v[100:103], v[164:167], v[228:231], v[100:103]
	v_mfma_f32_16x16x32_bf16 v[96:99], v[172:175], v[228:231], v[96:99]
	v_mfma_f32_16x16x32_bf16 v[84:87], v[164:167], v[236:239], v[84:87]
	v_mfma_f32_16x16x32_bf16 v[80:83], v[172:175], v[236:239], v[80:83]
	v_mfma_f32_16x16x32_bf16 v[68:71], v[164:167], v[244:247], v[68:71]
	v_mfma_f32_16x16x32_bf16 v[64:67], v[172:175], v[244:247], v[64:67]
	s_setprio 0
	s_barrier
	s_add_i32 s26, s45, s16
	s_mov_b32 m0, s26
	ds_read_b128 v[216:219], v204 offset:16384
	ds_read_b128 v[220:223], v204 offset:17408
	ds_read_b128 v[224:227], v204 offset:18432
	ds_read_b128 v[228:231], v204 offset:19456
	ds_read_b128 v[232:235], v204 offset:20480
	ds_read_b128 v[236:239], v204 offset:21504
	ds_read_b128 v[240:243], v204 offset:22528
	ds_read_b128 v[244:247], v204 offset:23552
	global_load_lds_dwordx4 v130, s[36:37]
	s_add_i32 m0, s26, 0x2000
	s_add_u32 s26, s36, 0xb0000
	s_addc_u32 s27, s37, 0
	s_add_i32 s52, s46, s16
	global_load_lds_dwordx4 v134, s[36:37]
	s_mov_b32 m0, s52
	s_nop 0
	global_load_lds_dwordx4 v130, s[26:27]
	s_add_i32 m0, s52, 0x2000
	s_nop 0
	global_load_lds_dwordx4 v134, s[26:27]
	s_mov_b32 m0, s17
	s_nop 0
	global_load_lds_dwordx4 v128, s[38:39]
	s_mov_b32 m0, s28
	s_nop 0
	global_load_lds_dwordx4 v132, s[38:39]
	s_waitcnt vmcnt(8)
	s_waitcnt lgkmcnt(0)
	s_setprio 1
	s_barrier

; #define PG8_MMA(ai, bj, At, Bt) do { __builtin_amdgcn_s_setprio(1); _Pragma("unroll") for (int m = 0; m < 4; ++m) _Pragma("unroll") for (int n = 0; n < 2; ++n) _Pragma("unroll") for (int k = 0; k < 2; ++k) \
;         acc[ai][bj][m][n] = __builtin_amdgcn_mfma_f32_16x16x32_bf16(Bt[n][k], At[m][k], acc[ai][bj][m][n], 0, 0, 0); __builtin_amdgcn_s_setprio(0); } while (0)
; #define PG8_WAIT_V(n) asm volatile("s_waitcnt vmcnt(" #n ")" ::: "memory")
; #define PG8_WAIT_L(n) asm volatile("s_waitcnt lgkmcnt(" #n ")" ::: "memory")
; #define PG8_BAR __builtin_amdgcn_s_barrier()
; #define PG8_SCHED __builtin_amdgcn_sched_barrier(0)
; template <class Epi>
; __device__ __forceinline__ void gemm_phase(LAS unsigned char* lds, const Gemm g, const StaticOrder& S, const Epi& E) {
;     ...
;             PG8_WAIT_V(8); PG8_WAIT_L(0); PG8_BAR; PG8_MMA(1, 0, At, B0); PG8_MMA(1, 1, At, B1); PG8_BAR; PG8_SCHED;
	v_mfma_f32_16x16x32_bf16 v[60:63], v[144:147], v[216:219], v[60:63]
	v_mfma_f32_16x16x32_bf16 v[56:59], v[152:155], v[216:219], v[56:59]
	v_mfma_f32_16x16x32_bf16 v[44:47], v[144:147], v[224:227], v[44:47]
	v_mfma_f32_16x16x32_bf16 v[40:43], v[152:155], v[224:227], v[40:43]
	v_mfma_f32_16x16x32_bf16 v[28:31], v[144:147], v[232:235], v[28:31]
	v_mfma_f32_16x16x32_bf16 v[24:27], v[152:155], v[232:235], v[24:27]
	v_mfma_f32_16x16x32_bf16 v[12:15], v[144:147], v[240:243], v[12:15]
	v_mfma_f32_16x16x32_bf16 v[8:11], v[152:155], v[240:243], v[8:11]
	v_mfma_f32_16x16x32_bf16 v[60:63], v[148:151], v[220:223], v[60:63]
	v_mfma_f32_16x16x32_bf16 v[56:59], v[156:159], v[220:223], v[56:59]
	v_mfma_f32_16x16x32_bf16 v[44:47], v[148:151], v[228:231], v[44:47]
	v_mfma_f32_16x16x32_bf16 v[40:43], v[156:159], v[228:231], v[40:43]
	v_mfma_f32_16x16x32_bf16 v[28:31], v[148:151], v[236:239], v[28:31]
	v_mfma_f32_16x16x32_bf16 v[24:27], v[156:159], v[236:239], v[24:27]
	v_mfma_f32_16x16x32_bf16 v[12:15], v[148:151], v[244:247], v[12:15]
	v_mfma_f32_16x16x32_bf16 v[8:11], v[156:159], v[244:247], v[8:11]


; #define PG8_STAGE(bufoff, gbase, voff) do { _Pragma("unroll") for (int _i = 0; _i < 2; ++_i) \
;         __builtin_amdgcn_global_load_lds((const unsigned*)((const char*)(gbase) + (voff)[_i]), (LAS unsigned*)(lds + (bufoff) + ldsw + _i * 8192), 16, 0, 0); } while (0)
; #define PG8_LDA(dst, b, h) do { _Pragma("unroll") for (int m = 0; m < 4; ++m) _Pragma("unroll") for (int k = 0; k < 2; ++k) dst[m][k] = *(const LAS bf16x8*)(lds + PG8_SA(b, h) + aoff + m * 2048 + k * 1024); } while (0)
; #define PG8_LDB(dst, b, h) do { _Pragma("unroll") for (int n = 0; n < 2; ++n) _Pragma("unroll") for (int k = 0; k < 2; ++k) dst[n][k] = *(const LAS bf16x8*)(lds + PG8_SB(b, h) + boff + n * 2048 + k * 1024); } while (0)
; #define PG8_MMA(ai, bj, At, Bt) do { __builtin_amdgcn_s_setprio(1); _Pragma("unroll") for (int m = 0; m < 4; ++m) _Pragma("unroll") for (int n = 0; n < 2; ++n) _Pragma("unroll") for (int k = 0; k < 2; ++k) \
;         acc[ai][bj][m][n] = __builtin_amdgcn_mfma_f32_16x16x32_bf16(Bt[n][k], At[m][k], acc[ai][bj][m][n], 0, 0, 0); __builtin_amdgcn_s_setprio(0); } while (0)
; #define PG8_WAIT_V(n) asm volatile("s_waitcnt vmcnt(" #n ")" ::: "memory")
; #define PG8_WAIT_L(n) asm volatile("s_waitcnt lgkmcnt(" #n ")" ::: "memory")
; #define PG8_BAR __builtin_amdgcn_s_barrier()
; #define PG8_SCHED __builtin_amdgcn_sched_barrier(0)
; template <class Epi>
; __device__ __forceinline__ void gemm_phase(LAS unsigned char* lds, const Gemm g, const StaticOrder& S, const Epi& E) {
;     ...
;             PG8_WAIT_V(8); PG8_WAIT_L(0); PG8_BAR; PG8_MMA(1, 0, At, B0); PG8_MMA(1, 1, At, B1); PG8_BAR; PG8_SCHED;
;             PG8_LDB(B0, 1, 0); PG8_LDB(B1, 1, 1); PG8_SCHED; PG8_LDA(At, 1, 0); PG8_STAGE(PG8_SA(0, 1), a2 + hsA, voffA);
;             PG8_WAIT_V(8); PG8_WAIT_L(0); PG8_BAR; PG8_MMA(0, 0, At, B0); PG8_MMA(0, 1, At, B1); PG8_BAR; PG8_SCHED;
	v_mfma_f32_16x16x32_bf16 v[52:55], v[160:163], v[216:219], v[52:55]
	v_mfma_f32_16x16x32_bf16 v[48:51], v[168:171], v[216:219], v[48:51]
	v_mfma_f32_16x16x32_bf16 v[36:39], v[160:163], v[224:227], v[36:39]
	v_mfma_f32_16x16x32_bf16 v[32:35], v[168:171], v[224:227], v[32:35]
	v_mfma_f32_16x16x32_bf16 v[20:23], v[160:163], v[232:235], v[20:23]
	v_mfma_f32_16x16x32_bf16 v[16:19], v[168:171], v[232:235], v[16:19]
	v_mfma_f32_16x16x32_bf16 v[4:7], v[160:163], v[240:243], v[4:7]
	v_mfma_f32_16x16x32_bf16 v[0:3], v[168:171], v[240:243], v[0:3]
	v_mfma_f32_16x16x32_bf16 v[52:55], v[164:167], v[220:223], v[52:55]
	v_mfma_f32_16x16x32_bf16 v[48:51], v[172:175], v[220:223], v[48:51]
	v_mfma_f32_16x16x32_bf16 v[36:39], v[164:167], v[228:231], v[36:39]
	v_mfma_f32_16x16x32_bf16 v[32:35], v[172:175], v[228:231], v[32:35]
	v_mfma_f32_16x16x32_bf16 v[20:23], v[164:167], v[236:239], v[20:23]
	v_mfma_f32_16x16x32_bf16 v[16:19], v[172:175], v[236:239], v[16:19]
	v_mfma_f32_16x16x32_bf16 v[4:7], v[164:167], v[244:247], v[4:7]
	v_mfma_f32_16x16x32_bf16 v[0:3], v[172:175], v[244:247], v[0:3]
	s_setprio 0
	s_barrier
	s_add_i32 s52, 0, 0x18000
	s_add_i32 s53, 0, 0x1c000
	v_add_u32_e32 v156, s52, v184
	v_add_u32_e32 v172, s53, v184
	ds_read_b128 v[144:147], v156
	ds_read_b128 v[148:151], v156 offset:1024
	ds_read_b128 v[152:155], v156 offset:2048
	ds_read_b128 v[156:159], v156 offset:3072
	ds_read_b128 v[160:163], v172
	ds_read_b128 v[164:167], v172 offset:1024
	ds_read_b128 v[168:171], v172 offset:2048
	ds_read_b128 v[172:175], v172 offset:3072
	s_add_u32 s26, s38, 0xb0000
	s_addc_u32 s27, s39, 0
	s_mov_b32 m0, s29
	ds_read_b128 v[216:219], v204 offset:32768
	ds_read_b128 v[220:223], v204 offset:33792
	ds_read_b128 v[224:227], v204 offset:34816
	ds_read_b128 v[228:231], v204 offset:35840
	ds_read_b128 v[232:235], v204 offset:36864
	ds_read_b128 v[236:239], v204 offset:37888
	ds_read_b128 v[240:243], v204 offset:38912
	ds_read_b128 v[244:247], v204 offset:39936
	global_load_lds_dwordx4 v128, s[26:27]
	s_mov_b32 m0, s30
	s_nop 0
	global_load_lds_dwordx4 v132, s[26:27]
	s_waitcnt vmcnt(8)
	s_waitcnt lgkmcnt(0)
	s_setprio 1
	s_barrier

; #define PG8_MMA(ai, bj, At, Bt) do { __builtin_amdgcn_s_setprio(1); _Pragma("unroll") for (int m = 0; m < 4; ++m) _Pragma("unroll") for (int n = 0; n < 2; ++n) _Pragma("unroll") for (int k = 0; k < 2; ++k) \
;         acc[ai][bj][m][n] = __builtin_amdgcn_mfma_f32_16x16x32_bf16(Bt[n][k], At[m][k], acc[ai][bj][m][n], 0, 0, 0); __builtin_amdgcn_s_setprio(0); } while (0)
; #define PG8_WAIT_V(n) asm volatile("s_waitcnt vmcnt(" #n ")" ::: "memory")
; #define PG8_WAIT_L(n) asm volatile("s_waitcnt lgkmcnt(" #n ")" ::: "memory")
; #define PG8_BAR __builtin_amdgcn_s_barrier()
; #define PG8_SCHED __builtin_amdgcn_sched_barrier(0)
; template <class Epi>
; __device__ __forceinline__ void gemm_phase(LAS unsigned char* lds, const Gemm g, const StaticOrder& S, const Epi& E) {
;     ...
;             PG8_WAIT_V(8); PG8_WAIT_L(0); PG8_BAR; PG8_MMA(0, 0, At, B0); PG8_MMA(0, 1, At, B1); PG8_BAR; PG8_SCHED;
	v_mfma_f32_16x16x32_bf16 v[124:127], v[144:147], v[216:219], v[124:127]
	v_mfma_f32_16x16x32_bf16 v[120:123], v[152:155], v[216:219], v[120:123]
	v_mfma_f32_16x16x32_bf16 v[108:111], v[144:147], v[224:227], v[108:111]
	v_mfma_f32_16x16x32_bf16 v[104:107], v[152:155], v[224:227], v[104:107]
	v_mfma_f32_16x16x32_bf16 v[92:95], v[144:147], v[232:235], v[92:95]
	v_mfma_f32_16x16x32_bf16 v[88:91], v[152:155], v[232:235], v[88:91]
	v_mfma_f32_16x16x32_bf16 v[76:79], v[144:147], v[240:243], v[76:79]
	v_mfma_f32_16x16x32_bf16 v[72:75], v[152:155], v[240:243], v[72:75]
	v_mfma_f32_16x16x32_bf16 v[124:127], v[148:151], v[220:223], v[124:127]
	v_mfma_f32_16x16x32_bf16 v[120:123], v[156:159], v[220:223], v[120:123]
	v_mfma_f32_16x16x32_bf16 v[108:111], v[148:151], v[228:231], v[108:111]
	v_mfma_f32_16x16x32_bf16 v[104:107], v[156:159], v[228:231], v[104:107]
	v_mfma_f32_16x16x32_bf16 v[92:95], v[148:151], v[236:239], v[92:95]
	v_mfma_f32_16x16x32_bf16 v[88:91], v[156:159], v[236:239], v[88:91]
	v_mfma_f32_16x16x32_bf16 v[76:79], v[148:151], v[244:247], v[76:79]
	v_mfma_f32_16x16x32_bf16 v[72:75], v[156:159], v[244:247], v[72:75]


; #define PG8_STAGE(bufoff, gbase, voff) do { _Pragma("unroll") for (int _i = 0; _i < 2; ++_i) \
;         __builtin_amdgcn_global_load_lds((const unsigned*)((const char*)(gbase) + (voff)[_i]), (LAS unsigned*)(lds + (bufoff) + ldsw + _i * 8192), 16, 0, 0); } while (0)
; #define PG8_LDA(dst, b, h) do { _Pragma("unroll") for (int m = 0; m < 4; ++m) _Pragma("unroll") for (int k = 0; k < 2; ++k) dst[m][k] = *(const LAS bf16x8*)(lds + PG8_SA(b, h) + aoff + m * 2048 + k * 1024); } while (0)
; #define PG8_MMA(ai, bj, At, Bt) do { __builtin_amdgcn_s_setprio(1); _Pragma("unroll") for (int m = 0; m < 4; ++m) _Pragma("unroll") for (int n = 0; n < 2; ++n) _Pragma("unroll") for (int k = 0; k < 2; ++k) \
;         acc[ai][bj][m][n] = __builtin_amdgcn_mfma_f32_16x16x32_bf16(Bt[n][k], At[m][k], acc[ai][bj][m][n], 0, 0, 0); __builtin_amdgcn_s_setprio(0); } while (0)
; #define PG8_WAIT_V(n) asm volatile("s_waitcnt vmcnt(" #n ")" ::: "memory")
; #define PG8_WAIT_L(n) asm volatile("s_waitcnt lgkmcnt(" #n ")" ::: "memory")
; #define PG8_BAR __builtin_amdgcn_s_barrier()
; #define PG8_SCHED __builtin_amdgcn_sched_barrier(0)
; template <class Epi>
; __device__ __forceinline__ void gemm_phase(LAS unsigned char* lds, const Gemm g, const StaticOrder& S, const Epi& E) {
;     ...
;             PG8_WAIT_V(8); PG8_WAIT_L(0); PG8_BAR; PG8_MMA(0, 0, At, B0); PG8_MMA(0, 1, At, B1); PG8_BAR; PG8_SCHED;
;             PG8_LDA(At, 1, 1); PG8_STAGE(PG8_SB(1, 0), b3, voffB); PG8_STAGE(PG8_SB(1, 1), b3 + hsB, voffB); PG8_STAGE(PG8_SA(1, 0), a3, voffA);
;             PG8_WAIT_V(8); PG8_WAIT_L(0); PG8_BAR; PG8_MMA(1, 0, At, B0); PG8_MMA(1, 1, At, B1); PG8_BAR; PG8_SCHED;
	v_mfma_f32_16x16x32_bf16 v[116:119], v[160:163], v[216:219], v[116:119]
	v_mfma_f32_16x16x32_bf16 v[112:115], v[168:171], v[216:219], v[112:115]
	v_mfma_f32_16x16x32_bf16 v[100:103], v[160:163], v[224:227], v[100:103]
	v_mfma_f32_16x16x32_bf16 v[96:99], v[168:171], v[224:227], v[96:99]
	v_mfma_f32_16x16x32_bf16 v[84:87], v[160:163], v[232:235], v[84:87]
	v_mfma_f32_16x16x32_bf16 v[80:83], v[168:171], v[232:235], v[80:83]
	v_mfma_f32_16x16x32_bf16 v[68:71], v[160:163], v[240:243], v[68:71]
	v_mfma_f32_16x16x32_bf16 v[64:67], v[168:171], v[240:243], v[64:67]
	v_mfma_f32_16x16x32_bf16 v[116:119], v[164:167], v[220:223], v[116:119]
	v_mfma_f32_16x16x32_bf16 v[112:115], v[172:175], v[220:223], v[112:115]
	v_mfma_f32_16x16x32_bf16 v[100:103], v[164:167], v[228:231], v[100:103]
	v_mfma_f32_16x16x32_bf16 v[96:99], v[172:175], v[228:231], v[96:99]
	v_mfma_f32_16x16x32_bf16 v[84:87], v[164:167], v[236:239], v[84:87]
	v_mfma_f32_16x16x32_bf16 v[80:83], v[172:175], v[236:239], v[80:83]
	v_mfma_f32_16x16x32_bf16 v[68:71], v[164:167], v[244:247], v[68:71]
	v_mfma_f32_16x16x32_bf16 v[64:67], v[172:175], v[244:247], v[64:67]
	s_setprio 0
	s_barrier
	s_add_u32 s98, s36, 0x80
	s_addc_u32 s99, s37, 0
	s_add_u32 s100, s38, 0x80
	s_addc_u32 s101, s39, 0
	s_add_i32 s26, s52, s16
	s_mov_b32 m0, s26
	ds_read_b128 v[216:219], v204 offset:49152
	ds_read_b128 v[220:223], v204 offset:50176
	ds_read_b128 v[224:227], v204 offset:51200
	ds_read_b128 v[228:231], v204 offset:52224
	ds_read_b128 v[232:235], v204 offset:53248
	ds_read_b128 v[236:239], v204 offset:54272
	ds_read_b128 v[240:243], v204 offset:55296
	ds_read_b128 v[244:247], v204 offset:56320
	global_load_lds_dwordx4 v130, s[98:99]
	s_add_i32 m0, s26, 0x2000
	s_add_u32 s26, s36, 0xb0080
	s_addc_u32 s27, s37, 0
	s_add_i32 s36, s53, s16
	global_load_lds_dwordx4 v134, s[98:99]
	s_mov_b32 m0, s36
	s_nop 0
	global_load_lds_dwordx4 v130, s[26:27]
	s_add_i32 m0, s36, 0x2000
	s_nop 0
	global_load_lds_dwordx4 v134, s[26:27]
	s_mov_b32 m0, s41
	s_nop 0
	global_load_lds_dwordx4 v128, s[100:101]
	s_mov_b32 m0, s42
	s_nop 0
	global_load_lds_dwordx4 v132, s[100:101]
	s_waitcnt vmcnt(8)
	s_waitcnt lgkmcnt(0)
	s_setprio 1
	s_barrier

; #define PG8_MMA(ai, bj, At, Bt) do { __builtin_amdgcn_s_setprio(1); _Pragma("unroll") for (int m = 0; m < 4; ++m) _Pragma("unroll") for (int n = 0; n < 2; ++n) _Pragma("unroll") for (int k = 0; k < 2; ++k) \
;         acc[ai][bj][m][n] = __builtin_amdgcn_mfma_f32_16x16x32_bf16(Bt[n][k], At[m][k], acc[ai][bj][m][n], 0, 0, 0); __builtin_amdgcn_s_setprio(0); } while (0)
; #define PG8_WAIT_V(n) asm volatile("s_waitcnt vmcnt(" #n ")" ::: "memory")
; #define PG8_WAIT_L(n) asm volatile("s_waitcnt lgkmcnt(" #n ")" ::: "memory")
; #define PG8_BAR __builtin_amdgcn_s_barrier()
; #define PG8_SCHED __builtin_amdgcn_sched_barrier(0)
; template <class Epi>
; __device__ __forceinline__ void gemm_phase(LAS unsigned char* lds, const Gemm g, const StaticOrder& S, const Epi& E) {
;     ...
;             PG8_WAIT_V(8); PG8_WAIT_L(0); PG8_BAR; PG8_MMA(1, 0, At, B0); PG8_MMA(1, 1, At, B1); PG8_BAR; PG8_SCHED;
	v_mfma_f32_16x16x32_bf16 v[60:63], v[144:147], v[216:219], v[60:63]
	v_mfma_f32_16x16x32_bf16 v[56:59], v[152:155], v[216:219], v[56:59]
	v_mfma_f32_16x16x32_bf16 v[44:47], v[144:147], v[224:227], v[44:47]
	v_mfma_f32_16x16x32_bf16 v[40:43], v[152:155], v[224:227], v[40:43]
	v_mfma_f32_16x16x32_bf16 v[28:31], v[144:147], v[232:235], v[28:31]
	v_mfma_f32_16x16x32_bf16 v[24:27], v[152:155], v[232:235], v[24:27]
	v_mfma_f32_16x16x32_bf16 v[12:15], v[144:147], v[240:243], v[12:15]
	v_mfma_f32_16x16x32_bf16 v[8:11], v[152:155], v[240:243], v[8:11]
	v_mfma_f32_16x16x32_bf16 v[60:63], v[148:151], v[220:223], v[60:63]
	v_mfma_f32_16x16x32_bf16 v[56:59], v[156:159], v[220:223], v[56:59]
	v_mfma_f32_16x16x32_bf16 v[44:47], v[148:151], v[228:231], v[44:47]
	v_mfma_f32_16x16x32_bf16 v[40:43], v[156:159], v[228:231], v[40:43]
	v_mfma_f32_16x16x32_bf16 v[28:31], v[148:151], v[236:239], v[28:31]
	v_mfma_f32_16x16x32_bf16 v[24:27], v[156:159], v[236:239], v[24:27]
	v_mfma_f32_16x16x32_bf16 v[12:15], v[148:151], v[244:247], v[12:15]
	v_mfma_f32_16x16x32_bf16 v[8:11], v[156:159], v[244:247], v[8:11]


; #define PG8_MMA(ai, bj, At, Bt) do { __builtin_amdgcn_s_setprio(1); _Pragma("unroll") for (int m = 0; m < 4; ++m) _Pragma("unroll") for (int n = 0; n < 2; ++n) _Pragma("unroll") for (int k = 0; k < 2; ++k) \
;         acc[ai][bj][m][n] = __builtin_amdgcn_mfma_f32_16x16x32_bf16(Bt[n][k], At[m][k], acc[ai][bj][m][n], 0, 0, 0); __builtin_amdgcn_s_setprio(0); } while (0)
; #define PG8_WAIT_V(n) asm volatile("s_waitcnt vmcnt(" #n ")" ::: "memory")
; #define PG8_WAIT_L(n) asm volatile("s_waitcnt lgkmcnt(" #n ")" ::: "memory")
; #define PG8_BAR __builtin_amdgcn_s_barrier()
; #define PG8_SCHED __builtin_amdgcn_sched_barrier(0)
; template <class Epi>
; __device__ __forceinline__ void gemm_phase(LAS unsigned char* lds, const Gemm g, const StaticOrder& S, const Epi& E) {
;     ...
;             PG8_WAIT_V(8); PG8_WAIT_L(0); PG8_BAR; PG8_MMA(1, 0, At, B0); PG8_MMA(1, 1, At, B1); PG8_BAR; PG8_SCHED;
;         }
;         if (wr == 0) PG8_BAR;
	v_mfma_f32_16x16x32_bf16 v[52:55], v[160:163], v[216:219], v[52:55]
	v_mfma_f32_16x16x32_bf16 v[48:51], v[168:171], v[216:219], v[48:51]
	v_mfma_f32_16x16x32_bf16 v[36:39], v[160:163], v[224:227], v[36:39]
	v_mfma_f32_16x16x32_bf16 v[32:35], v[168:171], v[224:227], v[32:35]
	v_mfma_f32_16x16x32_bf16 v[20:23], v[160:163], v[232:235], v[20:23]
	v_mfma_f32_16x16x32_bf16 v[16:19], v[168:171], v[232:235], v[16:19]
	v_mfma_f32_16x16x32_bf16 v[4:7], v[160:163], v[240:243], v[4:7]
	v_mfma_f32_16x16x32_bf16 v[0:3], v[168:171], v[240:243], v[0:3]
	v_mfma_f32_16x16x32_bf16 v[52:55], v[164:167], v[220:223], v[52:55]
	v_mfma_f32_16x16x32_bf16 v[48:51], v[172:175], v[220:223], v[48:51]
	v_mfma_f32_16x16x32_bf16 v[36:39], v[164:167], v[228:231], v[36:39]
	v_mfma_f32_16x16x32_bf16 v[32:35], v[172:175], v[228:231], v[32:35]
	v_mfma_f32_16x16x32_bf16 v[20:23], v[164:167], v[236:239], v[20:23]
	v_mfma_f32_16x16x32_bf16 v[16:19], v[172:175], v[236:239], v[16:19]
	v_mfma_f32_16x16x32_bf16 v[4:7], v[164:167], v[244:247], v[4:7]
	v_mfma_f32_16x16x32_bf16 v[0:3], v[172:175], v[244:247], v[0:3]
	s_setprio 0
	s_barrier
	s_add_i32 s51, s51, 2
	s_add_u32 s25, s25, 0x100
	s_addc_u32 s50, s50, 0
	s_cmp_gt_u32 s51, 41
	s_mov_b64 s[26:27], s[34:35]
	s_cbranch_scc0 .LBB0_1433
	s_and_b64 vcc, exec, s[18:19]
	s_cbranch_vccz .LBB0_1436
	s_barrier
